# ssd3-plus-setprio-shift
# speedup vs baseline: 1.0368x; 1.0089x over previous
; #define PG8_STAGE(bufoff, gbase, voff) do { _Pragma("unroll") for (int _i = 0; _i < 2; ++_i) \
;         __builtin_amdgcn_global_load_lds((const unsigned*)((const char*)(gbase) + (voff)[_i]), (LAS unsigned*)(lds + (bufoff) + ldsw + _i * 8192), 16, 0, 0); } while (0)
; #define PG8_LDA(dst, b, h) do { _Pragma("unroll") for (int m = 0; m < 4; ++m) _Pragma("unroll") for (int k = 0; k < 2; ++k) dst[m][k] = *(const LAS bf16x8*)(lds + PG8_SA(b, h) + aoff + m * 2048 + k * 1024); } while (0)
; #define PG8_LDB(dst, b, h) do { _Pragma("unroll") for (int n = 0; n < 2; ++n) _Pragma("unroll") for (int k = 0; k < 2; ++k) dst[n][k] = *(const LAS bf16x8*)(lds + PG8_SB(b, h) + boff + n * 2048 + k * 1024); } while (0)
; #define PG8_MMA(ai, bj, At, Bt) do { __builtin_amdgcn_s_setprio(1); _Pragma("unroll") for (int m = 0; m < 4; ++m) _Pragma("unroll") for (int n = 0; n < 2; ++n) _Pragma("unroll") for (int k = 0; k < 2; ++k) \
;         acc[ai][bj][m][n] = __builtin_amdgcn_mfma_f32_16x16x32_bf16(Bt[n][k], At[m][k], acc[ai][bj][m][n], 0, 0, 0); __builtin_amdgcn_s_setprio(0); } while (0)
; #define PG8_WAIT_V(n) asm volatile("s_waitcnt vmcnt(" #n ")" ::: "memory")
; #define PG8_WAIT_L(n) asm volatile("s_waitcnt lgkmcnt(" #n ")" ::: "memory")
; template <class Epi, class Sched, bool ATILE = false>
; __device__ __forceinline__ void gemm_phase(LAS unsigned char* lds, const Gemm g, const Sched& S, const Epi& E) {
;     ...
;         for (int t = 0; t < nt; t += 2) {
;             const bool last = (t == nt - 2);
;             const char* a1 = cA + (size_t)(t + 1) * kstepA;
;             const char* a2 = last ? nA : cA + (size_t)(t + 2) * kstepA; const char* b2 = last ? nB : cB + (size_t)(t + 2) * kstep;
;             const char* a3 = a2 + kstepA; const char* b3 = b2 + kstep;
;             PG8_LDB(B0, 0, 0); PG8_SCHED; PG8_LDA(At, 0, 0); PG8_STAGE(PG8_SA(1, 1), a1 + hstepA, voffA);
;             PG8_WAIT_L(8); PG8_BAR; PG8_WAIT_L(0); PG8_MMA(0, 0, At, B0); PG8_BAR; PG8_SCHED;
;             PG8_LDB(B1, 0, 1); PG8_STAGE(PG8_SB(0, 0), b2, voffB);
;             PG8_BAR; PG8_WAIT_L(0); PG8_MMA(0, 1, At, B1); PG8_BAR;
;             PG8_LDA(At, 0, 1); PG8_STAGE(PG8_SA(0, 0), a2, voffA);
;             PG8_BAR; PG8_WAIT_L(0); PG8_MMA(1, 0, At, B0); PG8_BAR; PG8_SCHED;
;             PG8_STAGE(PG8_SB(0, 1), b2 + hstepB, voffB);
;             PG8_WAIT_V(6); PG8_BAR; PG8_MMA(1, 1, At, B1); PG8_BAR;
.LBB0_625:
	ds_read_b128 v[182:185], v139
	ds_read_b128 v[186:189], v139 offset:1024
	ds_read_b128 v[190:193], v139 offset:2048
	ds_read_b128 v[194:197], v139 offset:3072
	s_add_i32 s62, s28, 2
	s_add_u32 s29, s26, 0xfff80080
	s_addc_u32 s30, s27, -1
	s_cmp_eq_u32 s59, s28
	s_cselect_b32 s28, s58, s60
	s_cselect_b32 s31, s13, s30
	s_cselect_b32 s30, s56, s29
	s_cselect_b32 s29, s57, s61
	s_add_i32 m0, s35, 0xc000
	ds_read_b128 v[198:201], v163
	ds_read_b128 v[202:205], v163 offset:1024
	ds_read_b128 v[206:209], v163 offset:2048
	ds_read_b128 v[210:213], v163 offset:3072
	ds_read_b128 v[214:217], v163 offset:4096
	ds_read_b128 v[218:221], v163 offset:5120
	ds_read_b128 v[222:225], v163 offset:6144
	ds_read_b128 v[226:229], v163 offset:7168
	global_load_lds_dwordx4 v172, s[26:27]
	s_add_i32 m0, s35, 0xe000
	s_nop 0
	global_load_lds_dwordx4 v174, s[26:27]
	s_waitcnt lgkmcnt(8)
	s_setprio 1
	s_barrier
	s_waitcnt lgkmcnt(0)
	v_mfma_f32_16x16x32_bf16 v[120:123], v[182:185], v[198:201], v[120:123]
	v_mfma_f32_16x16x32_bf16 v[112:115], v[190:193], v[198:201], v[112:115]
	v_mfma_f32_16x16x32_bf16 v[104:107], v[182:185], v[206:209], v[104:107]
	v_mfma_f32_16x16x32_bf16 v[96:99], v[190:193], v[206:209], v[96:99]
	v_mfma_f32_16x16x32_bf16 v[88:91], v[182:185], v[214:217], v[88:91]
	v_mfma_f32_16x16x32_bf16 v[80:83], v[190:193], v[214:217], v[80:83]
	v_mfma_f32_16x16x32_bf16 v[72:75], v[182:185], v[222:225], v[72:75]
	v_mfma_f32_16x16x32_bf16 v[64:67], v[190:193], v[222:225], v[64:67]
	v_mfma_f32_16x16x32_bf16 v[120:123], v[186:189], v[202:205], v[120:123]
	v_mfma_f32_16x16x32_bf16 v[112:115], v[194:197], v[202:205], v[112:115]
	v_mfma_f32_16x16x32_bf16 v[104:107], v[186:189], v[210:213], v[104:107]
	v_mfma_f32_16x16x32_bf16 v[96:99], v[194:197], v[210:213], v[96:99]
	v_mfma_f32_16x16x32_bf16 v[88:91], v[186:189], v[218:221], v[88:91]
	v_mfma_f32_16x16x32_bf16 v[80:83], v[194:197], v[218:221], v[80:83]
	v_mfma_f32_16x16x32_bf16 v[72:75], v[186:189], v[226:229], v[72:75]
	v_mfma_f32_16x16x32_bf16 v[64:67], v[194:197], v[226:229], v[64:67]
	s_barrier
	s_setprio 0
	s_add_i32 s63, s53, s34
	s_add_u32 s98, s28, s0
	s_addc_u32 s99, s29, s1
	s_mov_b32 m0, s63
	ds_read_b128 v[230:233], v167
	ds_read_b128 v[234:237], v167 offset:1024
	ds_read_b128 v[238:241], v167 offset:2048
	ds_read_b128 v[242:245], v167 offset:3072
	global_load_lds_dwordx4 v130, s[28:29]
	s_add_i32 m0, s63, 0x2000
	s_nop 0
	global_load_lds_dwordx4 v134, s[28:29]
	s_setprio 1
	s_barrier
	s_waitcnt lgkmcnt(0)
	v_mfma_f32_16x16x32_bf16 v[124:127], v[230:233], v[198:201], v[124:127]
	v_mfma_f32_16x16x32_bf16 v[116:119], v[238:241], v[198:201], v[116:119]
	v_mfma_f32_16x16x32_bf16 v[108:111], v[230:233], v[206:209], v[108:111]
	v_mfma_f32_16x16x32_bf16 v[100:103], v[238:241], v[206:209], v[100:103]
	v_mfma_f32_16x16x32_bf16 v[92:95], v[230:233], v[214:217], v[92:95]
	v_mfma_f32_16x16x32_bf16 v[84:87], v[238:241], v[214:217], v[84:87]
	v_mfma_f32_16x16x32_bf16 v[76:79], v[230:233], v[222:225], v[76:79]
	v_mfma_f32_16x16x32_bf16 v[68:71], v[238:241], v[222:225], v[68:71]
	v_mfma_f32_16x16x32_bf16 v[124:127], v[234:237], v[202:205], v[124:127]
	v_mfma_f32_16x16x32_bf16 v[116:119], v[242:245], v[202:205], v[116:119]
	v_mfma_f32_16x16x32_bf16 v[108:111], v[234:237], v[210:213], v[108:111]
	v_mfma_f32_16x16x32_bf16 v[100:103], v[242:245], v[210:213], v[100:103]
	v_mfma_f32_16x16x32_bf16 v[92:95], v[234:237], v[218:221], v[92:95]
	v_mfma_f32_16x16x32_bf16 v[84:87], v[242:245], v[218:221], v[84:87]
	v_mfma_f32_16x16x32_bf16 v[76:79], v[234:237], v[226:229], v[76:79]
	v_mfma_f32_16x16x32_bf16 v[68:71], v[242:245], v[226:229], v[68:71]
	s_barrier
	s_setprio 0
	s_mov_b32 m0, s35
	s_add_u32 s100, s30, s0
	s_addc_u32 s101, s31, s1
	ds_read_b128 v[198:201], v163 offset:16384
	ds_read_b128 v[202:205], v163 offset:17408
	ds_read_b128 v[206:209], v163 offset:18432
	ds_read_b128 v[210:213], v163 offset:19456
	ds_read_b128 v[214:217], v163 offset:20480
	ds_read_b128 v[218:221], v163 offset:21504
	ds_read_b128 v[222:225], v163 offset:22528
	ds_read_b128 v[226:229], v163 offset:23552
	global_load_lds_dwordx4 v128, s[30:31]
	s_mov_b32 m0, s36
	s_nop 0
	global_load_lds_dwordx4 v132, s[30:31]
	s_setprio 1
	s_barrier
	s_waitcnt lgkmcnt(0)
	v_mfma_f32_16x16x32_bf16 v[56:59], v[182:185], v[198:201], v[56:59]
	v_mfma_f32_16x16x32_bf16 v[48:51], v[190:193], v[198:201], v[48:51]
	v_mfma_f32_16x16x32_bf16 v[40:43], v[182:185], v[206:209], v[40:43]
	v_mfma_f32_16x16x32_bf16 v[32:35], v[190:193], v[206:209], v[32:35]
	v_mfma_f32_16x16x32_bf16 v[24:27], v[182:185], v[214:217], v[24:27]
	v_mfma_f32_16x16x32_bf16 v[16:19], v[190:193], v[214:217], v[16:19]
	v_mfma_f32_16x16x32_bf16 v[8:11], v[182:185], v[222:225], v[8:11]
	v_mfma_f32_16x16x32_bf16 v[4:7], v[190:193], v[222:225], v[4:7]
	v_mfma_f32_16x16x32_bf16 v[56:59], v[186:189], v[202:205], v[56:59]
	v_mfma_f32_16x16x32_bf16 v[48:51], v[194:197], v[202:205], v[48:51]
	v_mfma_f32_16x16x32_bf16 v[40:43], v[186:189], v[210:213], v[40:43]
	v_mfma_f32_16x16x32_bf16 v[32:35], v[194:197], v[210:213], v[32:35]
	v_mfma_f32_16x16x32_bf16 v[24:27], v[186:189], v[218:221], v[24:27]
	v_mfma_f32_16x16x32_bf16 v[16:19], v[194:197], v[218:221], v[16:19]
	v_mfma_f32_16x16x32_bf16 v[8:11], v[186:189], v[226:229], v[8:11]
	v_mfma_f32_16x16x32_bf16 v[4:7], v[194:197], v[226:229], v[4:7]
	s_barrier
	s_setprio 0
	s_add_u32 s64, s28, 0x80000
	s_addc_u32 s65, s29, 0
	s_add_i32 s63, s54, s34
	s_mov_b32 m0, s63
	s_nop 0
	global_load_lds_dwordx4 v130, s[64:65]
	s_add_i32 m0, s63, 0x2000
	s_nop 0
	global_load_lds_dwordx4 v134, s[64:65]
	s_waitcnt vmcnt(6)
	s_setprio 1
	s_barrier
; #define PG8_STAGE(bufoff, gbase, voff) do { _Pragma("unroll") for (int _i = 0; _i < 2; ++_i) \
;         __builtin_amdgcn_global_load_lds((const unsigned*)((const char*)(gbase) + (voff)[_i]), (LAS unsigned*)(lds + (bufoff) + ldsw + _i * 8192), 16, 0, 0); } while (0)
; #define PG8_LDA(dst, b, h) do { _Pragma("unroll") for (int m = 0; m < 4; ++m) _Pragma("unroll") for (int k = 0; k < 2; ++k) dst[m][k] = *(const LAS bf16x8*)(lds + PG8_SA(b, h) + aoff + m * 2048 + k * 1024); } while (0)
; #define PG8_LDB(dst, b, h) do { _Pragma("unroll") for (int n = 0; n < 2; ++n) _Pragma("unroll") for (int k = 0; k < 2; ++k) dst[n][k] = *(const LAS bf16x8*)(lds + PG8_SB(b, h) + boff + n * 2048 + k * 1024); } while (0)
; #define PG8_MMA(ai, bj, At, Bt) do { __builtin_amdgcn_s_setprio(1); _Pragma("unroll") for (int m = 0; m < 4; ++m) _Pragma("unroll") for (int n = 0; n < 2; ++n) _Pragma("unroll") for (int k = 0; k < 2; ++k) \
;         acc[ai][bj][m][n] = __builtin_amdgcn_mfma_f32_16x16x32_bf16(Bt[n][k], At[m][k], acc[ai][bj][m][n], 0, 0, 0); __builtin_amdgcn_s_setprio(0); } while (0)
; #define PG8_WAIT_V(n) asm volatile("s_waitcnt vmcnt(" #n ")" ::: "memory")
; #define PG8_WAIT_L(n) asm volatile("s_waitcnt lgkmcnt(" #n ")" ::: "memory")
; #define PG8_BAR __builtin_amdgcn_s_barrier()
; #define PG8_SCHED __builtin_amdgcn_sched_barrier(0)
; template <class Epi, class Sched, bool ATILE = false>
; __device__ __forceinline__ void gemm_phase(LAS unsigned char* lds, const Gemm g, const Sched& S, const Epi& E) {
;     ...
;             PG8_WAIT_V(6); PG8_BAR; PG8_MMA(1, 1, At, B1); PG8_BAR;
;             PG8_LDB(B0, 1, 0); PG8_SCHED; PG8_LDA(At, 1, 0); PG8_STAGE(PG8_SA(0, 1), a2 + hstepA, voffA);
;             PG8_WAIT_L(8); PG8_BAR; PG8_WAIT_L(0); PG8_MMA(0, 0, At, B0); PG8_BAR; PG8_SCHED;
;             PG8_LDB(B1, 1, 1); PG8_STAGE(PG8_SB(1, 0), b3, voffB);
;             PG8_BAR; PG8_WAIT_L(0); PG8_MMA(0, 1, At, B1); PG8_BAR;
	v_mfma_f32_16x16x32_bf16 v[60:63], v[230:233], v[198:201], v[60:63]
	v_mfma_f32_16x16x32_bf16 v[52:55], v[238:241], v[198:201], v[52:55]
	v_mfma_f32_16x16x32_bf16 v[44:47], v[230:233], v[206:209], v[44:47]
	v_mfma_f32_16x16x32_bf16 v[36:39], v[238:241], v[206:209], v[36:39]
	v_mfma_f32_16x16x32_bf16 v[28:31], v[230:233], v[214:217], v[28:31]
	v_mfma_f32_16x16x32_bf16 v[20:23], v[238:241], v[214:217], v[20:23]
	v_mfma_f32_16x16x32_bf16 v[12:15], v[230:233], v[222:225], v[12:15]
	v_mfma_f32_16x16x32_bf16 v[0:3], v[238:241], v[222:225], v[0:3]
	v_mfma_f32_16x16x32_bf16 v[60:63], v[234:237], v[202:205], v[60:63]
	v_mfma_f32_16x16x32_bf16 v[52:55], v[242:245], v[202:205], v[52:55]
	v_mfma_f32_16x16x32_bf16 v[44:47], v[234:237], v[210:213], v[44:47]
	v_mfma_f32_16x16x32_bf16 v[36:39], v[242:245], v[210:213], v[36:39]
	v_mfma_f32_16x16x32_bf16 v[28:31], v[234:237], v[218:221], v[28:31]
	v_mfma_f32_16x16x32_bf16 v[20:23], v[242:245], v[218:221], v[20:23]
	v_mfma_f32_16x16x32_bf16 v[12:15], v[234:237], v[226:229], v[12:15]
	v_mfma_f32_16x16x32_bf16 v[0:3], v[242:245], v[226:229], v[0:3]
	s_barrier
	s_setprio 0
	s_add_i32 s63, 0, 0x18000
	v_add_u32_e32 v176, s63, v161
	ds_read_b128 v[182:185], v176
	ds_read_b128 v[186:189], v176 offset:1024
	ds_read_b128 v[190:193], v176 offset:2048
	ds_read_b128 v[194:197], v176 offset:3072
	s_add_u32 s30, s30, 0x80000
	s_addc_u32 s31, s31, 0
	s_mov_b32 m0, s37
	ds_read_b128 v[198:201], v163 offset:32768
	ds_read_b128 v[202:205], v163 offset:33792
	ds_read_b128 v[206:209], v163 offset:34816
	ds_read_b128 v[210:213], v163 offset:35840
	ds_read_b128 v[214:217], v163 offset:36864
	ds_read_b128 v[218:221], v163 offset:37888
	ds_read_b128 v[222:225], v163 offset:38912
	ds_read_b128 v[226:229], v163 offset:39936
	global_load_lds_dwordx4 v128, s[30:31]
	s_mov_b32 m0, s38
	s_nop 0
	global_load_lds_dwordx4 v132, s[30:31]
	s_waitcnt lgkmcnt(8)
	s_setprio 1
	s_barrier
	s_waitcnt lgkmcnt(0)
	v_mfma_f32_16x16x32_bf16 v[120:123], v[182:185], v[198:201], v[120:123]
	v_mfma_f32_16x16x32_bf16 v[112:115], v[190:193], v[198:201], v[112:115]
	v_mfma_f32_16x16x32_bf16 v[104:107], v[182:185], v[206:209], v[104:107]
	v_mfma_f32_16x16x32_bf16 v[96:99], v[190:193], v[206:209], v[96:99]
	v_mfma_f32_16x16x32_bf16 v[88:91], v[182:185], v[214:217], v[88:91]
	v_mfma_f32_16x16x32_bf16 v[80:83], v[190:193], v[214:217], v[80:83]
	v_mfma_f32_16x16x32_bf16 v[72:75], v[182:185], v[222:225], v[72:75]
	v_mfma_f32_16x16x32_bf16 v[64:67], v[190:193], v[222:225], v[64:67]
	v_mfma_f32_16x16x32_bf16 v[120:123], v[186:189], v[202:205], v[120:123]
	v_mfma_f32_16x16x32_bf16 v[112:115], v[194:197], v[202:205], v[112:115]
	v_mfma_f32_16x16x32_bf16 v[104:107], v[186:189], v[210:213], v[104:107]
	v_mfma_f32_16x16x32_bf16 v[96:99], v[194:197], v[210:213], v[96:99]
	v_mfma_f32_16x16x32_bf16 v[88:91], v[186:189], v[218:221], v[88:91]
	v_mfma_f32_16x16x32_bf16 v[80:83], v[194:197], v[218:221], v[80:83]
	v_mfma_f32_16x16x32_bf16 v[72:75], v[186:189], v[226:229], v[72:75]
	v_mfma_f32_16x16x32_bf16 v[64:67], v[194:197], v[226:229], v[64:67]
	s_barrier
	s_setprio 0
	s_add_i32 s30, 0, 0x1c000
	s_add_i32 s31, s63, s34
	v_add_u32_e32 v176, s30, v161
	s_mov_b32 m0, s31
	ds_read_b128 v[230:233], v176
	ds_read_b128 v[234:237], v176 offset:1024
	ds_read_b128 v[238:241], v176 offset:2048
	ds_read_b128 v[242:245], v176 offset:3072
	global_load_lds_dwordx4 v130, s[98:99]
	s_add_i32 m0, s31, 0x2000
	s_nop 0
	global_load_lds_dwordx4 v134, s[98:99]
	s_setprio 1
	s_barrier
; #define PG8_STAGE(bufoff, gbase, voff) do { _Pragma("unroll") for (int _i = 0; _i < 2; ++_i) \
;         __builtin_amdgcn_global_load_lds((const unsigned*)((const char*)(gbase) + (voff)[_i]), (LAS unsigned*)(lds + (bufoff) + ldsw + _i * 8192), 16, 0, 0); } while (0)
; #define PG8_LDA(dst, b, h) do { _Pragma("unroll") for (int m = 0; m < 4; ++m) _Pragma("unroll") for (int k = 0; k < 2; ++k) dst[m][k] = *(const LAS bf16x8*)(lds + PG8_SA(b, h) + aoff + m * 2048 + k * 1024); } while (0)
; #define PG8_MMA(ai, bj, At, Bt) do { __builtin_amdgcn_s_setprio(1); _Pragma("unroll") for (int m = 0; m < 4; ++m) _Pragma("unroll") for (int n = 0; n < 2; ++n) _Pragma("unroll") for (int k = 0; k < 2; ++k) \
;         acc[ai][bj][m][n] = __builtin_amdgcn_mfma_f32_16x16x32_bf16(Bt[n][k], At[m][k], acc[ai][bj][m][n], 0, 0, 0); __builtin_amdgcn_s_setprio(0); } while (0)
; #define PG8_WAIT_V(n) asm volatile("s_waitcnt vmcnt(" #n ")" ::: "memory")
; #define PG8_WAIT_L(n) asm volatile("s_waitcnt lgkmcnt(" #n ")" ::: "memory")
; #define PG8_BAR __builtin_amdgcn_s_barrier()
; #define PG8_SCHED __builtin_amdgcn_sched_barrier(0)
; template <class Epi, class Sched, bool ATILE = false>
; __device__ __forceinline__ void gemm_phase(LAS unsigned char* lds, const Gemm g, const Sched& S, const Epi& E) {
;     ...
;             PG8_BAR; PG8_WAIT_L(0); PG8_MMA(0, 1, At, B1); PG8_BAR;
;             PG8_LDA(At, 1, 1); PG8_STAGE(PG8_SA(1, 0), a3, voffA);
;             PG8_BAR; PG8_WAIT_L(0); PG8_MMA(1, 0, At, B0); PG8_BAR; PG8_SCHED;
;             PG8_STAGE(PG8_SB(1, 1), b3 + hstepB, voffB);
;             PG8_WAIT_V(6); PG8_BAR; PG8_MMA(1, 1, At, B1); PG8_BAR;
;         }
	s_waitcnt lgkmcnt(0)
	v_mfma_f32_16x16x32_bf16 v[124:127], v[230:233], v[198:201], v[124:127]
	v_mfma_f32_16x16x32_bf16 v[116:119], v[238:241], v[198:201], v[116:119]
	v_mfma_f32_16x16x32_bf16 v[108:111], v[230:233], v[206:209], v[108:111]
	v_mfma_f32_16x16x32_bf16 v[100:103], v[238:241], v[206:209], v[100:103]
	v_mfma_f32_16x16x32_bf16 v[92:95], v[230:233], v[214:217], v[92:95]
	v_mfma_f32_16x16x32_bf16 v[84:87], v[238:241], v[214:217], v[84:87]
	v_mfma_f32_16x16x32_bf16 v[76:79], v[230:233], v[222:225], v[76:79]
	v_mfma_f32_16x16x32_bf16 v[68:71], v[238:241], v[222:225], v[68:71]
	v_mfma_f32_16x16x32_bf16 v[124:127], v[234:237], v[202:205], v[124:127]
	v_mfma_f32_16x16x32_bf16 v[116:119], v[242:245], v[202:205], v[116:119]
	v_mfma_f32_16x16x32_bf16 v[108:111], v[234:237], v[210:213], v[108:111]
	v_mfma_f32_16x16x32_bf16 v[100:103], v[242:245], v[210:213], v[100:103]
	v_mfma_f32_16x16x32_bf16 v[92:95], v[234:237], v[218:221], v[92:95]
	v_mfma_f32_16x16x32_bf16 v[84:87], v[242:245], v[218:221], v[84:87]
	v_mfma_f32_16x16x32_bf16 v[76:79], v[234:237], v[226:229], v[76:79]
	v_mfma_f32_16x16x32_bf16 v[68:71], v[242:245], v[226:229], v[68:71]
	s_barrier
	s_setprio 0
	s_mov_b32 m0, s41
	ds_read_b128 v[198:201], v163 offset:49152
	ds_read_b128 v[202:205], v163 offset:50176
	ds_read_b128 v[206:209], v163 offset:51200
	ds_read_b128 v[210:213], v163 offset:52224
	ds_read_b128 v[214:217], v163 offset:53248
	ds_read_b128 v[218:221], v163 offset:54272
	ds_read_b128 v[222:225], v163 offset:55296
	ds_read_b128 v[226:229], v163 offset:56320
	global_load_lds_dwordx4 v128, s[100:101]
	s_mov_b32 m0, s42
	s_nop 0
	global_load_lds_dwordx4 v132, s[100:101]
	s_setprio 1
	s_barrier
	s_waitcnt lgkmcnt(0)
	v_mfma_f32_16x16x32_bf16 v[56:59], v[182:185], v[198:201], v[56:59]
	v_mfma_f32_16x16x32_bf16 v[48:51], v[190:193], v[198:201], v[48:51]
	v_mfma_f32_16x16x32_bf16 v[40:43], v[182:185], v[206:209], v[40:43]
	v_mfma_f32_16x16x32_bf16 v[32:35], v[190:193], v[206:209], v[32:35]
	v_mfma_f32_16x16x32_bf16 v[24:27], v[182:185], v[214:217], v[24:27]
	v_mfma_f32_16x16x32_bf16 v[16:19], v[190:193], v[214:217], v[16:19]
	v_mfma_f32_16x16x32_bf16 v[8:11], v[182:185], v[222:225], v[8:11]
	v_mfma_f32_16x16x32_bf16 v[4:7], v[190:193], v[222:225], v[4:7]
	v_mfma_f32_16x16x32_bf16 v[56:59], v[186:189], v[202:205], v[56:59]
	v_mfma_f32_16x16x32_bf16 v[48:51], v[194:197], v[202:205], v[48:51]
	v_mfma_f32_16x16x32_bf16 v[40:43], v[186:189], v[210:213], v[40:43]
	v_mfma_f32_16x16x32_bf16 v[32:35], v[194:197], v[210:213], v[32:35]
	v_mfma_f32_16x16x32_bf16 v[24:27], v[186:189], v[218:221], v[24:27]
	v_mfma_f32_16x16x32_bf16 v[16:19], v[194:197], v[218:221], v[16:19]
	v_mfma_f32_16x16x32_bf16 v[8:11], v[186:189], v[226:229], v[8:11]
	v_mfma_f32_16x16x32_bf16 v[4:7], v[194:197], v[226:229], v[4:7]
	s_barrier
	s_setprio 0
	s_add_u32 s28, s28, 0x80080
	s_addc_u32 s29, s29, 0
	s_add_i32 s30, s30, s34
	s_mov_b32 m0, s30
	s_nop 0
	global_load_lds_dwordx4 v130, s[28:29]
	s_add_i32 m0, s30, 0x2000
	s_nop 0
	global_load_lds_dwordx4 v134, s[28:29]
	s_waitcnt vmcnt(6)
	s_setprio 1
	s_barrier
	v_mfma_f32_16x16x32_bf16 v[60:63], v[230:233], v[198:201], v[60:63]
	v_mfma_f32_16x16x32_bf16 v[52:55], v[238:241], v[198:201], v[52:55]
	v_mfma_f32_16x16x32_bf16 v[44:47], v[230:233], v[206:209], v[44:47]
	v_mfma_f32_16x16x32_bf16 v[36:39], v[238:241], v[206:209], v[36:39]
	v_mfma_f32_16x16x32_bf16 v[28:31], v[230:233], v[214:217], v[28:31]
	v_mfma_f32_16x16x32_bf16 v[20:23], v[238:241], v[214:217], v[20:23]
	v_mfma_f32_16x16x32_bf16 v[12:15], v[230:233], v[222:225], v[12:15]
	v_mfma_f32_16x16x32_bf16 v[0:3], v[238:241], v[222:225], v[0:3]
	v_mfma_f32_16x16x32_bf16 v[60:63], v[234:237], v[202:205], v[60:63]
	v_mfma_f32_16x16x32_bf16 v[52:55], v[242:245], v[202:205], v[52:55]
	v_mfma_f32_16x16x32_bf16 v[44:47], v[234:237], v[210:213], v[44:47]
	v_mfma_f32_16x16x32_bf16 v[36:39], v[242:245], v[210:213], v[36:39]
	v_mfma_f32_16x16x32_bf16 v[28:31], v[234:237], v[218:221], v[28:31]
	v_mfma_f32_16x16x32_bf16 v[20:23], v[242:245], v[218:221], v[20:23]
	v_mfma_f32_16x16x32_bf16 v[12:15], v[234:237], v[226:229], v[12:15]
	v_mfma_f32_16x16x32_bf16 v[0:3], v[242:245], v[226:229], v[0:3]
	s_barrier
	s_setprio 0
	s_add_u32 s26, s26, 0x100
	s_addc_u32 s27, s27, 0
	s_add_u32 s60, s60, 0x100
	s_addc_u32 s61, s61, 0
	s_cmp_ge_i32 s62, s11
	s_mov_b32 s28, s62
	s_cbranch_scc0 .LBB0_625
	s_branch .LBB0_616

; #define PG8_STAGE(bufoff, gbase, voff) do { _Pragma("unroll") for (int _i = 0; _i < 2; ++_i) \
;         __builtin_amdgcn_global_load_lds((const unsigned*)((const char*)(gbase) + (voff)[_i]), (LAS unsigned*)(lds + (bufoff) + ldsw + _i * 8192), 16, 0, 0); } while (0)
; #define PG8_LDA(dst, b, h) do { _Pragma("unroll") for (int m = 0; m < 4; ++m) _Pragma("unroll") for (int k = 0; k < 2; ++k) dst[m][k] = *(const LAS bf16x8*)(lds + PG8_SA(b, h) + aoff + m * 2048 + k * 1024); } while (0)
; #define PG8_LDB(dst, b, h) do { _Pragma("unroll") for (int n = 0; n < 2; ++n) _Pragma("unroll") for (int k = 0; k < 2; ++k) dst[n][k] = *(const LAS bf16x8*)(lds + PG8_SB(b, h) + boff + n * 2048 + k * 1024); } while (0)
; #define PG8_MMA(ai, bj, At, Bt) do { __builtin_amdgcn_s_setprio(1); _Pragma("unroll") for (int m = 0; m < 4; ++m) _Pragma("unroll") for (int n = 0; n < 2; ++n) _Pragma("unroll") for (int k = 0; k < 2; ++k) \
;         acc[ai][bj][m][n] = __builtin_amdgcn_mfma_f32_16x16x32_bf16(Bt[n][k], At[m][k], acc[ai][bj][m][n], 0, 0, 0); __builtin_amdgcn_s_setprio(0); } while (0)
; #define PG8_WAIT_V(n) asm volatile("s_waitcnt vmcnt(" #n ")" ::: "memory")
; #define PG8_WAIT_L(n) asm volatile("s_waitcnt lgkmcnt(" #n ")" ::: "memory")
; template <class Epi, class Sched, bool ATILE = false>
; __device__ __forceinline__ void gemm_phase(LAS unsigned char* lds, const Gemm g, const Sched& S, const Epi& E) {
;     ...
;         for (int t = 0; t < nt; t += 2) {
;             const bool last = (t == nt - 2);
;             const char* a1 = cA + (size_t)(t + 1) * kstepA;
;             const char* a2 = last ? nA : cA + (size_t)(t + 2) * kstepA; const char* b2 = last ? nB : cB + (size_t)(t + 2) * kstep;
;             const char* a3 = a2 + kstepA; const char* b3 = b2 + kstep;
;             PG8_LDB(B0, 0, 0); PG8_SCHED; PG8_LDA(At, 0, 0); PG8_STAGE(PG8_SA(1, 1), a1 + hstepA, voffA);
;             PG8_WAIT_L(8); PG8_BAR; PG8_WAIT_L(0); PG8_MMA(0, 0, At, B0); PG8_BAR; PG8_SCHED;
;             PG8_LDB(B1, 0, 1); PG8_STAGE(PG8_SB(0, 0), b2, voffB);
;             PG8_BAR; PG8_WAIT_L(0); PG8_MMA(0, 1, At, B1); PG8_BAR;
;             PG8_LDA(At, 0, 1); PG8_STAGE(PG8_SA(0, 0), a2, voffA);
;             PG8_BAR; PG8_WAIT_L(0); PG8_MMA(1, 0, At, B0); PG8_BAR; PG8_SCHED;
;             PG8_STAGE(PG8_SB(0, 1), b2 + hstepB, voffB);
;             PG8_WAIT_V(6); PG8_BAR; PG8_MMA(1, 1, At, B1); PG8_BAR;
.LBB0_739:
	ds_read_b128 v[20:23], v165
	ds_read_b128 v[28:31], v165 offset:1024
	ds_read_b128 v[136:139], v165 offset:2048
	ds_read_b128 v[140:143], v165 offset:3072
	s_add_i32 s62, s26, 2
	s_add_u32 s27, s24, 0x4000
	s_addc_u32 s28, s25, 0
	s_cmp_eq_u32 s11, s26
	s_cselect_b32 s30, s20, s27
	s_cselect_b32 s31, s21, s28
	s_cselect_b32 s26, s22, s60
	s_cselect_b32 s27, s23, s61
	s_add_u32 s28, s30, 0x8000
	s_addc_u32 s29, s31, 0
	s_add_i32 m0, s34, 0xc000
	ds_read_b128 v[144:147], v167
	ds_read_b128 v[148:151], v167 offset:1024
	ds_read_b128 v[200:203], v167 offset:2048
	ds_read_b128 v[204:207], v167 offset:3072
	ds_read_b128 v[208:211], v167 offset:4096
	ds_read_b128 v[212:215], v167 offset:5120
	ds_read_b128 v[220:223], v167 offset:6144
	ds_read_b128 v[224:227], v167 offset:7168
	global_load_lds_dwordx4 v194, s[24:25]
	s_add_i32 m0, s34, 0xe000
	s_nop 0
	global_load_lds_dwordx4 v196, s[24:25]
	s_waitcnt lgkmcnt(8)
	s_setprio 1
	s_barrier
	s_waitcnt lgkmcnt(0)
	v_mfma_f32_16x16x32_bf16 v[0:3], v[20:23], v[144:147], v[0:3]
	v_mfma_f32_16x16x32_bf16 v[4:7], v[136:139], v[144:147], v[4:7]
	v_mfma_f32_16x16x32_bf16 v[44:47], v[20:23], v[200:203], v[44:47]
	v_mfma_f32_16x16x32_bf16 v[36:39], v[136:139], v[200:203], v[36:39]
	v_mfma_f32_16x16x32_bf16 v[52:55], v[20:23], v[208:211], v[52:55]
	v_mfma_f32_16x16x32_bf16 v[48:51], v[136:139], v[208:211], v[48:51]
	v_mfma_f32_16x16x32_bf16 v[92:95], v[20:23], v[220:223], v[92:95]
	v_mfma_f32_16x16x32_bf16 v[84:87], v[136:139], v[220:223], v[84:87]
	v_mfma_f32_16x16x32_bf16 v[0:3], v[28:31], v[148:151], v[0:3]
	v_mfma_f32_16x16x32_bf16 v[4:7], v[140:143], v[148:151], v[4:7]
	v_mfma_f32_16x16x32_bf16 v[44:47], v[28:31], v[204:207], v[44:47]
	v_mfma_f32_16x16x32_bf16 v[36:39], v[140:143], v[204:207], v[36:39]
	v_mfma_f32_16x16x32_bf16 v[52:55], v[28:31], v[212:215], v[52:55]
	v_mfma_f32_16x16x32_bf16 v[48:51], v[140:143], v[212:215], v[48:51]
	v_mfma_f32_16x16x32_bf16 v[92:95], v[28:31], v[224:227], v[92:95]
	v_mfma_f32_16x16x32_bf16 v[84:87], v[140:143], v[224:227], v[84:87]
	s_barrier
	s_setprio 0
	s_add_i32 s63, s52, s33
	s_add_u32 s98, s26, s6
	s_addc_u32 s99, s27, s7
	s_mov_b32 m0, s63
	ds_read_b128 v[228:231], v177
	ds_read_b128 v[232:235], v177 offset:1024
	ds_read_b128 v[236:239], v177 offset:2048
	ds_read_b128 v[240:243], v177 offset:3072
	global_load_lds_dwordx4 v170, s[26:27]
	s_add_i32 m0, s63, 0x2000
	s_nop 0
	global_load_lds_dwordx4 v174, s[26:27]
	s_setprio 1
	s_barrier
	s_waitcnt lgkmcnt(0)
	v_mfma_f32_16x16x32_bf16 v[12:15], v[228:231], v[144:147], v[12:15]
	v_mfma_f32_16x16x32_bf16 v[8:11], v[236:239], v[144:147], v[8:11]
	v_mfma_f32_16x16x32_bf16 v[24:27], v[228:231], v[200:203], v[24:27]
	v_mfma_f32_16x16x32_bf16 v[16:19], v[236:239], v[200:203], v[16:19]
	v_mfma_f32_16x16x32_bf16 v[40:43], v[228:231], v[208:211], v[40:43]
	v_mfma_f32_16x16x32_bf16 v[32:35], v[236:239], v[208:211], v[32:35]
	v_mfma_f32_16x16x32_bf16 v[56:59], v[228:231], v[220:223], v[56:59]
	v_mfma_f32_16x16x32_bf16 v[60:63], v[236:239], v[220:223], v[60:63]
	v_mfma_f32_16x16x32_bf16 v[12:15], v[232:235], v[148:151], v[12:15]
	v_mfma_f32_16x16x32_bf16 v[8:11], v[240:243], v[148:151], v[8:11]
	v_mfma_f32_16x16x32_bf16 v[24:27], v[232:235], v[204:207], v[24:27]
	v_mfma_f32_16x16x32_bf16 v[16:19], v[240:243], v[204:207], v[16:19]
	v_mfma_f32_16x16x32_bf16 v[40:43], v[232:235], v[212:215], v[40:43]
	v_mfma_f32_16x16x32_bf16 v[32:35], v[240:243], v[212:215], v[32:35]
	v_mfma_f32_16x16x32_bf16 v[56:59], v[232:235], v[224:227], v[56:59]
	v_mfma_f32_16x16x32_bf16 v[60:63], v[240:243], v[224:227], v[60:63]
	s_barrier
	s_setprio 0
	s_mov_b32 m0, s34
	ds_read_b128 v[144:147], v167 offset:16384
	ds_read_b128 v[148:151], v167 offset:17408
	ds_read_b128 v[200:203], v167 offset:18432
	ds_read_b128 v[204:207], v167 offset:19456
	ds_read_b128 v[208:211], v167 offset:20480
	ds_read_b128 v[212:215], v167 offset:21504
	ds_read_b128 v[220:223], v167 offset:22528
	ds_read_b128 v[224:227], v167 offset:23552
	global_load_lds_dwordx4 v168, s[30:31]
	s_mov_b32 m0, s35
	s_nop 0
	global_load_lds_dwordx4 v172, s[30:31]
	s_setprio 1
	s_barrier
	s_waitcnt lgkmcnt(0)
	v_mfma_f32_16x16x32_bf16 v[64:67], v[20:23], v[144:147], v[64:67]
	v_mfma_f32_16x16x32_bf16 v[68:71], v[136:139], v[144:147], v[68:71]
	v_mfma_f32_16x16x32_bf16 v[108:111], v[20:23], v[200:203], v[108:111]
	v_mfma_f32_16x16x32_bf16 v[100:103], v[136:139], v[200:203], v[100:103]
	v_mfma_f32_16x16x32_bf16 v[116:119], v[20:23], v[208:211], v[116:119]
	v_mfma_f32_16x16x32_bf16 v[112:115], v[136:139], v[208:211], v[112:115]
	v_mfma_f32_16x16x32_bf16 v[20:23], v[20:23], v[220:223], v[132:135]
	v_mfma_f32_16x16x32_bf16 v[64:67], v[28:31], v[148:151], v[64:67]
	v_mfma_f32_16x16x32_bf16 v[68:71], v[140:143], v[148:151], v[68:71]
	v_mfma_f32_16x16x32_bf16 v[108:111], v[28:31], v[204:207], v[108:111]
	v_mfma_f32_16x16x32_bf16 v[100:103], v[140:143], v[204:207], v[100:103]
	v_mfma_f32_16x16x32_bf16 v[116:119], v[28:31], v[212:215], v[116:119]
	v_mfma_f32_16x16x32_bf16 v[112:115], v[140:143], v[212:215], v[112:115]
	v_mfma_f32_16x16x32_bf16 v[20:23], v[28:31], v[224:227], v[20:23]
	v_mfma_f32_16x16x32_bf16 v[28:31], v[136:139], v[220:223], v[128:131]
	v_mfma_f32_16x16x32_bf16 v[28:31], v[140:143], v[224:227], v[28:31]
	s_barrier
	s_setprio 0
	s_add_u32 s64, s26, 0x158000
	s_addc_u32 s65, s27, 0
	s_add_i32 s63, s53, s33
	s_mov_b32 m0, s63
	s_nop 0
	global_load_lds_dwordx4 v170, s[64:65]
	s_add_i32 m0, s63, 0x2000
	s_nop 0
	global_load_lds_dwordx4 v174, s[64:65]
	s_waitcnt vmcnt(6)
	s_setprio 1
	s_barrier
; #define PG8_STAGE(bufoff, gbase, voff) do { _Pragma("unroll") for (int _i = 0; _i < 2; ++_i) \
;         __builtin_amdgcn_global_load_lds((const unsigned*)((const char*)(gbase) + (voff)[_i]), (LAS unsigned*)(lds + (bufoff) + ldsw + _i * 8192), 16, 0, 0); } while (0)
; #define PG8_LDA(dst, b, h) do { _Pragma("unroll") for (int m = 0; m < 4; ++m) _Pragma("unroll") for (int k = 0; k < 2; ++k) dst[m][k] = *(const LAS bf16x8*)(lds + PG8_SA(b, h) + aoff + m * 2048 + k * 1024); } while (0)
; #define PG8_LDB(dst, b, h) do { _Pragma("unroll") for (int n = 0; n < 2; ++n) _Pragma("unroll") for (int k = 0; k < 2; ++k) dst[n][k] = *(const LAS bf16x8*)(lds + PG8_SB(b, h) + boff + n * 2048 + k * 1024); } while (0)
; #define PG8_MMA(ai, bj, At, Bt) do { __builtin_amdgcn_s_setprio(1); _Pragma("unroll") for (int m = 0; m < 4; ++m) _Pragma("unroll") for (int n = 0; n < 2; ++n) _Pragma("unroll") for (int k = 0; k < 2; ++k) \
;         acc[ai][bj][m][n] = __builtin_amdgcn_mfma_f32_16x16x32_bf16(Bt[n][k], At[m][k], acc[ai][bj][m][n], 0, 0, 0); __builtin_amdgcn_s_setprio(0); } while (0)
; #define PG8_WAIT_V(n) asm volatile("s_waitcnt vmcnt(" #n ")" ::: "memory")
; #define PG8_WAIT_L(n) asm volatile("s_waitcnt lgkmcnt(" #n ")" ::: "memory")
; #define PG8_BAR __builtin_amdgcn_s_barrier()
; #define PG8_SCHED __builtin_amdgcn_sched_barrier(0)
; template <class Epi, class Sched, bool ATILE = false>
; __device__ __forceinline__ void gemm_phase(LAS unsigned char* lds, const Gemm g, const Sched& S, const Epi& E) {
;     ...
;             PG8_WAIT_V(6); PG8_BAR; PG8_MMA(1, 1, At, B1); PG8_BAR;
;             PG8_LDB(B0, 1, 0); PG8_SCHED; PG8_LDA(At, 1, 0); PG8_STAGE(PG8_SA(0, 1), a2 + hstepA, voffA);
;             PG8_WAIT_L(8); PG8_BAR; PG8_WAIT_L(0); PG8_MMA(0, 0, At, B0); PG8_BAR; PG8_SCHED;
;             PG8_LDB(B1, 1, 1); PG8_STAGE(PG8_SB(1, 0), b3, voffB);
;             PG8_BAR; PG8_WAIT_L(0); PG8_MMA(0, 1, At, B1); PG8_BAR;
;             PG8_LDA(At, 1, 1); PG8_STAGE(PG8_SA(1, 0), a3, voffA);
	v_mfma_f32_16x16x32_bf16 v[76:79], v[228:231], v[144:147], v[76:79]
	v_mfma_f32_16x16x32_bf16 v[72:75], v[236:239], v[144:147], v[72:75]
	v_mfma_f32_16x16x32_bf16 v[88:91], v[228:231], v[200:203], v[88:91]
	v_mfma_f32_16x16x32_bf16 v[80:83], v[236:239], v[200:203], v[80:83]
	v_mfma_f32_16x16x32_bf16 v[104:107], v[228:231], v[208:211], v[104:107]
	v_mfma_f32_16x16x32_bf16 v[96:99], v[236:239], v[208:211], v[96:99]
	v_mfma_f32_16x16x32_bf16 v[120:123], v[228:231], v[220:223], v[120:123]
	v_mfma_f32_16x16x32_bf16 v[124:127], v[236:239], v[220:223], v[124:127]
	v_mfma_f32_16x16x32_bf16 v[76:79], v[232:235], v[148:151], v[76:79]
	v_mfma_f32_16x16x32_bf16 v[72:75], v[240:243], v[148:151], v[72:75]
	v_mfma_f32_16x16x32_bf16 v[88:91], v[232:235], v[204:207], v[88:91]
	v_mfma_f32_16x16x32_bf16 v[80:83], v[240:243], v[204:207], v[80:83]
	v_mfma_f32_16x16x32_bf16 v[104:107], v[232:235], v[212:215], v[104:107]
	v_mfma_f32_16x16x32_bf16 v[96:99], v[240:243], v[212:215], v[96:99]
	v_mfma_f32_16x16x32_bf16 v[120:123], v[232:235], v[224:227], v[120:123]
	v_mfma_f32_16x16x32_bf16 v[124:127], v[240:243], v[224:227], v[124:127]
	s_barrier
	s_setprio 0
	s_add_i32 s63, 0, 0x18000
	v_add_u32_e32 v140, s63, v161
	ds_read_b128 v[128:131], v140
	ds_read_b128 v[132:135], v140 offset:1024
	ds_read_b128 v[136:139], v140 offset:2048
	ds_read_b128 v[140:143], v140 offset:3072
	s_add_u32 s30, s30, 0x4000
	s_addc_u32 s31, s31, 0
	s_mov_b32 m0, s36
	ds_read_b128 v[144:147], v167 offset:32768
	ds_read_b128 v[148:151], v167 offset:33792
	ds_read_b128 v[200:203], v167 offset:34816
	ds_read_b128 v[204:207], v167 offset:35840
	ds_read_b128 v[208:211], v167 offset:36864
	ds_read_b128 v[212:215], v167 offset:37888
	ds_read_b128 v[220:223], v167 offset:38912
	ds_read_b128 v[224:227], v167 offset:39936
	global_load_lds_dwordx4 v168, s[30:31]
	s_mov_b32 m0, s37
	s_nop 0
	global_load_lds_dwordx4 v172, s[30:31]
	s_waitcnt lgkmcnt(8)
	s_setprio 1
	s_barrier
	s_waitcnt lgkmcnt(0)
	v_mfma_f32_16x16x32_bf16 v[0:3], v[128:131], v[144:147], v[0:3]
	v_mfma_f32_16x16x32_bf16 v[4:7], v[136:139], v[144:147], v[4:7]
	v_mfma_f32_16x16x32_bf16 v[44:47], v[128:131], v[200:203], v[44:47]
	v_mfma_f32_16x16x32_bf16 v[36:39], v[136:139], v[200:203], v[36:39]
	v_mfma_f32_16x16x32_bf16 v[52:55], v[128:131], v[208:211], v[52:55]
	v_mfma_f32_16x16x32_bf16 v[48:51], v[136:139], v[208:211], v[48:51]
	v_mfma_f32_16x16x32_bf16 v[92:95], v[128:131], v[220:223], v[92:95]
	v_mfma_f32_16x16x32_bf16 v[84:87], v[136:139], v[220:223], v[84:87]
	v_mfma_f32_16x16x32_bf16 v[0:3], v[132:135], v[148:151], v[0:3]
	v_mfma_f32_16x16x32_bf16 v[4:7], v[140:143], v[148:151], v[4:7]
	v_mfma_f32_16x16x32_bf16 v[44:47], v[132:135], v[204:207], v[44:47]
	v_mfma_f32_16x16x32_bf16 v[36:39], v[140:143], v[204:207], v[36:39]
	v_mfma_f32_16x16x32_bf16 v[52:55], v[132:135], v[212:215], v[52:55]
	v_mfma_f32_16x16x32_bf16 v[48:51], v[140:143], v[212:215], v[48:51]
	v_mfma_f32_16x16x32_bf16 v[92:95], v[132:135], v[224:227], v[92:95]
	v_mfma_f32_16x16x32_bf16 v[84:87], v[140:143], v[224:227], v[84:87]
	s_barrier
	s_setprio 0
	s_add_i32 s30, 0, 0x1c000
	s_add_i32 s31, s63, s33
	v_add_u32_e32 v219, s30, v161
	s_mov_b32 m0, s31
	ds_read_b128 v[228:231], v219
	ds_read_b128 v[232:235], v219 offset:1024
	ds_read_b128 v[236:239], v219 offset:2048
	ds_read_b128 v[240:243], v219 offset:3072
	global_load_lds_dwordx4 v170, s[98:99]
	s_add_i32 m0, s31, 0x2000
	s_nop 0
	global_load_lds_dwordx4 v174, s[98:99]
	s_setprio 1
	s_barrier
	s_waitcnt lgkmcnt(0)
	v_mfma_f32_16x16x32_bf16 v[12:15], v[228:231], v[144:147], v[12:15]
	v_mfma_f32_16x16x32_bf16 v[8:11], v[236:239], v[144:147], v[8:11]
	v_mfma_f32_16x16x32_bf16 v[24:27], v[228:231], v[200:203], v[24:27]
	v_mfma_f32_16x16x32_bf16 v[16:19], v[236:239], v[200:203], v[16:19]
	v_mfma_f32_16x16x32_bf16 v[40:43], v[228:231], v[208:211], v[40:43]
	v_mfma_f32_16x16x32_bf16 v[32:35], v[236:239], v[208:211], v[32:35]
	v_mfma_f32_16x16x32_bf16 v[56:59], v[228:231], v[220:223], v[56:59]
	v_mfma_f32_16x16x32_bf16 v[60:63], v[236:239], v[220:223], v[60:63]
	v_mfma_f32_16x16x32_bf16 v[12:15], v[232:235], v[148:151], v[12:15]
	v_mfma_f32_16x16x32_bf16 v[8:11], v[240:243], v[148:151], v[8:11]
	v_mfma_f32_16x16x32_bf16 v[24:27], v[232:235], v[204:207], v[24:27]
	v_mfma_f32_16x16x32_bf16 v[16:19], v[240:243], v[204:207], v[16:19]
	v_mfma_f32_16x16x32_bf16 v[40:43], v[232:235], v[212:215], v[40:43]
	v_mfma_f32_16x16x32_bf16 v[32:35], v[240:243], v[212:215], v[32:35]
	v_mfma_f32_16x16x32_bf16 v[56:59], v[232:235], v[224:227], v[56:59]
	v_mfma_f32_16x16x32_bf16 v[60:63], v[240:243], v[224:227], v[60:63]
	s_barrier
	s_setprio 0
	s_mov_b32 m0, s39
	ds_read_b128 v[144:147], v167 offset:49152
	ds_read_b128 v[148:151], v167 offset:50176
	ds_read_b128 v[200:203], v167 offset:51200
	ds_read_b128 v[204:207], v167 offset:52224
	ds_read_b128 v[208:211], v167 offset:53248
	ds_read_b128 v[212:215], v167 offset:54272
	ds_read_b128 v[220:223], v167 offset:55296
	ds_read_b128 v[224:227], v167 offset:56320
	global_load_lds_dwordx4 v168, s[28:29]
	s_mov_b32 m0, s40
	s_nop 0
	global_load_lds_dwordx4 v172, s[28:29]
	s_setprio 1
	s_barrier
; __device__ __forceinline__ float bflo(unsigned w) { return __uint_as_float(w << 16); }
; __device__ __forceinline__ float bfhi(unsigned w) { return __uint_as_float(w & 0xffff0000u); }
; #define PG8_STAGE(bufoff, gbase, voff) do { _Pragma("unroll") for (int _i = 0; _i < 2; ++_i) \
;         __builtin_amdgcn_global_load_lds((const unsigned*)((const char*)(gbase) + (voff)[_i]), (LAS unsigned*)(lds + (bufoff) + ldsw + _i * 8192), 16, 0, 0); } while (0)
; #define PG8_LDA(dst, b, h) do { _Pragma("unroll") for (int m = 0; m < 4; ++m) _Pragma("unroll") for (int k = 0; k < 2; ++k) dst[m][k] = *(const LAS bf16x8*)(lds + PG8_SA(b, h) + aoff + m * 2048 + k * 1024); } while (0)
; #define PG8_MMA(ai, bj, At, Bt) do { __builtin_amdgcn_s_setprio(1); _Pragma("unroll") for (int m = 0; m < 4; ++m) _Pragma("unroll") for (int n = 0; n < 2; ++n) _Pragma("unroll") for (int k = 0; k < 2; ++k) \
;         acc[ai][bj][m][n] = __builtin_amdgcn_mfma_f32_16x16x32_bf16(Bt[n][k], At[m][k], acc[ai][bj][m][n], 0, 0, 0); __builtin_amdgcn_s_setprio(0); } while (0)
; #define PG8_WAIT_V(n) asm volatile("s_waitcnt vmcnt(" #n ")" ::: "memory")
; #define PG8_WAIT_L(n) asm volatile("s_waitcnt lgkmcnt(" #n ")" ::: "memory")
; #define PG8_BAR __builtin_amdgcn_s_barrier()
; #define PG8_SCHED __builtin_amdgcn_sched_barrier(0)
; template <class Epi, class Sched, bool ATILE = false>
; __device__ __forceinline__ void gemm_phase(LAS unsigned char* lds, const Gemm g, const Sched& S, const Epi& E) {
;     ...
;             PG8_LDA(At, 1, 1); PG8_STAGE(PG8_SA(1, 0), a3, voffA);
;             PG8_BAR; PG8_WAIT_L(0); PG8_MMA(1, 0, At, B0); PG8_BAR; PG8_SCHED;
;             PG8_STAGE(PG8_SB(1, 1), b3 + hstepB, voffB);
;             PG8_WAIT_V(6); PG8_BAR; PG8_MMA(1, 1, At, B1); PG8_BAR;
;     __device__ __forceinline__ void operator()(const f32x4 (&acc)[2][2][4][2], const Unit& u, int wr, int wc, int fr, int fq) const {
;     ...
;                     const f32x4 v0 = (f32x4){bflo(x.x), bfhi(x.x), bflo(x.y), bfhi(x.y)} + alpha * acc[ai][bj][m][0];
;                     const f32x4 v1 = (f32x4){bflo(x.z), bfhi(x.z), bflo(x.w), bfhi(x.w)} + alpha * acc[ai][bj][m][1];
	s_waitcnt lgkmcnt(0)
	v_mfma_f32_16x16x32_bf16 v[64:67], v[128:131], v[144:147], v[64:67]
	v_mfma_f32_16x16x32_bf16 v[108:111], v[128:131], v[200:203], v[108:111]
	v_mfma_f32_16x16x32_bf16 v[116:119], v[128:131], v[208:211], v[116:119]
	v_mfma_f32_16x16x32_bf16 v[20:23], v[128:131], v[220:223], v[20:23]
	v_mfma_f32_16x16x32_bf16 v[64:67], v[132:135], v[148:151], v[64:67]
	v_mfma_f32_16x16x32_bf16 v[68:71], v[136:139], v[144:147], v[68:71]
	v_mfma_f32_16x16x32_bf16 v[108:111], v[132:135], v[204:207], v[108:111]
	v_mfma_f32_16x16x32_bf16 v[100:103], v[136:139], v[200:203], v[100:103]
	v_mfma_f32_16x16x32_bf16 v[116:119], v[132:135], v[212:215], v[116:119]
	v_mfma_f32_16x16x32_bf16 v[112:115], v[136:139], v[208:211], v[112:115]
	v_mfma_f32_16x16x32_bf16 v[132:135], v[132:135], v[224:227], v[20:23]
	v_mfma_f32_16x16x32_bf16 v[20:23], v[136:139], v[220:223], v[28:31]
	v_mfma_f32_16x16x32_bf16 v[68:71], v[140:143], v[148:151], v[68:71]
	v_mfma_f32_16x16x32_bf16 v[100:103], v[140:143], v[204:207], v[100:103]
	v_mfma_f32_16x16x32_bf16 v[112:115], v[140:143], v[212:215], v[112:115]
	v_mfma_f32_16x16x32_bf16 v[128:131], v[140:143], v[224:227], v[20:23]
	s_barrier
	s_setprio 0
	s_add_u32 s26, s26, 0x158080
	s_addc_u32 s27, s27, 0
	s_add_i32 s28, s30, s33
	s_mov_b32 m0, s28
	s_nop 0
	global_load_lds_dwordx4 v170, s[26:27]
	s_add_i32 m0, s28, 0x2000
	s_nop 0
	global_load_lds_dwordx4 v174, s[26:27]
	s_waitcnt vmcnt(6)
	s_setprio 1
	s_barrier
	v_mfma_f32_16x16x32_bf16 v[20:23], v[228:231], v[144:147], v[76:79]
	v_mfma_f32_16x16x32_bf16 v[76:79], v[232:235], v[148:151], v[20:23]
	v_mfma_f32_16x16x32_bf16 v[20:23], v[236:239], v[144:147], v[72:75]
	v_mfma_f32_16x16x32_bf16 v[72:75], v[240:243], v[148:151], v[20:23]
	v_mfma_f32_16x16x32_bf16 v[20:23], v[228:231], v[200:203], v[88:91]
	v_mfma_f32_16x16x32_bf16 v[88:91], v[232:235], v[204:207], v[20:23]
	v_mfma_f32_16x16x32_bf16 v[20:23], v[236:239], v[200:203], v[80:83]
	v_mfma_f32_16x16x32_bf16 v[80:83], v[240:243], v[204:207], v[20:23]
	v_mfma_f32_16x16x32_bf16 v[20:23], v[228:231], v[208:211], v[104:107]
	v_mfma_f32_16x16x32_bf16 v[104:107], v[232:235], v[212:215], v[20:23]
	v_mfma_f32_16x16x32_bf16 v[20:23], v[236:239], v[208:211], v[96:99]
	v_mfma_f32_16x16x32_bf16 v[96:99], v[240:243], v[212:215], v[20:23]
	v_mfma_f32_16x16x32_bf16 v[20:23], v[228:231], v[220:223], v[120:123]
	v_mfma_f32_16x16x32_bf16 v[120:123], v[232:235], v[224:227], v[20:23]
	v_mfma_f32_16x16x32_bf16 v[20:23], v[236:239], v[220:223], v[124:127]
	v_mfma_f32_16x16x32_bf16 v[124:127], v[240:243], v[224:227], v[20:23]
	s_barrier
	s_setprio 0
	s_add_u32 s60, s60, 0x100
	s_addc_u32 s61, s61, 0
	s_add_u32 s24, s24, 0x10000
	s_addc_u32 s25, s25, 0
	s_cmp_ge_i32 s62, s59
	s_mov_b32 s26, s62
	s_cbranch_scc0 .LBB0_739
	v_pk_mul_f32 v[2:3], v[2:3], 0.5 op_sel_hi:[1,0]
	v_pk_mul_f32 v[0:1], v[0:1], 0.5 op_sel_hi:[1,0]
	v_pk_mul_f32 v[6:7], v[6:7], 0.5 op_sel_hi:[1,0]
	v_pk_mul_f32 v[4:5], v[4:5], 0.5 op_sel_hi:[1,0]
	v_pk_mul_f32 v[22:23], v[14:15], 0.5 op_sel_hi:[1,0]
	v_pk_mul_f32 v[20:21], v[12:13], 0.5 op_sel_hi:[1,0]
	v_pk_mul_f32 v[30:31], v[10:11], 0.5 op_sel_hi:[1,0]
	v_pk_mul_f32 v[28:29], v[8:9], 0.5 op_sel_hi:[1,0]
	v_pk_mul_f32 v[10:11], v[46:47], 0.5 op_sel_hi:[1,0]
	v_pk_mul_f32 v[8:9], v[44:45], 0.5 op_sel_hi:[1,0]
	v_pk_mul_f32 v[14:15], v[38:39], 0.5 op_sel_hi:[1,0]
	v_pk_mul_f32 v[12:13], v[36:37], 0.5 op_sel_hi:[1,0]
	v_pk_mul_f32 v[38:39], v[26:27], 0.5 op_sel_hi:[1,0]
	v_pk_mul_f32 v[36:37], v[24:25], 0.5 op_sel_hi:[1,0]
	v_pk_mul_f32 v[46:47], v[18:19], 0.5 op_sel_hi:[1,0]
	v_pk_mul_f32 v[44:45], v[16:17], 0.5 op_sel_hi:[1,0]
	v_pk_mul_f32 v[18:19], v[54:55], 0.5 op_sel_hi:[1,0]
	v_pk_mul_f32 v[16:17], v[52:53], 0.5 op_sel_hi:[1,0]
	v_pk_mul_f32 v[26:27], v[50:51], 0.5 op_sel_hi:[1,0]
	v_pk_mul_f32 v[24:25], v[48:49], 0.5 op_sel_hi:[1,0]
	v_pk_mul_f32 v[50:51], v[42:43], 0.5 op_sel_hi:[1,0]
	v_pk_mul_f32 v[48:49], v[40:41], 0.5 op_sel_hi:[1,0]
	v_pk_mul_f32 v[54:55], v[34:35], 0.5 op_sel_hi:[1,0]
	v_pk_mul_f32 v[52:53], v[32:33], 0.5 op_sel_hi:[1,0]
	v_pk_mul_f32 v[34:35], v[94:95], 0.5 op_sel_hi:[1,0]
	v_pk_mul_f32 v[32:33], v[92:93], 0.5 op_sel_hi:[1,0]
	v_pk_mul_f32 v[42:43], v[86:87], 0.5 op_sel_hi:[1,0]
	v_pk_mul_f32 v[40:41], v[84:85], 0.5 op_sel_hi:[1,0]
	v_pk_mul_f32 v[58:59], v[58:59], 0.5 op_sel_hi:[1,0]
	v_pk_mul_f32 v[56:57], v[56:57], 0.5 op_sel_hi:[1,0]
	v_pk_mul_f32 v[62:63], v[62:63], 0.5 op_sel_hi:[1,0]
	v_pk_mul_f32 v[60:61], v[60:61], 0.5 op_sel_hi:[1,0]
	v_pk_mul_f32 v[66:67], v[66:67], 0.5 op_sel_hi:[1,0]
	v_pk_mul_f32 v[64:65], v[64:65], 0.5 op_sel_hi:[1,0]
	v_pk_mul_f32 v[70:71], v[70:71], 0.5 op_sel_hi:[1,0]
	v_pk_mul_f32 v[68:69], v[68:69], 0.5 op_sel_hi:[1,0]
	v_pk_mul_f32 v[86:87], v[78:79], 0.5 op_sel_hi:[1,0]
	v_pk_mul_f32 v[84:85], v[76:77], 0.5 op_sel_hi:[1,0]
	v_pk_mul_f32 v[94:95], v[74:75], 0.5 op_sel_hi:[1,0]
	v_pk_mul_f32 v[92:93], v[72:73], 0.5 op_sel_hi:[1,0]
	v_pk_mul_f32 v[74:75], v[110:111], 0.5 op_sel_hi:[1,0]
	v_pk_mul_f32 v[72:73], v[108:109], 0.5 op_sel_hi:[1,0]
	v_pk_mul_f32 v[78:79], v[102:103], 0.5 op_sel_hi:[1,0]
	v_pk_mul_f32 v[76:77], v[100:101], 0.5 op_sel_hi:[1,0]
	v_pk_mul_f32 v[102:103], v[90:91], 0.5 op_sel_hi:[1,0]
	v_pk_mul_f32 v[100:101], v[88:89], 0.5 op_sel_hi:[1,0]
	v_pk_mul_f32 v[110:111], v[82:83], 0.5 op_sel_hi:[1,0]
	v_pk_mul_f32 v[108:109], v[80:81], 0.5 op_sel_hi:[1,0]
	v_pk_mul_f32 v[82:83], v[118:119], 0.5 op_sel_hi:[1,0]
	v_pk_mul_f32 v[80:81], v[116:117], 0.5 op_sel_hi:[1,0]
	v_pk_mul_f32 v[90:91], v[114:115], 0.5 op_sel_hi:[1,0]
	v_pk_mul_f32 v[88:89], v[112:113], 0.5 op_sel_hi:[1,0]
	v_pk_mul_f32 v[114:115], v[106:107], 0.5 op_sel_hi:[1,0]
	v_pk_mul_f32 v[112:113], v[104:105], 0.5 op_sel_hi:[1,0]
	v_pk_mul_f32 v[118:119], v[98:99], 0.5 op_sel_hi:[1,0]
	v_pk_mul_f32 v[116:117], v[96:97], 0.5 op_sel_hi:[1,0]
	v_pk_mul_f32 v[98:99], v[134:135], 0.5 op_sel_hi:[1,0]
	v_pk_mul_f32 v[96:97], v[132:133], 0.5 op_sel_hi:[1,0]
	v_pk_mul_f32 v[106:107], v[130:131], 0.5 op_sel_hi:[1,0]
	v_pk_mul_f32 v[104:105], v[128:129], 0.5 op_sel_hi:[1,0]
	v_pk_mul_f32 v[122:123], v[122:123], 0.5 op_sel_hi:[1,0]
	v_pk_mul_f32 v[120:121], v[120:121], 0.5 op_sel_hi:[1,0]
	v_pk_mul_f32 v[126:127], v[126:127], 0.5 op_sel_hi:[1,0]
	v_pk_mul_f32 v[124:125], v[124:125], 0.5 op_sel_hi:[1,0]
	s_branch .LBB0_744

; #define PG8_STAGE(bufoff, gbase, voff) do { _Pragma("unroll") for (int _i = 0; _i < 2; ++_i) \
;         __builtin_amdgcn_global_load_lds((const unsigned*)((const char*)(gbase) + (voff)[_i]), (LAS unsigned*)(lds + (bufoff) + ldsw + _i * 8192), 16, 0, 0); } while (0)
; #define PG8_LDA(dst, b, h) do { _Pragma("unroll") for (int m = 0; m < 4; ++m) _Pragma("unroll") for (int k = 0; k < 2; ++k) dst[m][k] = *(const LAS bf16x8*)(lds + PG8_SA(b, h) + aoff + m * 2048 + k * 1024); } while (0)
; #define PG8_LDB(dst, b, h) do { _Pragma("unroll") for (int n = 0; n < 2; ++n) _Pragma("unroll") for (int k = 0; k < 2; ++k) dst[n][k] = *(const LAS bf16x8*)(lds + PG8_SB(b, h) + boff + n * 2048 + k * 1024); } while (0)
; #define PG8_MMA(ai, bj, At, Bt) do { __builtin_amdgcn_s_setprio(1); _Pragma("unroll") for (int m = 0; m < 4; ++m) _Pragma("unroll") for (int n = 0; n < 2; ++n) _Pragma("unroll") for (int k = 0; k < 2; ++k) \
;         acc[ai][bj][m][n] = __builtin_amdgcn_mfma_f32_16x16x32_bf16(Bt[n][k], At[m][k], acc[ai][bj][m][n], 0, 0, 0); __builtin_amdgcn_s_setprio(0); } while (0)
; #define PG8_WAIT_V(n) asm volatile("s_waitcnt vmcnt(" #n ")" ::: "memory")
; #define PG8_WAIT_L(n) asm volatile("s_waitcnt lgkmcnt(" #n ")" ::: "memory")
; template <class Epi, class Sched, bool ATILE = false>
; __device__ __forceinline__ void gemm_phase(LAS unsigned char* lds, const Gemm g, const Sched& S, const Epi& E) {
;     ...
;         for (int t = 0; t < nt; t += 2) {
;             const bool last = (t == nt - 2);
;             const char* a1 = cA + (size_t)(t + 1) * kstepA;
;             const char* a2 = last ? nA : cA + (size_t)(t + 2) * kstepA; const char* b2 = last ? nB : cB + (size_t)(t + 2) * kstep;
;             const char* a3 = a2 + kstepA; const char* b3 = b2 + kstep;
;             PG8_LDB(B0, 0, 0); PG8_SCHED; PG8_LDA(At, 0, 0); PG8_STAGE(PG8_SA(1, 1), a1 + hstepA, voffA);
;             PG8_WAIT_L(8); PG8_BAR; PG8_WAIT_L(0); PG8_MMA(0, 0, At, B0); PG8_BAR; PG8_SCHED;
;             PG8_LDB(B1, 0, 1); PG8_STAGE(PG8_SB(0, 0), b2, voffB);
;             PG8_BAR; PG8_WAIT_L(0); PG8_MMA(0, 1, At, B1); PG8_BAR;
;             PG8_LDA(At, 0, 1); PG8_STAGE(PG8_SA(0, 0), a2, voffA);
;             PG8_BAR; PG8_WAIT_L(0); PG8_MMA(1, 0, At, B0); PG8_BAR; PG8_SCHED;
;             PG8_STAGE(PG8_SB(0, 1), b2 + hstepB, voffB);
;             PG8_WAIT_V(6); PG8_BAR; PG8_MMA(1, 1, At, B1); PG8_BAR;
.LBB0_895:
	ds_read_b128 v[32:35], v165
	ds_read_b128 v[36:39], v165 offset:1024
	ds_read_b128 v[178:181], v165 offset:2048
	ds_read_b128 v[182:185], v165 offset:3072
	s_add_i32 s88, s73, 2
	s_add_u32 s84, s12, 0xfff80080
	s_addc_u32 s85, s13, -1
	s_cmp_eq_u32 s53, s73
	s_cselect_b32 s87, s11, s85
	s_cselect_b32 s86, s20, s84
	s_cselect_b32 s85, s41, s63
	s_cselect_b32 s84, s52, s62
	s_add_i32 m0, s35, 0xc000
	ds_read_b128 v[192:195], v167
	ds_read_b128 v[196:199], v167 offset:1024
	ds_read_b128 v[200:203], v167 offset:2048
	ds_read_b128 v[204:207], v167 offset:3072
	ds_read_b128 v[208:211], v167 offset:4096
	ds_read_b128 v[212:215], v167 offset:5120
	ds_read_b128 v[216:219], v167 offset:6144
	ds_read_b128 v[220:223], v167 offset:7168
	global_load_lds_dwordx4 v170, s[12:13]
	s_add_i32 m0, s35, 0xe000
	s_nop 0
	global_load_lds_dwordx4 v172, s[12:13]
	s_waitcnt lgkmcnt(8)
	s_setprio 1
	s_barrier
	s_waitcnt lgkmcnt(0)
	v_mfma_f32_16x16x32_bf16 v[132:135], v[32:35], v[192:195], v[132:135]
	v_mfma_f32_16x16x32_bf16 v[128:131], v[178:181], v[192:195], v[128:131]
	v_mfma_f32_16x16x32_bf16 v[116:119], v[32:35], v[200:203], v[116:119]
	v_mfma_f32_16x16x32_bf16 v[112:115], v[178:181], v[200:203], v[112:115]
	v_mfma_f32_16x16x32_bf16 v[100:103], v[32:35], v[208:211], v[100:103]
	v_mfma_f32_16x16x32_bf16 v[96:99], v[178:181], v[208:211], v[96:99]
	v_mfma_f32_16x16x32_bf16 v[84:87], v[32:35], v[216:219], v[84:87]
	v_mfma_f32_16x16x32_bf16 v[80:83], v[178:181], v[216:219], v[80:83]
	v_mfma_f32_16x16x32_bf16 v[132:135], v[36:39], v[196:199], v[132:135]
	v_mfma_f32_16x16x32_bf16 v[128:131], v[182:185], v[196:199], v[128:131]
	v_mfma_f32_16x16x32_bf16 v[116:119], v[36:39], v[204:207], v[116:119]
	v_mfma_f32_16x16x32_bf16 v[112:115], v[182:185], v[204:207], v[112:115]
	v_mfma_f32_16x16x32_bf16 v[100:103], v[36:39], v[212:215], v[100:103]
	v_mfma_f32_16x16x32_bf16 v[96:99], v[182:185], v[212:215], v[96:99]
	v_mfma_f32_16x16x32_bf16 v[84:87], v[36:39], v[220:223], v[84:87]
	v_mfma_f32_16x16x32_bf16 v[80:83], v[182:185], v[220:223], v[80:83]
	s_barrier
	s_setprio 0
	s_add_i32 s73, s43, s31
	s_add_u32 s98, s84, s22
	s_addc_u32 s99, s85, s23
	s_mov_b32 m0, s73
	ds_read_b128 v[224:227], v186
	ds_read_b128 v[228:231], v186 offset:1024
	ds_read_b128 v[232:235], v186 offset:2048
	ds_read_b128 v[236:239], v186 offset:3072
	global_load_lds_dwordx4 v138, s[84:85]
	s_add_i32 m0, s73, 0x2000
	s_nop 0
	global_load_lds_dwordx4 v142, s[84:85]
	s_setprio 1
	s_barrier
	s_waitcnt lgkmcnt(0)
	v_mfma_f32_16x16x32_bf16 v[124:127], v[224:227], v[192:195], v[124:127]
	v_mfma_f32_16x16x32_bf16 v[120:123], v[232:235], v[192:195], v[120:123]
	v_mfma_f32_16x16x32_bf16 v[108:111], v[224:227], v[200:203], v[108:111]
	v_mfma_f32_16x16x32_bf16 v[104:107], v[232:235], v[200:203], v[104:107]
	v_mfma_f32_16x16x32_bf16 v[92:95], v[224:227], v[208:211], v[92:95]
	v_mfma_f32_16x16x32_bf16 v[88:91], v[232:235], v[208:211], v[88:91]
	v_mfma_f32_16x16x32_bf16 v[76:79], v[224:227], v[216:219], v[76:79]
	v_mfma_f32_16x16x32_bf16 v[72:75], v[232:235], v[216:219], v[72:75]
	v_mfma_f32_16x16x32_bf16 v[124:127], v[228:231], v[196:199], v[124:127]
	v_mfma_f32_16x16x32_bf16 v[120:123], v[236:239], v[196:199], v[120:123]
	v_mfma_f32_16x16x32_bf16 v[108:111], v[228:231], v[204:207], v[108:111]
	v_mfma_f32_16x16x32_bf16 v[104:107], v[236:239], v[204:207], v[104:107]
	v_mfma_f32_16x16x32_bf16 v[92:95], v[228:231], v[212:215], v[92:95]
	v_mfma_f32_16x16x32_bf16 v[88:91], v[236:239], v[212:215], v[88:91]
	v_mfma_f32_16x16x32_bf16 v[76:79], v[228:231], v[220:223], v[76:79]
	v_mfma_f32_16x16x32_bf16 v[72:75], v[236:239], v[220:223], v[72:75]
	s_barrier
	s_setprio 0
	s_mov_b32 m0, s35
	s_add_u32 s100, s86, s22
	s_addc_u32 s101, s87, s23
	ds_read_b128 v[192:195], v167 offset:16384
	ds_read_b128 v[196:199], v167 offset:17408
	ds_read_b128 v[200:203], v167 offset:18432
	ds_read_b128 v[204:207], v167 offset:19456
	ds_read_b128 v[208:211], v167 offset:20480
	ds_read_b128 v[212:215], v167 offset:21504
	ds_read_b128 v[216:219], v167 offset:22528
	ds_read_b128 v[220:223], v167 offset:23552
	global_load_lds_dwordx4 v136, s[86:87]
	s_mov_b32 m0, s37
	s_nop 0
	global_load_lds_dwordx4 v140, s[86:87]
	s_setprio 1
	s_barrier
	s_waitcnt lgkmcnt(0)
	v_mfma_f32_16x16x32_bf16 v[68:71], v[32:35], v[192:195], v[68:71]
	v_mfma_f32_16x16x32_bf16 v[64:67], v[178:181], v[192:195], v[64:67]
	v_mfma_f32_16x16x32_bf16 v[52:55], v[32:35], v[200:203], v[52:55]
	v_mfma_f32_16x16x32_bf16 v[48:51], v[178:181], v[200:203], v[48:51]
	v_mfma_f32_16x16x32_bf16 v[28:31], v[32:35], v[208:211], v[28:31]
	v_mfma_f32_16x16x32_bf16 v[24:27], v[178:181], v[208:211], v[24:27]
	v_mfma_f32_16x16x32_bf16 v[12:15], v[32:35], v[216:219], v[12:15]
	v_mfma_f32_16x16x32_bf16 v[8:11], v[178:181], v[216:219], v[8:11]
	v_mfma_f32_16x16x32_bf16 v[68:71], v[36:39], v[196:199], v[68:71]
	v_mfma_f32_16x16x32_bf16 v[64:67], v[182:185], v[196:199], v[64:67]
	v_mfma_f32_16x16x32_bf16 v[52:55], v[36:39], v[204:207], v[52:55]
	v_mfma_f32_16x16x32_bf16 v[48:51], v[182:185], v[204:207], v[48:51]
	v_mfma_f32_16x16x32_bf16 v[28:31], v[36:39], v[212:215], v[28:31]
	v_mfma_f32_16x16x32_bf16 v[24:27], v[182:185], v[212:215], v[24:27]
	v_mfma_f32_16x16x32_bf16 v[12:15], v[36:39], v[220:223], v[12:15]
	v_mfma_f32_16x16x32_bf16 v[8:11], v[182:185], v[220:223], v[8:11]
	s_barrier
	s_setprio 0
	s_add_u32 vcc_lo, s84, 0x80000
	s_addc_u32 vcc_hi, s85, 0
	s_add_i32 s73, s56, s31
	v_lshl_add_u64 v[32:33], vcc, 0, v[138:139]
	s_mov_b32 m0, s73
	s_nop 0
	global_load_lds_dwordx4 v[32:33], off
	v_lshl_add_u64 v[32:33], vcc, 0, v[142:143]
	s_add_i32 m0, s73, 0x2000
	s_nop 0
	global_load_lds_dwordx4 v[32:33], off
	s_waitcnt vmcnt(6)
	s_setprio 1
	s_barrier
; #define PG8_STAGE(bufoff, gbase, voff) do { _Pragma("unroll") for (int _i = 0; _i < 2; ++_i) \
;         __builtin_amdgcn_global_load_lds((const unsigned*)((const char*)(gbase) + (voff)[_i]), (LAS unsigned*)(lds + (bufoff) + ldsw + _i * 8192), 16, 0, 0); } while (0)
; #define PG8_LDA(dst, b, h) do { _Pragma("unroll") for (int m = 0; m < 4; ++m) _Pragma("unroll") for (int k = 0; k < 2; ++k) dst[m][k] = *(const LAS bf16x8*)(lds + PG8_SA(b, h) + aoff + m * 2048 + k * 1024); } while (0)
; #define PG8_LDB(dst, b, h) do { _Pragma("unroll") for (int n = 0; n < 2; ++n) _Pragma("unroll") for (int k = 0; k < 2; ++k) dst[n][k] = *(const LAS bf16x8*)(lds + PG8_SB(b, h) + boff + n * 2048 + k * 1024); } while (0)
; #define PG8_MMA(ai, bj, At, Bt) do { __builtin_amdgcn_s_setprio(1); _Pragma("unroll") for (int m = 0; m < 4; ++m) _Pragma("unroll") for (int n = 0; n < 2; ++n) _Pragma("unroll") for (int k = 0; k < 2; ++k) \
;         acc[ai][bj][m][n] = __builtin_amdgcn_mfma_f32_16x16x32_bf16(Bt[n][k], At[m][k], acc[ai][bj][m][n], 0, 0, 0); __builtin_amdgcn_s_setprio(0); } while (0)
; #define PG8_WAIT_V(n) asm volatile("s_waitcnt vmcnt(" #n ")" ::: "memory")
; #define PG8_WAIT_L(n) asm volatile("s_waitcnt lgkmcnt(" #n ")" ::: "memory")
; #define PG8_BAR __builtin_amdgcn_s_barrier()
; #define PG8_SCHED __builtin_amdgcn_sched_barrier(0)
; template <class Epi, class Sched, bool ATILE = false>
; __device__ __forceinline__ void gemm_phase(LAS unsigned char* lds, const Gemm g, const Sched& S, const Epi& E) {
;     ...
;             PG8_WAIT_V(6); PG8_BAR; PG8_MMA(1, 1, At, B1); PG8_BAR;
;             PG8_LDB(B0, 1, 0); PG8_SCHED; PG8_LDA(At, 1, 0); PG8_STAGE(PG8_SA(0, 1), a2 + hstepA, voffA);
;             PG8_WAIT_L(8); PG8_BAR; PG8_WAIT_L(0); PG8_MMA(0, 0, At, B0); PG8_BAR; PG8_SCHED;
;             PG8_LDB(B1, 1, 1); PG8_STAGE(PG8_SB(1, 0), b3, voffB);
;             PG8_BAR; PG8_WAIT_L(0); PG8_MMA(0, 1, At, B1); PG8_BAR;
	v_mfma_f32_16x16x32_bf16 v[44:47], v[224:227], v[200:203], v[44:47]
	v_mfma_f32_16x16x32_bf16 v[40:43], v[232:235], v[200:203], v[40:43]
	v_mfma_f32_16x16x32_bf16 v[20:23], v[224:227], v[208:211], v[20:23]
	v_mfma_f32_16x16x32_bf16 v[16:19], v[232:235], v[208:211], v[16:19]
	v_mfma_f32_16x16x32_bf16 v[4:7], v[224:227], v[216:219], v[4:7]
	v_mfma_f32_16x16x32_bf16 v[0:3], v[232:235], v[216:219], v[0:3]
	v_mfma_f32_16x16x32_bf16 v[32:35], v[224:227], v[192:195], v[60:63]
	v_mfma_f32_16x16x32_bf16 v[36:39], v[232:235], v[192:195], v[56:59]
	v_mfma_f32_16x16x32_bf16 v[44:47], v[228:231], v[204:207], v[44:47]
	v_mfma_f32_16x16x32_bf16 v[40:43], v[236:239], v[204:207], v[40:43]
	v_mfma_f32_16x16x32_bf16 v[20:23], v[228:231], v[212:215], v[20:23]
	v_mfma_f32_16x16x32_bf16 v[16:19], v[236:239], v[212:215], v[16:19]
	v_mfma_f32_16x16x32_bf16 v[4:7], v[228:231], v[220:223], v[4:7]
	v_mfma_f32_16x16x32_bf16 v[0:3], v[236:239], v[220:223], v[0:3]
	v_mfma_f32_16x16x32_bf16 v[32:35], v[228:231], v[196:199], v[32:35]
	v_mfma_f32_16x16x32_bf16 v[36:39], v[236:239], v[196:199], v[36:39]
	s_barrier
	s_setprio 0
	s_add_i32 s73, 0, 0x18000
	v_add_u32_e32 v144, s73, v161
	ds_read_b128 v[56:59], v144
	ds_read_b128 v[60:63], v144 offset:1024
	ds_read_b128 v[178:181], v144 offset:2048
	ds_read_b128 v[182:185], v144 offset:3072
	s_add_u32 s86, s86, 0x80000
	s_addc_u32 s87, s87, 0
	s_mov_b32 m0, s39
	ds_read_b128 v[192:195], v167 offset:32768
	ds_read_b128 v[196:199], v167 offset:33792
	ds_read_b128 v[200:203], v167 offset:34816
	ds_read_b128 v[204:207], v167 offset:35840
	ds_read_b128 v[208:211], v167 offset:36864
	ds_read_b128 v[212:215], v167 offset:37888
	ds_read_b128 v[216:219], v167 offset:38912
	ds_read_b128 v[220:223], v167 offset:39936
	global_load_lds_dwordx4 v136, s[86:87]
	s_mov_b32 m0, s97
	s_nop 0
	global_load_lds_dwordx4 v140, s[86:87]
	s_waitcnt lgkmcnt(8)
	s_setprio 1
	s_barrier
	s_waitcnt lgkmcnt(0)
	v_mfma_f32_16x16x32_bf16 v[132:135], v[56:59], v[192:195], v[132:135]
	v_mfma_f32_16x16x32_bf16 v[128:131], v[178:181], v[192:195], v[128:131]
	v_mfma_f32_16x16x32_bf16 v[116:119], v[56:59], v[200:203], v[116:119]
	v_mfma_f32_16x16x32_bf16 v[112:115], v[178:181], v[200:203], v[112:115]
	v_mfma_f32_16x16x32_bf16 v[100:103], v[56:59], v[208:211], v[100:103]
	v_mfma_f32_16x16x32_bf16 v[96:99], v[178:181], v[208:211], v[96:99]
	v_mfma_f32_16x16x32_bf16 v[84:87], v[56:59], v[216:219], v[84:87]
	v_mfma_f32_16x16x32_bf16 v[80:83], v[178:181], v[216:219], v[80:83]
	v_mfma_f32_16x16x32_bf16 v[132:135], v[60:63], v[196:199], v[132:135]
	v_mfma_f32_16x16x32_bf16 v[128:131], v[182:185], v[196:199], v[128:131]
	v_mfma_f32_16x16x32_bf16 v[116:119], v[60:63], v[204:207], v[116:119]
	v_mfma_f32_16x16x32_bf16 v[112:115], v[182:185], v[204:207], v[112:115]
	v_mfma_f32_16x16x32_bf16 v[100:103], v[60:63], v[212:215], v[100:103]
	v_mfma_f32_16x16x32_bf16 v[96:99], v[182:185], v[212:215], v[96:99]
	v_mfma_f32_16x16x32_bf16 v[84:87], v[60:63], v[220:223], v[84:87]
	v_mfma_f32_16x16x32_bf16 v[80:83], v[182:185], v[220:223], v[80:83]
	s_barrier
	s_setprio 0
	s_add_i32 s86, 0, 0x1c000
	s_add_i32 s73, s73, s31
	v_add_u32_e32 v144, s86, v161
	s_mov_b32 m0, s73
	ds_read_b128 v[224:227], v144
	ds_read_b128 v[228:231], v144 offset:1024
	ds_read_b128 v[232:235], v144 offset:2048
	ds_read_b128 v[236:239], v144 offset:3072
	global_load_lds_dwordx4 v138, s[98:99]
	s_add_i32 m0, s73, 0x2000
	s_nop 0
	global_load_lds_dwordx4 v142, s[98:99]
	s_setprio 1
	s_barrier
; #define PG8_STAGE(bufoff, gbase, voff) do { _Pragma("unroll") for (int _i = 0; _i < 2; ++_i) \
;         __builtin_amdgcn_global_load_lds((const unsigned*)((const char*)(gbase) + (voff)[_i]), (LAS unsigned*)(lds + (bufoff) + ldsw + _i * 8192), 16, 0, 0); } while (0)
; #define PG8_LDA(dst, b, h) do { _Pragma("unroll") for (int m = 0; m < 4; ++m) _Pragma("unroll") for (int k = 0; k < 2; ++k) dst[m][k] = *(const LAS bf16x8*)(lds + PG8_SA(b, h) + aoff + m * 2048 + k * 1024); } while (0)
; #define PG8_MMA(ai, bj, At, Bt) do { __builtin_amdgcn_s_setprio(1); _Pragma("unroll") for (int m = 0; m < 4; ++m) _Pragma("unroll") for (int n = 0; n < 2; ++n) _Pragma("unroll") for (int k = 0; k < 2; ++k) \
;         acc[ai][bj][m][n] = __builtin_amdgcn_mfma_f32_16x16x32_bf16(Bt[n][k], At[m][k], acc[ai][bj][m][n], 0, 0, 0); __builtin_amdgcn_s_setprio(0); } while (0)
; #define PG8_WAIT_V(n) asm volatile("s_waitcnt vmcnt(" #n ")" ::: "memory")
; #define PG8_WAIT_L(n) asm volatile("s_waitcnt lgkmcnt(" #n ")" ::: "memory")
; #define PG8_BAR __builtin_amdgcn_s_barrier()
; #define PG8_SCHED __builtin_amdgcn_sched_barrier(0)
; template <class Epi, class Sched, bool ATILE = false>
; __device__ __forceinline__ void gemm_phase(LAS unsigned char* lds, const Gemm g, const Sched& S, const Epi& E) {
;     ...
;             PG8_BAR; PG8_WAIT_L(0); PG8_MMA(0, 1, At, B1); PG8_BAR;
;             PG8_LDA(At, 1, 1); PG8_STAGE(PG8_SA(1, 0), a3, voffA);
;             PG8_BAR; PG8_WAIT_L(0); PG8_MMA(1, 0, At, B0); PG8_BAR; PG8_SCHED;
;             PG8_STAGE(PG8_SB(1, 1), b3 + hstepB, voffB);
;             PG8_WAIT_V(6); PG8_BAR; PG8_MMA(1, 1, At, B1); PG8_BAR;
;         }
	s_waitcnt lgkmcnt(0)
	v_mfma_f32_16x16x32_bf16 v[124:127], v[224:227], v[192:195], v[124:127]
	v_mfma_f32_16x16x32_bf16 v[120:123], v[232:235], v[192:195], v[120:123]
	v_mfma_f32_16x16x32_bf16 v[108:111], v[224:227], v[200:203], v[108:111]
	v_mfma_f32_16x16x32_bf16 v[104:107], v[232:235], v[200:203], v[104:107]
	v_mfma_f32_16x16x32_bf16 v[92:95], v[224:227], v[208:211], v[92:95]
	v_mfma_f32_16x16x32_bf16 v[88:91], v[232:235], v[208:211], v[88:91]
	v_mfma_f32_16x16x32_bf16 v[76:79], v[224:227], v[216:219], v[76:79]
	v_mfma_f32_16x16x32_bf16 v[72:75], v[232:235], v[216:219], v[72:75]
	v_mfma_f32_16x16x32_bf16 v[124:127], v[228:231], v[196:199], v[124:127]
	v_mfma_f32_16x16x32_bf16 v[120:123], v[236:239], v[196:199], v[120:123]
	v_mfma_f32_16x16x32_bf16 v[108:111], v[228:231], v[204:207], v[108:111]
	v_mfma_f32_16x16x32_bf16 v[104:107], v[236:239], v[204:207], v[104:107]
	v_mfma_f32_16x16x32_bf16 v[92:95], v[228:231], v[212:215], v[92:95]
	v_mfma_f32_16x16x32_bf16 v[88:91], v[236:239], v[212:215], v[88:91]
	v_mfma_f32_16x16x32_bf16 v[76:79], v[228:231], v[220:223], v[76:79]
	v_mfma_f32_16x16x32_bf16 v[72:75], v[236:239], v[220:223], v[72:75]
	s_barrier
	s_setprio 0
	s_mov_b32 m0, s4
	ds_read_b128 v[192:195], v167 offset:49152
	ds_read_b128 v[196:199], v167 offset:50176
	ds_read_b128 v[200:203], v167 offset:51200
	ds_read_b128 v[204:207], v167 offset:52224
	ds_read_b128 v[208:211], v167 offset:53248
	ds_read_b128 v[212:215], v167 offset:54272
	ds_read_b128 v[216:219], v167 offset:55296
	ds_read_b128 v[220:223], v167 offset:56320
	global_load_lds_dwordx4 v136, s[100:101]
	s_mov_b32 m0, s5
	s_nop 0
	global_load_lds_dwordx4 v140, s[100:101]
	s_setprio 1
	s_barrier
	s_waitcnt lgkmcnt(0)
	v_mfma_f32_16x16x32_bf16 v[68:71], v[56:59], v[192:195], v[68:71]
	v_mfma_f32_16x16x32_bf16 v[64:67], v[178:181], v[192:195], v[64:67]
	v_mfma_f32_16x16x32_bf16 v[52:55], v[56:59], v[200:203], v[52:55]
	v_mfma_f32_16x16x32_bf16 v[48:51], v[178:181], v[200:203], v[48:51]
	v_mfma_f32_16x16x32_bf16 v[28:31], v[56:59], v[208:211], v[28:31]
	v_mfma_f32_16x16x32_bf16 v[24:27], v[178:181], v[208:211], v[24:27]
	v_mfma_f32_16x16x32_bf16 v[12:15], v[56:59], v[216:219], v[12:15]
	v_mfma_f32_16x16x32_bf16 v[8:11], v[178:181], v[216:219], v[8:11]
	v_mfma_f32_16x16x32_bf16 v[68:71], v[60:63], v[196:199], v[68:71]
	v_mfma_f32_16x16x32_bf16 v[64:67], v[182:185], v[196:199], v[64:67]
	v_mfma_f32_16x16x32_bf16 v[52:55], v[60:63], v[204:207], v[52:55]
	v_mfma_f32_16x16x32_bf16 v[48:51], v[182:185], v[204:207], v[48:51]
	v_mfma_f32_16x16x32_bf16 v[28:31], v[60:63], v[212:215], v[28:31]
	v_mfma_f32_16x16x32_bf16 v[24:27], v[182:185], v[212:215], v[24:27]
	v_mfma_f32_16x16x32_bf16 v[12:15], v[60:63], v[220:223], v[12:15]
	v_mfma_f32_16x16x32_bf16 v[8:11], v[182:185], v[220:223], v[8:11]
	s_barrier
	s_setprio 0
	s_add_u32 s84, s84, 0x80080
	s_addc_u32 s85, s85, 0
	s_add_i32 s73, s86, s31
	s_mov_b32 m0, s73
	s_nop 0
	global_load_lds_dwordx4 v138, s[84:85]
	s_add_i32 m0, s73, 0x2000
	s_nop 0
	global_load_lds_dwordx4 v142, s[84:85]
	s_waitcnt vmcnt(6)
	s_setprio 1
	s_barrier
	v_mfma_f32_16x16x32_bf16 v[32:35], v[224:227], v[192:195], v[32:35]
	v_mfma_f32_16x16x32_bf16 v[60:63], v[228:231], v[196:199], v[32:35]
	v_mfma_f32_16x16x32_bf16 v[32:35], v[232:235], v[192:195], v[36:39]
	v_mfma_f32_16x16x32_bf16 v[56:59], v[236:239], v[196:199], v[32:35]
	v_mfma_f32_16x16x32_bf16 v[32:35], v[224:227], v[200:203], v[44:47]
	v_mfma_f32_16x16x32_bf16 v[44:47], v[228:231], v[204:207], v[32:35]
	v_mfma_f32_16x16x32_bf16 v[32:35], v[232:235], v[200:203], v[40:43]
	v_mfma_f32_16x16x32_bf16 v[20:23], v[224:227], v[208:211], v[20:23]
	v_mfma_f32_16x16x32_bf16 v[16:19], v[232:235], v[208:211], v[16:19]
	v_mfma_f32_16x16x32_bf16 v[4:7], v[224:227], v[216:219], v[4:7]
	v_mfma_f32_16x16x32_bf16 v[0:3], v[232:235], v[216:219], v[0:3]
	v_mfma_f32_16x16x32_bf16 v[40:43], v[236:239], v[204:207], v[32:35]
	v_mfma_f32_16x16x32_bf16 v[20:23], v[228:231], v[212:215], v[20:23]
	v_mfma_f32_16x16x32_bf16 v[16:19], v[236:239], v[212:215], v[16:19]
	v_mfma_f32_16x16x32_bf16 v[4:7], v[228:231], v[220:223], v[4:7]
	v_mfma_f32_16x16x32_bf16 v[0:3], v[236:239], v[220:223], v[0:3]
	s_barrier
	s_setprio 0
	s_add_u32 s12, s12, 0x100
	s_addc_u32 s13, s13, 0
	s_add_u32 s62, s62, 0x100
	s_addc_u32 s63, s63, 0
	s_cmp_ge_i32 s88, s1
	s_mov_b32 s73, s88
	s_cbranch_scc0 .LBB0_895
	s_branch .LBB0_897

; #define PG8_STAGE(bufoff, gbase, voff) do { _Pragma("unroll") for (int _i = 0; _i < 2; ++_i) \
;         __builtin_amdgcn_global_load_lds((const unsigned*)((const char*)(gbase) + (voff)[_i]), (LAS unsigned*)(lds + (bufoff) + ldsw + _i * 8192), 16, 0, 0); } while (0)
; #define PG8_LDA(dst, b, h) do { _Pragma("unroll") for (int m = 0; m < 4; ++m) _Pragma("unroll") for (int k = 0; k < 2; ++k) dst[m][k] = *(const LAS bf16x8*)(lds + PG8_SA(b, h) + aoff + m * 2048 + k * 1024); } while (0)
; #define PG8_LDB(dst, b, h) do { _Pragma("unroll") for (int n = 0; n < 2; ++n) _Pragma("unroll") for (int k = 0; k < 2; ++k) dst[n][k] = *(const LAS bf16x8*)(lds + PG8_SB(b, h) + boff + n * 2048 + k * 1024); } while (0)
; #define PG8_MMA(ai, bj, At, Bt) do { __builtin_amdgcn_s_setprio(1); _Pragma("unroll") for (int m = 0; m < 4; ++m) _Pragma("unroll") for (int n = 0; n < 2; ++n) _Pragma("unroll") for (int k = 0; k < 2; ++k) \
;         acc[ai][bj][m][n] = __builtin_amdgcn_mfma_f32_16x16x32_bf16(Bt[n][k], At[m][k], acc[ai][bj][m][n], 0, 0, 0); __builtin_amdgcn_s_setprio(0); } while (0)
; #define PG8_WAIT_V(n) asm volatile("s_waitcnt vmcnt(" #n ")" ::: "memory")
; #define PG8_WAIT_L(n) asm volatile("s_waitcnt lgkmcnt(" #n ")" ::: "memory")
; template <class Epi, class Sched, bool ATILE = false>
; __device__ __forceinline__ void gemm_phase(LAS unsigned char* lds, const Gemm g, const Sched& S, const Epi& E) {
;     ...
;         for (int t = 0; t < nt; t += 2) {
;             const bool last = (t == nt - 2);
;             const char* a1 = cA + (size_t)(t + 1) * kstepA;
;             const char* a2 = last ? nA : cA + (size_t)(t + 2) * kstepA; const char* b2 = last ? nB : cB + (size_t)(t + 2) * kstep;
;             const char* a3 = a2 + kstepA; const char* b3 = b2 + kstep;
;             PG8_LDB(B0, 0, 0); PG8_SCHED; PG8_LDA(At, 0, 0); PG8_STAGE(PG8_SA(1, 1), a1 + hstepA, voffA);
;             PG8_WAIT_L(8); PG8_BAR; PG8_WAIT_L(0); PG8_MMA(0, 0, At, B0); PG8_BAR; PG8_SCHED;
;             PG8_LDB(B1, 0, 1); PG8_STAGE(PG8_SB(0, 0), b2, voffB);
;             PG8_BAR; PG8_WAIT_L(0); PG8_MMA(0, 1, At, B1); PG8_BAR;
;             PG8_LDA(At, 0, 1); PG8_STAGE(PG8_SA(0, 0), a2, voffA);
;             PG8_BAR; PG8_WAIT_L(0); PG8_MMA(1, 0, At, B0); PG8_BAR; PG8_SCHED;
;             PG8_STAGE(PG8_SB(0, 1), b2 + hstepB, voffB);
;             PG8_WAIT_V(6); PG8_BAR; PG8_MMA(1, 1, At, B1); PG8_BAR;
.LBB0_1298:
	ds_read_b128 v[82:85], v79
	ds_read_b128 v[86:89], v79 offset:1024
	ds_read_b128 v[90:93], v79 offset:2048
	ds_read_b128 v[94:97], v79 offset:3072
	s_add_i32 s60, s20, 2
	s_add_u32 s18, s16, 0x100
	s_addc_u32 s19, s17, 0
	s_cmp_eq_u32 s57, s20
	s_cselect_b32 s20, s56, s58
	s_cselect_b32 s23, s9, s19
	s_cselect_b32 s22, s8, s18
	s_cselect_b32 s21, s55, s59
	s_mov_b32 m0, s38
	v_lshl_add_u64 v[130:131], s[16:17], 0, v[74:75]
	ds_read_b128 v[98:101], v80
	ds_read_b128 v[102:105], v80 offset:1024
	ds_read_b128 v[106:109], v80 offset:2048
	ds_read_b128 v[110:113], v80 offset:3072
	ds_read_b128 v[114:117], v80 offset:4096
	ds_read_b128 v[118:121], v80 offset:5120
	ds_read_b128 v[122:125], v80 offset:6144
	ds_read_b128 v[126:129], v80 offset:7168
	global_load_lds_dwordx4 v[130:131], off
	v_lshl_add_u64 v[130:131], s[16:17], 0, v[76:77]
	s_mov_b32 m0, s39
	s_nop 0
	global_load_lds_dwordx4 v[130:131], off
	s_waitcnt lgkmcnt(8)
	s_setprio 1
	s_barrier
	s_waitcnt lgkmcnt(0)
	v_mfma_f32_16x16x32_bf16 v[60:63], v[82:85], v[98:101], v[60:63]
	v_mfma_f32_16x16x32_bf16 v[56:59], v[90:93], v[98:101], v[56:59]
	v_mfma_f32_16x16x32_bf16 v[52:55], v[82:85], v[106:109], v[52:55]
	v_mfma_f32_16x16x32_bf16 v[48:51], v[90:93], v[106:109], v[48:51]
	v_mfma_f32_16x16x32_bf16 v[44:47], v[82:85], v[114:117], v[44:47]
	v_mfma_f32_16x16x32_bf16 v[40:43], v[90:93], v[114:117], v[40:43]
	v_mfma_f32_16x16x32_bf16 v[36:39], v[82:85], v[122:125], v[36:39]
	v_mfma_f32_16x16x32_bf16 v[32:35], v[90:93], v[122:125], v[32:35]
	v_mfma_f32_16x16x32_bf16 v[60:63], v[86:89], v[102:105], v[60:63]
	v_mfma_f32_16x16x32_bf16 v[56:59], v[94:97], v[102:105], v[56:59]
	v_mfma_f32_16x16x32_bf16 v[52:55], v[86:89], v[110:113], v[52:55]
	v_mfma_f32_16x16x32_bf16 v[48:51], v[94:97], v[110:113], v[48:51]
	v_mfma_f32_16x16x32_bf16 v[44:47], v[86:89], v[118:121], v[44:47]
	v_mfma_f32_16x16x32_bf16 v[40:43], v[94:97], v[118:121], v[40:43]
	v_mfma_f32_16x16x32_bf16 v[36:39], v[86:89], v[126:129], v[36:39]
	v_mfma_f32_16x16x32_bf16 v[32:35], v[94:97], v[126:129], v[32:35]
	s_barrier
	s_setprio 0
	s_mov_b32 m0, s40
	v_lshl_add_u64 v[130:131], s[20:21], 0, v[68:69]
	global_load_lds_dwordx4 v[130:131], off
	v_lshl_add_u64 v[132:133], s[20:21], 0, v[64:65]
	s_mov_b32 m0, s41
	s_nop 0
	global_load_lds_dwordx4 v[132:133], off
	s_barrier
	s_waitcnt lgkmcnt(0)
	s_setprio 1
	s_setprio 0
	s_mov_b32 m0, s25
	v_lshl_add_u64 v[134:135], s[22:23], 0, v[70:71]
	s_barrier
	ds_read_b128 v[98:101], v80 offset:16384
	ds_read_b128 v[102:105], v80 offset:17408
	ds_read_b128 v[106:109], v80 offset:18432
	ds_read_b128 v[110:113], v80 offset:19456
	ds_read_b128 v[114:117], v80 offset:20480
	ds_read_b128 v[118:121], v80 offset:21504
	ds_read_b128 v[122:125], v80 offset:22528
	ds_read_b128 v[126:129], v80 offset:23552
	global_load_lds_dwordx4 v[134:135], off
	v_lshl_add_u64 v[136:137], s[22:23], 0, v[66:67]
	s_mov_b32 m0, s26
	s_nop 0
	global_load_lds_dwordx4 v[136:137], off
	s_setprio 1
	s_barrier
	s_waitcnt lgkmcnt(0)
	v_mfma_f32_16x16x32_bf16 v[28:31], v[82:85], v[98:101], v[28:31]
	v_mfma_f32_16x16x32_bf16 v[24:27], v[90:93], v[98:101], v[24:27]
	v_mfma_f32_16x16x32_bf16 v[20:23], v[82:85], v[106:109], v[20:23]
	v_mfma_f32_16x16x32_bf16 v[16:19], v[90:93], v[106:109], v[16:19]
	v_mfma_f32_16x16x32_bf16 v[12:15], v[82:85], v[114:117], v[12:15]
	v_mfma_f32_16x16x32_bf16 v[8:11], v[90:93], v[114:117], v[8:11]
	v_mfma_f32_16x16x32_bf16 v[4:7], v[82:85], v[122:125], v[4:7]
	v_mfma_f32_16x16x32_bf16 v[0:3], v[90:93], v[122:125], v[0:3]
	v_mfma_f32_16x16x32_bf16 v[28:31], v[86:89], v[102:105], v[28:31]
	v_mfma_f32_16x16x32_bf16 v[24:27], v[94:97], v[102:105], v[24:27]
	v_mfma_f32_16x16x32_bf16 v[20:23], v[86:89], v[110:113], v[20:23]
	v_mfma_f32_16x16x32_bf16 v[16:19], v[94:97], v[110:113], v[16:19]
	v_mfma_f32_16x16x32_bf16 v[12:15], v[86:89], v[118:121], v[12:15]
	v_mfma_f32_16x16x32_bf16 v[8:11], v[94:97], v[118:121], v[8:11]
	v_mfma_f32_16x16x32_bf16 v[4:7], v[86:89], v[126:129], v[4:7]
	v_mfma_f32_16x16x32_bf16 v[0:3], v[94:97], v[126:129], v[0:3]
	s_barrier
	s_setprio 0
	s_add_u32 s16, s20, 0x10000
	s_addc_u32 s17, s21, 0
	s_mov_b32 m0, s27
	s_nop 0
	global_load_lds_dwordx4 v68, s[16:17]
	s_mov_b32 m0, s28
	s_nop 0
	global_load_lds_dwordx4 v64, s[16:17]
	s_waitcnt vmcnt(6)
	s_barrier
; #define PG8_STAGE(bufoff, gbase, voff) do { _Pragma("unroll") for (int _i = 0; _i < 2; ++_i) \
;         __builtin_amdgcn_global_load_lds((const unsigned*)((const char*)(gbase) + (voff)[_i]), (LAS unsigned*)(lds + (bufoff) + ldsw + _i * 8192), 16, 0, 0); } while (0)
; #define PG8_LDA(dst, b, h) do { _Pragma("unroll") for (int m = 0; m < 4; ++m) _Pragma("unroll") for (int k = 0; k < 2; ++k) dst[m][k] = *(const LAS bf16x8*)(lds + PG8_SA(b, h) + aoff + m * 2048 + k * 1024); } while (0)
; #define PG8_LDB(dst, b, h) do { _Pragma("unroll") for (int n = 0; n < 2; ++n) _Pragma("unroll") for (int k = 0; k < 2; ++k) dst[n][k] = *(const LAS bf16x8*)(lds + PG8_SB(b, h) + boff + n * 2048 + k * 1024); } while (0)
; #define PG8_MMA(ai, bj, At, Bt) do { __builtin_amdgcn_s_setprio(1); _Pragma("unroll") for (int m = 0; m < 4; ++m) _Pragma("unroll") for (int n = 0; n < 2; ++n) _Pragma("unroll") for (int k = 0; k < 2; ++k) \
;         acc[ai][bj][m][n] = __builtin_amdgcn_mfma_f32_16x16x32_bf16(Bt[n][k], At[m][k], acc[ai][bj][m][n], 0, 0, 0); __builtin_amdgcn_s_setprio(0); } while (0)
; #define PG8_WAIT_V(n) asm volatile("s_waitcnt vmcnt(" #n ")" ::: "memory")
; #define PG8_WAIT_L(n) asm volatile("s_waitcnt lgkmcnt(" #n ")" ::: "memory")
; #define PG8_BAR __builtin_amdgcn_s_barrier()
; #define PG8_SCHED __builtin_amdgcn_sched_barrier(0)
; template <class Epi, class Sched, bool ATILE = false>
; __device__ __forceinline__ void gemm_phase(LAS unsigned char* lds, const Gemm g, const Sched& S, const Epi& E) {
;     ...
;             PG8_WAIT_V(6); PG8_BAR; PG8_MMA(1, 1, At, B1); PG8_BAR;
;             PG8_LDB(B0, 1, 0); PG8_SCHED; PG8_LDA(At, 1, 0); PG8_STAGE(PG8_SA(0, 1), a2 + hstepA, voffA);
;             PG8_WAIT_L(8); PG8_BAR; PG8_WAIT_L(0); PG8_MMA(0, 0, At, B0); PG8_BAR; PG8_SCHED;
;             PG8_LDB(B1, 1, 1); PG8_STAGE(PG8_SB(1, 0), b3, voffB);
;             PG8_BAR; PG8_WAIT_L(0); PG8_MMA(0, 1, At, B1); PG8_BAR;
;             PG8_LDA(At, 1, 1); PG8_STAGE(PG8_SA(1, 0), a3, voffA);
;             PG8_BAR; PG8_WAIT_L(0); PG8_MMA(1, 0, At, B0); PG8_BAR; PG8_SCHED;
;             PG8_STAGE(PG8_SB(1, 1), b3 + hstepB, voffB);
;             PG8_WAIT_V(6); PG8_BAR; PG8_MMA(1, 1, At, B1); PG8_BAR;
;         }
	s_setprio 1
	s_setprio 0
	s_barrier
	ds_read_b128 v[82:85], v81
	ds_read_b128 v[86:89], v81 offset:1024
	ds_read_b128 v[90:93], v81 offset:2048
	ds_read_b128 v[94:97], v81 offset:3072
	s_add_u32 s16, s22, 0x18000
	s_addc_u32 s17, s23, 0
	s_mov_b32 m0, s29
	ds_read_b128 v[98:101], v80 offset:32768
	ds_read_b128 v[102:105], v80 offset:33792
	ds_read_b128 v[106:109], v80 offset:34816
	ds_read_b128 v[110:113], v80 offset:35840
	ds_read_b128 v[114:117], v80 offset:36864
	ds_read_b128 v[118:121], v80 offset:37888
	ds_read_b128 v[122:125], v80 offset:38912
	ds_read_b128 v[126:129], v80 offset:39936
	global_load_lds_dwordx4 v70, s[16:17]
	s_mov_b32 m0, s30
	s_nop 0
	global_load_lds_dwordx4 v66, s[16:17]
	s_waitcnt lgkmcnt(8)
	s_setprio 1
	s_barrier
	s_waitcnt lgkmcnt(0)
	v_mfma_f32_16x16x32_bf16 v[60:63], v[82:85], v[98:101], v[60:63]
	v_mfma_f32_16x16x32_bf16 v[56:59], v[90:93], v[98:101], v[56:59]
	v_mfma_f32_16x16x32_bf16 v[52:55], v[82:85], v[106:109], v[52:55]
	v_mfma_f32_16x16x32_bf16 v[48:51], v[90:93], v[106:109], v[48:51]
	v_mfma_f32_16x16x32_bf16 v[44:47], v[82:85], v[114:117], v[44:47]
	v_mfma_f32_16x16x32_bf16 v[40:43], v[90:93], v[114:117], v[40:43]
	v_mfma_f32_16x16x32_bf16 v[36:39], v[82:85], v[122:125], v[36:39]
	v_mfma_f32_16x16x32_bf16 v[32:35], v[90:93], v[122:125], v[32:35]
	v_mfma_f32_16x16x32_bf16 v[60:63], v[86:89], v[102:105], v[60:63]
	v_mfma_f32_16x16x32_bf16 v[56:59], v[94:97], v[102:105], v[56:59]
	v_mfma_f32_16x16x32_bf16 v[52:55], v[86:89], v[110:113], v[52:55]
	v_mfma_f32_16x16x32_bf16 v[48:51], v[94:97], v[110:113], v[48:51]
	v_mfma_f32_16x16x32_bf16 v[44:47], v[86:89], v[118:121], v[44:47]
	v_mfma_f32_16x16x32_bf16 v[40:43], v[94:97], v[118:121], v[40:43]
	v_mfma_f32_16x16x32_bf16 v[36:39], v[86:89], v[126:129], v[36:39]
	v_mfma_f32_16x16x32_bf16 v[32:35], v[94:97], v[126:129], v[32:35]
	s_barrier
	s_setprio 0
	s_mov_b32 m0, s43
	v_lshl_add_u64 v[98:99], v[130:131], 0, s[6:7]
	global_load_lds_dwordx4 v[98:99], off
	v_lshl_add_u64 v[98:99], v[132:133], 0, s[6:7]
	s_mov_b32 m0, s44
	s_nop 0
	global_load_lds_dwordx4 v[98:99], off
	s_barrier
	s_waitcnt lgkmcnt(0)
	s_setprio 1
	s_setprio 0
	s_mov_b32 m0, s34
	v_lshl_add_u64 v[130:131], v[134:135], 0, s[6:7]
	s_barrier
	ds_read_b128 v[98:101], v80 offset:49152
	ds_read_b128 v[102:105], v80 offset:50176
	ds_read_b128 v[106:109], v80 offset:51200
	ds_read_b128 v[110:113], v80 offset:52224
	ds_read_b128 v[114:117], v80 offset:53248
	ds_read_b128 v[118:121], v80 offset:54272
	ds_read_b128 v[122:125], v80 offset:55296
	ds_read_b128 v[126:129], v80 offset:56320
	global_load_lds_dwordx4 v[130:131], off
	v_lshl_add_u64 v[130:131], v[136:137], 0, s[6:7]
	s_mov_b32 m0, s35
	s_nop 0
	global_load_lds_dwordx4 v[130:131], off
	s_setprio 1
	s_barrier
	s_waitcnt lgkmcnt(0)
	v_mfma_f32_16x16x32_bf16 v[28:31], v[82:85], v[98:101], v[28:31]
	v_mfma_f32_16x16x32_bf16 v[24:27], v[90:93], v[98:101], v[24:27]
	v_mfma_f32_16x16x32_bf16 v[20:23], v[82:85], v[106:109], v[20:23]
	v_mfma_f32_16x16x32_bf16 v[16:19], v[90:93], v[106:109], v[16:19]
	v_mfma_f32_16x16x32_bf16 v[12:15], v[82:85], v[114:117], v[12:15]
	v_mfma_f32_16x16x32_bf16 v[8:11], v[90:93], v[114:117], v[8:11]
	v_mfma_f32_16x16x32_bf16 v[4:7], v[82:85], v[122:125], v[4:7]
	v_mfma_f32_16x16x32_bf16 v[0:3], v[90:93], v[122:125], v[0:3]
	v_mfma_f32_16x16x32_bf16 v[28:31], v[86:89], v[102:105], v[28:31]
	v_mfma_f32_16x16x32_bf16 v[24:27], v[94:97], v[102:105], v[24:27]
	v_mfma_f32_16x16x32_bf16 v[20:23], v[86:89], v[110:113], v[20:23]
	v_mfma_f32_16x16x32_bf16 v[16:19], v[94:97], v[110:113], v[16:19]
	v_mfma_f32_16x16x32_bf16 v[12:15], v[86:89], v[118:121], v[12:15]
	v_mfma_f32_16x16x32_bf16 v[8:11], v[94:97], v[118:121], v[8:11]
	v_mfma_f32_16x16x32_bf16 v[4:7], v[86:89], v[126:129], v[4:7]
	v_mfma_f32_16x16x32_bf16 v[0:3], v[94:97], v[126:129], v[0:3]
	s_barrier
	s_setprio 0
	s_add_u32 s16, s20, 0x10080
	s_addc_u32 s17, s21, 0
	s_mov_b32 m0, s36
	s_nop 0
	global_load_lds_dwordx4 v68, s[16:17]
	s_mov_b32 m0, s37
	s_nop 0
	global_load_lds_dwordx4 v64, s[16:17]
	s_waitcnt vmcnt(6)
	s_barrier
	s_setprio 1
	s_setprio 0
	s_add_u32 s58, s58, 0x100
	s_addc_u32 s59, s59, 0
	s_cmp_ge_i32 s60, s54
	s_mov_b64 s[16:17], s[18:19]
	s_mov_b32 s20, s60
	s_barrier
	s_cbranch_scc0 .LBB0_1298
	s_branch .LBB0_1293

; #define PG8_STAGE(bufoff, gbase, voff) do { _Pragma("unroll") for (int _i = 0; _i < 2; ++_i) \
;         __builtin_amdgcn_global_load_lds((const unsigned*)((const char*)(gbase) + (voff)[_i]), (LAS unsigned*)(lds + (bufoff) + ldsw + _i * 8192), 16, 0, 0); } while (0)
; #define PG8_LDA(dst, b, h) do { _Pragma("unroll") for (int m = 0; m < 4; ++m) _Pragma("unroll") for (int k = 0; k < 2; ++k) dst[m][k] = *(const LAS bf16x8*)(lds + PG8_SA(b, h) + aoff + m * 2048 + k * 1024); } while (0)
; #define PG8_LDB(dst, b, h) do { _Pragma("unroll") for (int n = 0; n < 2; ++n) _Pragma("unroll") for (int k = 0; k < 2; ++k) dst[n][k] = *(const LAS bf16x8*)(lds + PG8_SB(b, h) + boff + n * 2048 + k * 1024); } while (0)
; #define PG8_MMA(ai, bj, At, Bt) do { __builtin_amdgcn_s_setprio(1); _Pragma("unroll") for (int m = 0; m < 4; ++m) _Pragma("unroll") for (int n = 0; n < 2; ++n) _Pragma("unroll") for (int k = 0; k < 2; ++k) \
;         acc[ai][bj][m][n] = __builtin_amdgcn_mfma_f32_16x16x32_bf16(Bt[n][k], At[m][k], acc[ai][bj][m][n], 0, 0, 0); __builtin_amdgcn_s_setprio(0); } while (0)
; #define PG8_WAIT_V(n) asm volatile("s_waitcnt vmcnt(" #n ")" ::: "memory")
; #define PG8_WAIT_L(n) asm volatile("s_waitcnt lgkmcnt(" #n ")" ::: "memory")
; template <class Epi, class Sched, bool ATILE = false>
; __device__ __forceinline__ void gemm_phase(LAS unsigned char* lds, const Gemm g, const Sched& S, const Epi& E) {
;     ...
;         for (int t = 0; t < nt; t += 2) {
;             const bool last = (t == nt - 2);
;             const char* a1 = cA + (size_t)(t + 1) * kstepA;
;             const char* a2 = last ? nA : cA + (size_t)(t + 2) * kstepA; const char* b2 = last ? nB : cB + (size_t)(t + 2) * kstep;
;             const char* a3 = a2 + kstepA; const char* b3 = b2 + kstep;
;             PG8_LDB(B0, 0, 0); PG8_SCHED; PG8_LDA(At, 0, 0); PG8_STAGE(PG8_SA(1, 1), a1 + hstepA, voffA);
;             PG8_WAIT_L(8); PG8_BAR; PG8_WAIT_L(0); PG8_MMA(0, 0, At, B0); PG8_BAR; PG8_SCHED;
;             PG8_LDB(B1, 0, 1); PG8_STAGE(PG8_SB(0, 0), b2, voffB);
;             PG8_BAR; PG8_WAIT_L(0); PG8_MMA(0, 1, At, B1); PG8_BAR;
;             PG8_LDA(At, 0, 1); PG8_STAGE(PG8_SA(0, 0), a2, voffA);
;             PG8_BAR; PG8_WAIT_L(0); PG8_MMA(1, 0, At, B0); PG8_BAR; PG8_SCHED;
;             PG8_STAGE(PG8_SB(0, 1), b2 + hstepB, voffB);
;             PG8_WAIT_V(6); PG8_BAR; PG8_MMA(1, 1, At, B1); PG8_BAR;
.LBB0_1426:
	ds_read_b128 v[162:165], v147
	ds_read_b128 v[166:169], v147 offset:1024
	ds_read_b128 v[170:173], v147 offset:2048
	ds_read_b128 v[174:177], v147 offset:3072
	s_add_i32 s58, s18, 2
	s_add_u32 s16, s12, 0x100
	s_addc_u32 s17, s13, 0
	s_cmp_eq_u32 s55, s18
	s_cselect_b32 s18, s10, s56
	s_cselect_b32 s21, s7, s17
	s_cselect_b32 s20, s6, s16
	s_cselect_b32 s19, s11, s57
	s_mov_b32 m0, s30
	v_lshl_add_u64 v[144:145], s[12:13], 0, v[140:141]
	ds_read_b128 v[178:181], v148
	ds_read_b128 v[182:185], v148 offset:1024
	ds_read_b128 v[186:189], v148 offset:2048
	ds_read_b128 v[190:193], v148 offset:3072
	ds_read_b128 v[194:197], v148 offset:4096
	ds_read_b128 v[198:201], v148 offset:5120
	ds_read_b128 v[202:205], v148 offset:6144
	ds_read_b128 v[206:209], v148 offset:7168
	global_load_lds_dwordx4 v[144:145], off
	v_lshl_add_u64 v[144:145], s[12:13], 0, v[142:143]
	s_mov_b32 m0, s31
	s_nop 0
	global_load_lds_dwordx4 v[144:145], off
	s_waitcnt lgkmcnt(8)
	s_setprio 1
	s_barrier
	s_waitcnt lgkmcnt(0)
	v_mfma_f32_16x16x32_bf16 v[124:127], v[162:165], v[178:181], v[124:127]
	v_mfma_f32_16x16x32_bf16 v[120:123], v[170:173], v[178:181], v[120:123]
	v_mfma_f32_16x16x32_bf16 v[108:111], v[162:165], v[186:189], v[108:111]
	v_mfma_f32_16x16x32_bf16 v[104:107], v[170:173], v[186:189], v[104:107]
	v_mfma_f32_16x16x32_bf16 v[92:95], v[162:165], v[194:197], v[92:95]
	v_mfma_f32_16x16x32_bf16 v[88:91], v[170:173], v[194:197], v[88:91]
	v_mfma_f32_16x16x32_bf16 v[76:79], v[162:165], v[202:205], v[76:79]
	v_mfma_f32_16x16x32_bf16 v[72:75], v[170:173], v[202:205], v[72:75]
	v_mfma_f32_16x16x32_bf16 v[124:127], v[166:169], v[182:185], v[124:127]
	v_mfma_f32_16x16x32_bf16 v[120:123], v[174:177], v[182:185], v[120:123]
	v_mfma_f32_16x16x32_bf16 v[108:111], v[166:169], v[190:193], v[108:111]
	v_mfma_f32_16x16x32_bf16 v[104:107], v[174:177], v[190:193], v[104:107]
	v_mfma_f32_16x16x32_bf16 v[92:95], v[166:169], v[198:201], v[92:95]
	v_mfma_f32_16x16x32_bf16 v[88:91], v[174:177], v[198:201], v[88:91]
	v_mfma_f32_16x16x32_bf16 v[76:79], v[166:169], v[206:209], v[76:79]
	v_mfma_f32_16x16x32_bf16 v[72:75], v[174:177], v[206:209], v[72:75]
	s_barrier
	s_setprio 0
	s_mov_b32 m0, s33
	v_lshl_add_u64 v[144:145], s[18:19], 0, v[132:133]
	ds_read_b128 v[210:213], v149
	ds_read_b128 v[214:217], v149 offset:1024
	ds_read_b128 v[218:221], v149 offset:2048
	ds_read_b128 v[222:225], v149 offset:3072
	global_load_lds_dwordx4 v[144:145], off
	v_lshl_add_u64 v[226:227], s[18:19], 0, v[128:129]
	s_mov_b32 m0, s34
	s_nop 0
	global_load_lds_dwordx4 v[226:227], off
	s_setprio 1
	s_barrier
	s_waitcnt lgkmcnt(0)
	v_mfma_f32_16x16x32_bf16 v[116:119], v[210:213], v[178:181], v[116:119]
	v_mfma_f32_16x16x32_bf16 v[112:115], v[218:221], v[178:181], v[112:115]
	v_mfma_f32_16x16x32_bf16 v[100:103], v[210:213], v[186:189], v[100:103]
	v_mfma_f32_16x16x32_bf16 v[96:99], v[218:221], v[186:189], v[96:99]
	v_mfma_f32_16x16x32_bf16 v[84:87], v[210:213], v[194:197], v[84:87]
	v_mfma_f32_16x16x32_bf16 v[80:83], v[218:221], v[194:197], v[80:83]
	v_mfma_f32_16x16x32_bf16 v[68:71], v[210:213], v[202:205], v[68:71]
	v_mfma_f32_16x16x32_bf16 v[64:67], v[218:221], v[202:205], v[64:67]
	v_mfma_f32_16x16x32_bf16 v[116:119], v[214:217], v[182:185], v[116:119]
	v_mfma_f32_16x16x32_bf16 v[112:115], v[222:225], v[182:185], v[112:115]
	v_mfma_f32_16x16x32_bf16 v[100:103], v[214:217], v[190:193], v[100:103]
	v_mfma_f32_16x16x32_bf16 v[96:99], v[222:225], v[190:193], v[96:99]
	v_mfma_f32_16x16x32_bf16 v[84:87], v[214:217], v[198:201], v[84:87]
	v_mfma_f32_16x16x32_bf16 v[80:83], v[222:225], v[198:201], v[80:83]
	v_mfma_f32_16x16x32_bf16 v[68:71], v[214:217], v[206:209], v[68:71]
	v_mfma_f32_16x16x32_bf16 v[64:67], v[222:225], v[206:209], v[64:67]
	s_barrier
	s_setprio 0
	s_mov_b32 m0, s22
	v_lshl_add_u64 v[228:229], s[20:21], 0, v[134:135]
	ds_read_b128 v[178:181], v148 offset:16384
	ds_read_b128 v[182:185], v148 offset:17408
	ds_read_b128 v[186:189], v148 offset:18432
	ds_read_b128 v[190:193], v148 offset:19456
	ds_read_b128 v[194:197], v148 offset:20480
	ds_read_b128 v[198:201], v148 offset:21504
	ds_read_b128 v[202:205], v148 offset:22528
	ds_read_b128 v[206:209], v148 offset:23552
	global_load_lds_dwordx4 v[228:229], off
	v_lshl_add_u64 v[230:231], s[20:21], 0, v[130:131]
	s_mov_b32 m0, s23
	s_nop 0
	global_load_lds_dwordx4 v[230:231], off
	s_setprio 1
	s_barrier
	s_waitcnt lgkmcnt(0)
	v_mfma_f32_16x16x32_bf16 v[60:63], v[162:165], v[178:181], v[60:63]
	v_mfma_f32_16x16x32_bf16 v[56:59], v[170:173], v[178:181], v[56:59]
	v_mfma_f32_16x16x32_bf16 v[44:47], v[162:165], v[186:189], v[44:47]
	v_mfma_f32_16x16x32_bf16 v[40:43], v[170:173], v[186:189], v[40:43]
	v_mfma_f32_16x16x32_bf16 v[28:31], v[162:165], v[194:197], v[28:31]
	v_mfma_f32_16x16x32_bf16 v[24:27], v[170:173], v[194:197], v[24:27]
	v_mfma_f32_16x16x32_bf16 v[12:15], v[162:165], v[202:205], v[12:15]
	v_mfma_f32_16x16x32_bf16 v[8:11], v[170:173], v[202:205], v[8:11]
	v_mfma_f32_16x16x32_bf16 v[60:63], v[166:169], v[182:185], v[60:63]
	v_mfma_f32_16x16x32_bf16 v[56:59], v[174:177], v[182:185], v[56:59]
	v_mfma_f32_16x16x32_bf16 v[44:47], v[166:169], v[190:193], v[44:47]
	v_mfma_f32_16x16x32_bf16 v[40:43], v[174:177], v[190:193], v[40:43]
	v_mfma_f32_16x16x32_bf16 v[28:31], v[166:169], v[198:201], v[28:31]
	v_mfma_f32_16x16x32_bf16 v[24:27], v[174:177], v[198:201], v[24:27]
	v_mfma_f32_16x16x32_bf16 v[12:15], v[166:169], v[206:209], v[12:15]
	v_mfma_f32_16x16x32_bf16 v[8:11], v[174:177], v[206:209], v[8:11]
	s_barrier
	s_setprio 0
	s_add_u32 s12, s18, 0x18000
	s_addc_u32 s13, s19, 0
	s_mov_b32 m0, s35
	s_nop 0
	global_load_lds_dwordx4 v132, s[12:13]
	s_mov_b32 m0, s36
	s_nop 0
	global_load_lds_dwordx4 v128, s[12:13]
	s_waitcnt vmcnt(6)
	s_setprio 1
	s_barrier
; #define PG8_STAGE(bufoff, gbase, voff) do { _Pragma("unroll") for (int _i = 0; _i < 2; ++_i) \
;         __builtin_amdgcn_global_load_lds((const unsigned*)((const char*)(gbase) + (voff)[_i]), (LAS unsigned*)(lds + (bufoff) + ldsw + _i * 8192), 16, 0, 0); } while (0)
; #define PG8_LDA(dst, b, h) do { _Pragma("unroll") for (int m = 0; m < 4; ++m) _Pragma("unroll") for (int k = 0; k < 2; ++k) dst[m][k] = *(const LAS bf16x8*)(lds + PG8_SA(b, h) + aoff + m * 2048 + k * 1024); } while (0)
; #define PG8_LDB(dst, b, h) do { _Pragma("unroll") for (int n = 0; n < 2; ++n) _Pragma("unroll") for (int k = 0; k < 2; ++k) dst[n][k] = *(const LAS bf16x8*)(lds + PG8_SB(b, h) + boff + n * 2048 + k * 1024); } while (0)
; #define PG8_MMA(ai, bj, At, Bt) do { __builtin_amdgcn_s_setprio(1); _Pragma("unroll") for (int m = 0; m < 4; ++m) _Pragma("unroll") for (int n = 0; n < 2; ++n) _Pragma("unroll") for (int k = 0; k < 2; ++k) \
;         acc[ai][bj][m][n] = __builtin_amdgcn_mfma_f32_16x16x32_bf16(Bt[n][k], At[m][k], acc[ai][bj][m][n], 0, 0, 0); __builtin_amdgcn_s_setprio(0); } while (0)
; #define PG8_WAIT_V(n) asm volatile("s_waitcnt vmcnt(" #n ")" ::: "memory")
; #define PG8_WAIT_L(n) asm volatile("s_waitcnt lgkmcnt(" #n ")" ::: "memory")
; #define PG8_BAR __builtin_amdgcn_s_barrier()
; #define PG8_SCHED __builtin_amdgcn_sched_barrier(0)
; template <class Epi, class Sched, bool ATILE = false>
; __device__ __forceinline__ void gemm_phase(LAS unsigned char* lds, const Gemm g, const Sched& S, const Epi& E) {
;     ...
;             PG8_WAIT_V(6); PG8_BAR; PG8_MMA(1, 1, At, B1); PG8_BAR;
;             PG8_LDB(B0, 1, 0); PG8_SCHED; PG8_LDA(At, 1, 0); PG8_STAGE(PG8_SA(0, 1), a2 + hstepA, voffA);
;             PG8_WAIT_L(8); PG8_BAR; PG8_WAIT_L(0); PG8_MMA(0, 0, At, B0); PG8_BAR; PG8_SCHED;
;             PG8_LDB(B1, 1, 1); PG8_STAGE(PG8_SB(1, 0), b3, voffB);
;             PG8_BAR; PG8_WAIT_L(0); PG8_MMA(0, 1, At, B1); PG8_BAR;
	v_mfma_f32_16x16x32_bf16 v[52:55], v[210:213], v[178:181], v[52:55]
	v_mfma_f32_16x16x32_bf16 v[48:51], v[218:221], v[178:181], v[48:51]
	v_mfma_f32_16x16x32_bf16 v[36:39], v[210:213], v[186:189], v[36:39]
	v_mfma_f32_16x16x32_bf16 v[32:35], v[218:221], v[186:189], v[32:35]
	v_mfma_f32_16x16x32_bf16 v[20:23], v[210:213], v[194:197], v[20:23]
	v_mfma_f32_16x16x32_bf16 v[16:19], v[218:221], v[194:197], v[16:19]
	v_mfma_f32_16x16x32_bf16 v[4:7], v[210:213], v[202:205], v[4:7]
	v_mfma_f32_16x16x32_bf16 v[0:3], v[218:221], v[202:205], v[0:3]
	v_mfma_f32_16x16x32_bf16 v[52:55], v[214:217], v[182:185], v[52:55]
	v_mfma_f32_16x16x32_bf16 v[48:51], v[222:225], v[182:185], v[48:51]
	v_mfma_f32_16x16x32_bf16 v[36:39], v[214:217], v[190:193], v[36:39]
	v_mfma_f32_16x16x32_bf16 v[32:35], v[222:225], v[190:193], v[32:35]
	v_mfma_f32_16x16x32_bf16 v[20:23], v[214:217], v[198:201], v[20:23]
	v_mfma_f32_16x16x32_bf16 v[16:19], v[222:225], v[198:201], v[16:19]
	v_mfma_f32_16x16x32_bf16 v[4:7], v[214:217], v[206:209], v[4:7]
	v_mfma_f32_16x16x32_bf16 v[0:3], v[222:225], v[206:209], v[0:3]
	s_barrier
	s_setprio 0
	ds_read_b128 v[162:165], v150
	ds_read_b128 v[166:169], v150 offset:1024
	ds_read_b128 v[170:173], v150 offset:2048
	ds_read_b128 v[174:177], v150 offset:3072
	s_add_u32 s12, s20, 0x18000
	s_addc_u32 s13, s21, 0
	s_mov_b32 m0, s24
	ds_read_b128 v[178:181], v148 offset:32768
	ds_read_b128 v[182:185], v148 offset:33792
	ds_read_b128 v[186:189], v148 offset:34816
	ds_read_b128 v[190:193], v148 offset:35840
	ds_read_b128 v[194:197], v148 offset:36864
	ds_read_b128 v[198:201], v148 offset:37888
	ds_read_b128 v[202:205], v148 offset:38912
	ds_read_b128 v[206:209], v148 offset:39936
	global_load_lds_dwordx4 v134, s[12:13]
	s_mov_b32 m0, s25
	s_nop 0
	global_load_lds_dwordx4 v130, s[12:13]
	s_waitcnt lgkmcnt(8)
	s_setprio 1
	s_barrier
	s_waitcnt lgkmcnt(0)
	v_mfma_f32_16x16x32_bf16 v[124:127], v[162:165], v[178:181], v[124:127]
	v_mfma_f32_16x16x32_bf16 v[120:123], v[170:173], v[178:181], v[120:123]
	v_mfma_f32_16x16x32_bf16 v[108:111], v[162:165], v[186:189], v[108:111]
	v_mfma_f32_16x16x32_bf16 v[104:107], v[170:173], v[186:189], v[104:107]
	v_mfma_f32_16x16x32_bf16 v[92:95], v[162:165], v[194:197], v[92:95]
	v_mfma_f32_16x16x32_bf16 v[88:91], v[170:173], v[194:197], v[88:91]
	v_mfma_f32_16x16x32_bf16 v[76:79], v[162:165], v[202:205], v[76:79]
	v_mfma_f32_16x16x32_bf16 v[72:75], v[170:173], v[202:205], v[72:75]
	v_mfma_f32_16x16x32_bf16 v[124:127], v[166:169], v[182:185], v[124:127]
	v_mfma_f32_16x16x32_bf16 v[120:123], v[174:177], v[182:185], v[120:123]
	v_mfma_f32_16x16x32_bf16 v[108:111], v[166:169], v[190:193], v[108:111]
	v_mfma_f32_16x16x32_bf16 v[104:107], v[174:177], v[190:193], v[104:107]
	v_mfma_f32_16x16x32_bf16 v[92:95], v[166:169], v[198:201], v[92:95]
	v_mfma_f32_16x16x32_bf16 v[88:91], v[174:177], v[198:201], v[88:91]
	v_mfma_f32_16x16x32_bf16 v[76:79], v[166:169], v[206:209], v[76:79]
	v_mfma_f32_16x16x32_bf16 v[72:75], v[174:177], v[206:209], v[72:75]
	s_barrier
	s_setprio 0
	s_mov_b32 m0, s40
	v_lshl_add_u64 v[144:145], v[144:145], 0, s[0:1]
	ds_read_b128 v[210:213], v157
	ds_read_b128 v[214:217], v157 offset:1024
	ds_read_b128 v[218:221], v157 offset:2048
	ds_read_b128 v[222:225], v157 offset:3072
	global_load_lds_dwordx4 v[144:145], off
	v_lshl_add_u64 v[144:145], v[226:227], 0, s[0:1]
	s_mov_b32 m0, s41
	s_nop 0
	global_load_lds_dwordx4 v[144:145], off
	s_setprio 1
	s_barrier
; #define PG8_STAGE(bufoff, gbase, voff) do { _Pragma("unroll") for (int _i = 0; _i < 2; ++_i) \
;         __builtin_amdgcn_global_load_lds((const unsigned*)((const char*)(gbase) + (voff)[_i]), (LAS unsigned*)(lds + (bufoff) + ldsw + _i * 8192), 16, 0, 0); } while (0)
; #define PG8_LDA(dst, b, h) do { _Pragma("unroll") for (int m = 0; m < 4; ++m) _Pragma("unroll") for (int k = 0; k < 2; ++k) dst[m][k] = *(const LAS bf16x8*)(lds + PG8_SA(b, h) + aoff + m * 2048 + k * 1024); } while (0)
; #define PG8_MMA(ai, bj, At, Bt) do { __builtin_amdgcn_s_setprio(1); _Pragma("unroll") for (int m = 0; m < 4; ++m) _Pragma("unroll") for (int n = 0; n < 2; ++n) _Pragma("unroll") for (int k = 0; k < 2; ++k) \
;         acc[ai][bj][m][n] = __builtin_amdgcn_mfma_f32_16x16x32_bf16(Bt[n][k], At[m][k], acc[ai][bj][m][n], 0, 0, 0); __builtin_amdgcn_s_setprio(0); } while (0)
; #define PG8_WAIT_V(n) asm volatile("s_waitcnt vmcnt(" #n ")" ::: "memory")
; #define PG8_WAIT_L(n) asm volatile("s_waitcnt lgkmcnt(" #n ")" ::: "memory")
; #define PG8_BAR __builtin_amdgcn_s_barrier()
; #define PG8_SCHED __builtin_amdgcn_sched_barrier(0)
; template <class Epi, class Sched, bool ATILE = false>
; __device__ __forceinline__ void gemm_phase(LAS unsigned char* lds, const Gemm g, const Sched& S, const Epi& E) {
;     ...
;             PG8_BAR; PG8_WAIT_L(0); PG8_MMA(0, 1, At, B1); PG8_BAR;
;             PG8_LDA(At, 1, 1); PG8_STAGE(PG8_SA(1, 0), a3, voffA);
;             PG8_BAR; PG8_WAIT_L(0); PG8_MMA(1, 0, At, B0); PG8_BAR; PG8_SCHED;
;             PG8_STAGE(PG8_SB(1, 1), b3 + hstepB, voffB);
;             PG8_WAIT_V(6); PG8_BAR; PG8_MMA(1, 1, At, B1); PG8_BAR;
;         }
	s_waitcnt lgkmcnt(0)
	v_mfma_f32_16x16x32_bf16 v[116:119], v[210:213], v[178:181], v[116:119]
	v_mfma_f32_16x16x32_bf16 v[112:115], v[218:221], v[178:181], v[112:115]
	v_mfma_f32_16x16x32_bf16 v[100:103], v[210:213], v[186:189], v[100:103]
	v_mfma_f32_16x16x32_bf16 v[96:99], v[218:221], v[186:189], v[96:99]
	v_mfma_f32_16x16x32_bf16 v[84:87], v[210:213], v[194:197], v[84:87]
	v_mfma_f32_16x16x32_bf16 v[80:83], v[218:221], v[194:197], v[80:83]
	v_mfma_f32_16x16x32_bf16 v[68:71], v[210:213], v[202:205], v[68:71]
	v_mfma_f32_16x16x32_bf16 v[64:67], v[218:221], v[202:205], v[64:67]
	v_mfma_f32_16x16x32_bf16 v[116:119], v[214:217], v[182:185], v[116:119]
	v_mfma_f32_16x16x32_bf16 v[112:115], v[222:225], v[182:185], v[112:115]
	v_mfma_f32_16x16x32_bf16 v[100:103], v[214:217], v[190:193], v[100:103]
	v_mfma_f32_16x16x32_bf16 v[96:99], v[222:225], v[190:193], v[96:99]
	v_mfma_f32_16x16x32_bf16 v[84:87], v[214:217], v[198:201], v[84:87]
	v_mfma_f32_16x16x32_bf16 v[80:83], v[222:225], v[198:201], v[80:83]
	v_mfma_f32_16x16x32_bf16 v[68:71], v[214:217], v[206:209], v[68:71]
	v_mfma_f32_16x16x32_bf16 v[64:67], v[222:225], v[206:209], v[64:67]
	s_barrier
	s_setprio 0
	s_mov_b32 m0, s28
	v_lshl_add_u64 v[144:145], v[228:229], 0, s[0:1]
	ds_read_b128 v[178:181], v148 offset:49152
	ds_read_b128 v[182:185], v148 offset:50176
	ds_read_b128 v[186:189], v148 offset:51200
	ds_read_b128 v[190:193], v148 offset:52224
	ds_read_b128 v[194:197], v148 offset:53248
	ds_read_b128 v[198:201], v148 offset:54272
	ds_read_b128 v[202:205], v148 offset:55296
	ds_read_b128 v[206:209], v148 offset:56320
	global_load_lds_dwordx4 v[144:145], off
	v_lshl_add_u64 v[144:145], v[230:231], 0, s[0:1]
	s_mov_b32 m0, s29
	s_nop 0
	global_load_lds_dwordx4 v[144:145], off
	s_setprio 1
	s_barrier
	s_waitcnt lgkmcnt(0)
	v_mfma_f32_16x16x32_bf16 v[60:63], v[162:165], v[178:181], v[60:63]
	v_mfma_f32_16x16x32_bf16 v[56:59], v[170:173], v[178:181], v[56:59]
	v_mfma_f32_16x16x32_bf16 v[44:47], v[162:165], v[186:189], v[44:47]
	v_mfma_f32_16x16x32_bf16 v[40:43], v[170:173], v[186:189], v[40:43]
	v_mfma_f32_16x16x32_bf16 v[28:31], v[162:165], v[194:197], v[28:31]
	v_mfma_f32_16x16x32_bf16 v[24:27], v[170:173], v[194:197], v[24:27]
	v_mfma_f32_16x16x32_bf16 v[12:15], v[162:165], v[202:205], v[12:15]
	v_mfma_f32_16x16x32_bf16 v[8:11], v[170:173], v[202:205], v[8:11]
	v_mfma_f32_16x16x32_bf16 v[60:63], v[166:169], v[182:185], v[60:63]
	v_mfma_f32_16x16x32_bf16 v[56:59], v[174:177], v[182:185], v[56:59]
	v_mfma_f32_16x16x32_bf16 v[44:47], v[166:169], v[190:193], v[44:47]
	v_mfma_f32_16x16x32_bf16 v[40:43], v[174:177], v[190:193], v[40:43]
	v_mfma_f32_16x16x32_bf16 v[28:31], v[166:169], v[198:201], v[28:31]
	v_mfma_f32_16x16x32_bf16 v[24:27], v[174:177], v[198:201], v[24:27]
	v_mfma_f32_16x16x32_bf16 v[12:15], v[166:169], v[206:209], v[12:15]
	v_mfma_f32_16x16x32_bf16 v[8:11], v[174:177], v[206:209], v[8:11]
	s_barrier
	s_setprio 0
	s_add_u32 s12, s18, 0x18080
	s_addc_u32 s13, s19, 0
	s_mov_b32 m0, s42
	s_nop 0
	global_load_lds_dwordx4 v132, s[12:13]
	s_mov_b32 m0, s43
	s_nop 0
	global_load_lds_dwordx4 v128, s[12:13]
	s_waitcnt vmcnt(6)
	s_setprio 1
	s_barrier
	v_mfma_f32_16x16x32_bf16 v[52:55], v[210:213], v[178:181], v[52:55]
	v_mfma_f32_16x16x32_bf16 v[48:51], v[218:221], v[178:181], v[48:51]
	v_mfma_f32_16x16x32_bf16 v[36:39], v[210:213], v[186:189], v[36:39]
	v_mfma_f32_16x16x32_bf16 v[32:35], v[218:221], v[186:189], v[32:35]
	v_mfma_f32_16x16x32_bf16 v[20:23], v[210:213], v[194:197], v[20:23]
	v_mfma_f32_16x16x32_bf16 v[16:19], v[218:221], v[194:197], v[16:19]
	v_mfma_f32_16x16x32_bf16 v[4:7], v[210:213], v[202:205], v[4:7]
	v_mfma_f32_16x16x32_bf16 v[0:3], v[218:221], v[202:205], v[0:3]
	v_mfma_f32_16x16x32_bf16 v[52:55], v[214:217], v[182:185], v[52:55]
	v_mfma_f32_16x16x32_bf16 v[48:51], v[222:225], v[182:185], v[48:51]
	v_mfma_f32_16x16x32_bf16 v[36:39], v[214:217], v[190:193], v[36:39]
	v_mfma_f32_16x16x32_bf16 v[32:35], v[222:225], v[190:193], v[32:35]
	v_mfma_f32_16x16x32_bf16 v[20:23], v[214:217], v[198:201], v[20:23]
	v_mfma_f32_16x16x32_bf16 v[16:19], v[222:225], v[198:201], v[16:19]
	v_mfma_f32_16x16x32_bf16 v[4:7], v[214:217], v[206:209], v[4:7]
	v_mfma_f32_16x16x32_bf16 v[0:3], v[222:225], v[206:209], v[0:3]
	s_barrier
	s_setprio 0
	s_add_u32 s56, s56, 0x100
	s_addc_u32 s57, s57, 0
	s_cmp_ge_i32 s58, s54
	s_mov_b64 s[12:13], s[16:17]
	s_mov_b32 s18, s58
	s_cbranch_scc0 .LBB0_1426
	s_branch .LBB0_1428

; #define PG8_STAGE(bufoff, gbase, voff) do { _Pragma("unroll") for (int _i = 0; _i < 2; ++_i) \
;         __builtin_amdgcn_global_load_lds((const unsigned*)((const char*)(gbase) + (voff)[_i]), (LAS unsigned*)(lds + (bufoff) + ldsw + _i * 8192), 16, 0, 0); } while (0)
; #define PG8_LDA(dst, b, h) do { _Pragma("unroll") for (int m = 0; m < 4; ++m) _Pragma("unroll") for (int k = 0; k < 2; ++k) dst[m][k] = *(const LAS bf16x8*)(lds + PG8_SA(b, h) + aoff + m * 2048 + k * 1024); } while (0)
; #define PG8_LDB(dst, b, h) do { _Pragma("unroll") for (int n = 0; n < 2; ++n) _Pragma("unroll") for (int k = 0; k < 2; ++k) dst[n][k] = *(const LAS bf16x8*)(lds + PG8_SB(b, h) + boff + n * 2048 + k * 1024); } while (0)
; #define PG8_MMA(ai, bj, At, Bt) do { __builtin_amdgcn_s_setprio(1); _Pragma("unroll") for (int m = 0; m < 4; ++m) _Pragma("unroll") for (int n = 0; n < 2; ++n) _Pragma("unroll") for (int k = 0; k < 2; ++k) \
;         acc[ai][bj][m][n] = __builtin_amdgcn_mfma_f32_16x16x32_bf16(Bt[n][k], At[m][k], acc[ai][bj][m][n], 0, 0, 0); __builtin_amdgcn_s_setprio(0); } while (0)
; #define PG8_WAIT_V(n) asm volatile("s_waitcnt vmcnt(" #n ")" ::: "memory")
; #define PG8_WAIT_L(n) asm volatile("s_waitcnt lgkmcnt(" #n ")" ::: "memory")
; template <class Epi, class Sched, bool ATILE = false>
; __device__ __forceinline__ void gemm_phase(LAS unsigned char* lds, const Gemm g, const Sched& S, const Epi& E) {
;     ...
;         for (int t = 0; t < nt; t += 2) {
;             const bool last = (t == nt - 2);
;             const char* a1 = cA + (size_t)(t + 1) * kstepA;
;             const char* a2 = last ? nA : cA + (size_t)(t + 2) * kstepA; const char* b2 = last ? nB : cB + (size_t)(t + 2) * kstep;
;             const char* a3 = a2 + kstepA; const char* b3 = b2 + kstep;
;             PG8_LDB(B0, 0, 0); PG8_SCHED; PG8_LDA(At, 0, 0); PG8_STAGE(PG8_SA(1, 1), a1 + hstepA, voffA);
;             PG8_WAIT_L(8); PG8_BAR; PG8_WAIT_L(0); PG8_MMA(0, 0, At, B0); PG8_BAR; PG8_SCHED;
;             PG8_LDB(B1, 0, 1); PG8_STAGE(PG8_SB(0, 0), b2, voffB);
;             PG8_BAR; PG8_WAIT_L(0); PG8_MMA(0, 1, At, B1); PG8_BAR;
;             PG8_LDA(At, 0, 1); PG8_STAGE(PG8_SA(0, 0), a2, voffA);
;             PG8_BAR; PG8_WAIT_L(0); PG8_MMA(1, 0, At, B0); PG8_BAR; PG8_SCHED;
;             PG8_STAGE(PG8_SB(0, 1), b2 + hstepB, voffB);
;             PG8_WAIT_V(6); PG8_BAR; PG8_MMA(1, 1, At, B1); PG8_BAR;
.LBB0_1517:
	ds_read_b128 v[96:99], v182
	ds_read_b128 v[100:103], v182 offset:1024
	ds_read_b128 v[112:115], v182 offset:2048
	ds_read_b128 v[116:119], v182 offset:3072
	s_add_i32 s54, s26, 2
	s_add_u32 s27, s24, 0xfffc0080
	s_addc_u32 s28, s25, -1
	s_cmp_eq_u32 s45, s26
	s_cselect_b32 s26, s44, s52
	s_cselect_b32 s29, s17, s28
	s_cselect_b32 s28, s42, s27
	s_cselect_b32 s27, s43, s53
	s_add_i32 m0, s23, 0xc000
	ds_read_b128 v[144:147], v183
	ds_read_b128 v[174:177], v183 offset:1024
	ds_read_b128 v[178:181], v183 offset:2048
	ds_read_b128 v[186:189], v183 offset:3072
	ds_read_b128 v[190:193], v183 offset:4096
	ds_read_b128 v[194:197], v183 offset:5120
	ds_read_b128 v[198:201], v183 offset:6144
	ds_read_b128 v[202:205], v183 offset:7168
	global_load_lds_dwordx4 v166, s[24:25]
	s_add_i32 m0, s23, 0xe000
	s_nop 0
	global_load_lds_dwordx4 v168, s[24:25]
	s_waitcnt lgkmcnt(8)
	s_setprio 1
	s_barrier
	s_waitcnt lgkmcnt(0)
	v_mfma_f32_16x16x32_bf16 v[140:143], v[96:99], v[144:147], v[140:143]
	v_mfma_f32_16x16x32_bf16 v[136:139], v[112:115], v[144:147], v[136:139]
	v_mfma_f32_16x16x32_bf16 v[124:127], v[96:99], v[178:181], v[124:127]
	v_mfma_f32_16x16x32_bf16 v[120:123], v[112:115], v[178:181], v[120:123]
	v_mfma_f32_16x16x32_bf16 v[92:95], v[96:99], v[190:193], v[92:95]
	v_mfma_f32_16x16x32_bf16 v[88:91], v[112:115], v[190:193], v[88:91]
	v_mfma_f32_16x16x32_bf16 v[76:79], v[96:99], v[198:201], v[76:79]
	v_mfma_f32_16x16x32_bf16 v[72:75], v[112:115], v[198:201], v[72:75]
	v_mfma_f32_16x16x32_bf16 v[140:143], v[100:103], v[174:177], v[140:143]
	v_mfma_f32_16x16x32_bf16 v[136:139], v[116:119], v[174:177], v[136:139]
	v_mfma_f32_16x16x32_bf16 v[124:127], v[100:103], v[186:189], v[124:127]
	v_mfma_f32_16x16x32_bf16 v[120:123], v[116:119], v[186:189], v[120:123]
	v_mfma_f32_16x16x32_bf16 v[92:95], v[100:103], v[194:197], v[92:95]
	v_mfma_f32_16x16x32_bf16 v[88:91], v[116:119], v[194:197], v[88:91]
	v_mfma_f32_16x16x32_bf16 v[76:79], v[100:103], v[202:205], v[76:79]
	v_mfma_f32_16x16x32_bf16 v[72:75], v[116:119], v[202:205], v[72:75]
	s_barrier
	s_setprio 0
	s_add_i32 s55, s39, s5
	s_add_u32 s98, s26, s10
	s_addc_u32 s99, s27, s11
	s_mov_b32 m0, s55
	ds_read_b128 v[206:209], v184
	ds_read_b128 v[210:213], v184 offset:1024
	ds_read_b128 v[214:217], v184 offset:2048
	ds_read_b128 v[218:221], v184 offset:3072
	global_load_lds_dwordx4 v150, s[26:27]
	s_add_i32 m0, s55, 0x2000
	s_nop 0
	global_load_lds_dwordx4 v164, s[26:27]
	s_setprio 1
	s_barrier
	s_waitcnt lgkmcnt(0)
	v_mfma_f32_16x16x32_bf16 v[132:135], v[206:209], v[144:147], v[132:135]
	v_mfma_f32_16x16x32_bf16 v[128:131], v[214:217], v[144:147], v[128:131]
	v_mfma_f32_16x16x32_bf16 v[108:111], v[206:209], v[178:181], v[108:111]
	v_mfma_f32_16x16x32_bf16 v[104:107], v[214:217], v[178:181], v[104:107]
	v_mfma_f32_16x16x32_bf16 v[84:87], v[206:209], v[190:193], v[84:87]
	v_mfma_f32_16x16x32_bf16 v[80:83], v[214:217], v[190:193], v[80:83]
	v_mfma_f32_16x16x32_bf16 v[68:71], v[206:209], v[198:201], v[68:71]
	v_mfma_f32_16x16x32_bf16 v[64:67], v[214:217], v[198:201], v[64:67]
	v_mfma_f32_16x16x32_bf16 v[132:135], v[210:213], v[174:177], v[132:135]
	v_mfma_f32_16x16x32_bf16 v[128:131], v[218:221], v[174:177], v[128:131]
	v_mfma_f32_16x16x32_bf16 v[108:111], v[210:213], v[186:189], v[108:111]
	v_mfma_f32_16x16x32_bf16 v[104:107], v[218:221], v[186:189], v[104:107]
	v_mfma_f32_16x16x32_bf16 v[84:87], v[210:213], v[194:197], v[84:87]
	v_mfma_f32_16x16x32_bf16 v[80:83], v[218:221], v[194:197], v[80:83]
	v_mfma_f32_16x16x32_bf16 v[68:71], v[210:213], v[202:205], v[68:71]
	v_mfma_f32_16x16x32_bf16 v[64:67], v[218:221], v[202:205], v[64:67]
	s_barrier
	s_setprio 0
	s_mov_b32 m0, s23
	s_add_u32 s100, s28, s10
	s_addc_u32 s101, s29, s11
	ds_read_b128 v[144:147], v183 offset:16384
	ds_read_b128 v[174:177], v183 offset:17408
	ds_read_b128 v[178:181], v183 offset:18432
	ds_read_b128 v[186:189], v183 offset:19456
	ds_read_b128 v[190:193], v183 offset:20480
	ds_read_b128 v[194:197], v183 offset:21504
	ds_read_b128 v[198:201], v183 offset:22528
	ds_read_b128 v[202:205], v183 offset:23552
	global_load_lds_dwordx4 v148, s[28:29]
	s_mov_b32 m0, s30
	s_nop 0
	global_load_lds_dwordx4 v162, s[28:29]
	s_setprio 1
	s_barrier
	s_waitcnt lgkmcnt(0)
	v_mfma_f32_16x16x32_bf16 v[60:63], v[96:99], v[144:147], v[60:63]
	v_mfma_f32_16x16x32_bf16 v[56:59], v[112:115], v[144:147], v[56:59]
	v_mfma_f32_16x16x32_bf16 v[44:47], v[96:99], v[178:181], v[44:47]
	v_mfma_f32_16x16x32_bf16 v[40:43], v[112:115], v[178:181], v[40:43]
	v_mfma_f32_16x16x32_bf16 v[28:31], v[96:99], v[190:193], v[28:31]
	v_mfma_f32_16x16x32_bf16 v[24:27], v[112:115], v[190:193], v[24:27]
	v_mfma_f32_16x16x32_bf16 v[12:15], v[96:99], v[198:201], v[12:15]
	v_mfma_f32_16x16x32_bf16 v[8:11], v[112:115], v[198:201], v[8:11]
	v_mfma_f32_16x16x32_bf16 v[60:63], v[100:103], v[174:177], v[60:63]
	v_mfma_f32_16x16x32_bf16 v[56:59], v[116:119], v[174:177], v[56:59]
	v_mfma_f32_16x16x32_bf16 v[44:47], v[100:103], v[186:189], v[44:47]
	v_mfma_f32_16x16x32_bf16 v[40:43], v[116:119], v[186:189], v[40:43]
	v_mfma_f32_16x16x32_bf16 v[28:31], v[100:103], v[194:197], v[28:31]
	v_mfma_f32_16x16x32_bf16 v[24:27], v[116:119], v[194:197], v[24:27]
	v_mfma_f32_16x16x32_bf16 v[12:15], v[100:103], v[202:205], v[12:15]
	v_mfma_f32_16x16x32_bf16 v[8:11], v[116:119], v[202:205], v[8:11]
	s_barrier
	s_setprio 0
	s_add_u32 s56, s26, 0x40000
	s_addc_u32 s57, s27, 0
	s_add_i32 s55, s40, s5
	s_mov_b32 m0, s55
	s_nop 0
	global_load_lds_dwordx4 v150, s[56:57]
	s_add_i32 m0, s55, 0x2000
	s_nop 0
	global_load_lds_dwordx4 v164, s[56:57]
	s_waitcnt vmcnt(6)
	s_setprio 1
	s_barrier
; #define PG8_STAGE(bufoff, gbase, voff) do { _Pragma("unroll") for (int _i = 0; _i < 2; ++_i) \
;         __builtin_amdgcn_global_load_lds((const unsigned*)((const char*)(gbase) + (voff)[_i]), (LAS unsigned*)(lds + (bufoff) + ldsw + _i * 8192), 16, 0, 0); } while (0)
; #define PG8_LDA(dst, b, h) do { _Pragma("unroll") for (int m = 0; m < 4; ++m) _Pragma("unroll") for (int k = 0; k < 2; ++k) dst[m][k] = *(const LAS bf16x8*)(lds + PG8_SA(b, h) + aoff + m * 2048 + k * 1024); } while (0)
; #define PG8_LDB(dst, b, h) do { _Pragma("unroll") for (int n = 0; n < 2; ++n) _Pragma("unroll") for (int k = 0; k < 2; ++k) dst[n][k] = *(const LAS bf16x8*)(lds + PG8_SB(b, h) + boff + n * 2048 + k * 1024); } while (0)
; #define PG8_MMA(ai, bj, At, Bt) do { __builtin_amdgcn_s_setprio(1); _Pragma("unroll") for (int m = 0; m < 4; ++m) _Pragma("unroll") for (int n = 0; n < 2; ++n) _Pragma("unroll") for (int k = 0; k < 2; ++k) \
;         acc[ai][bj][m][n] = __builtin_amdgcn_mfma_f32_16x16x32_bf16(Bt[n][k], At[m][k], acc[ai][bj][m][n], 0, 0, 0); __builtin_amdgcn_s_setprio(0); } while (0)
; #define PG8_WAIT_V(n) asm volatile("s_waitcnt vmcnt(" #n ")" ::: "memory")
; #define PG8_WAIT_L(n) asm volatile("s_waitcnt lgkmcnt(" #n ")" ::: "memory")
; #define PG8_BAR __builtin_amdgcn_s_barrier()
; #define PG8_SCHED __builtin_amdgcn_sched_barrier(0)
; template <class Epi, class Sched, bool ATILE = false>
; __device__ __forceinline__ void gemm_phase(LAS unsigned char* lds, const Gemm g, const Sched& S, const Epi& E) {
;     ...
;             PG8_WAIT_V(6); PG8_BAR; PG8_MMA(1, 1, At, B1); PG8_BAR;
;             PG8_LDB(B0, 1, 0); PG8_SCHED; PG8_LDA(At, 1, 0); PG8_STAGE(PG8_SA(0, 1), a2 + hstepA, voffA);
;             PG8_WAIT_L(8); PG8_BAR; PG8_WAIT_L(0); PG8_MMA(0, 0, At, B0); PG8_BAR; PG8_SCHED;
;             PG8_LDB(B1, 1, 1); PG8_STAGE(PG8_SB(1, 0), b3, voffB);
;             PG8_BAR; PG8_WAIT_L(0); PG8_MMA(0, 1, At, B1); PG8_BAR;
	v_mfma_f32_16x16x32_bf16 v[52:55], v[206:209], v[144:147], v[52:55]
	v_mfma_f32_16x16x32_bf16 v[48:51], v[214:217], v[144:147], v[48:51]
	v_mfma_f32_16x16x32_bf16 v[36:39], v[206:209], v[178:181], v[36:39]
	v_mfma_f32_16x16x32_bf16 v[32:35], v[214:217], v[178:181], v[32:35]
	v_mfma_f32_16x16x32_bf16 v[20:23], v[206:209], v[190:193], v[20:23]
	v_mfma_f32_16x16x32_bf16 v[16:19], v[214:217], v[190:193], v[16:19]
	v_mfma_f32_16x16x32_bf16 v[4:7], v[206:209], v[198:201], v[4:7]
	v_mfma_f32_16x16x32_bf16 v[0:3], v[214:217], v[198:201], v[0:3]
	v_mfma_f32_16x16x32_bf16 v[52:55], v[210:213], v[174:177], v[52:55]
	v_mfma_f32_16x16x32_bf16 v[48:51], v[218:221], v[174:177], v[48:51]
	v_mfma_f32_16x16x32_bf16 v[36:39], v[210:213], v[186:189], v[36:39]
	v_mfma_f32_16x16x32_bf16 v[32:35], v[218:221], v[186:189], v[32:35]
	v_mfma_f32_16x16x32_bf16 v[20:23], v[210:213], v[194:197], v[20:23]
	v_mfma_f32_16x16x32_bf16 v[16:19], v[218:221], v[194:197], v[16:19]
	v_mfma_f32_16x16x32_bf16 v[4:7], v[210:213], v[202:205], v[4:7]
	v_mfma_f32_16x16x32_bf16 v[0:3], v[218:221], v[202:205], v[0:3]
	s_barrier
	s_setprio 0
	s_add_i32 s55, 0, 0x18000
	v_add_u32_e32 v116, s55, v159
	ds_read_b128 v[96:99], v116
	ds_read_b128 v[100:103], v116 offset:1024
	ds_read_b128 v[112:115], v116 offset:2048
	ds_read_b128 v[116:119], v116 offset:3072
	s_add_u32 s28, s28, 0x40000
	s_addc_u32 s29, s29, 0
	s_mov_b32 m0, s31
	ds_read_b128 v[144:147], v183 offset:32768
	ds_read_b128 v[174:177], v183 offset:33792
	ds_read_b128 v[178:181], v183 offset:34816
	ds_read_b128 v[186:189], v183 offset:35840
	ds_read_b128 v[190:193], v183 offset:36864
	ds_read_b128 v[194:197], v183 offset:37888
	ds_read_b128 v[198:201], v183 offset:38912
	ds_read_b128 v[202:205], v183 offset:39936
	global_load_lds_dwordx4 v148, s[28:29]
	s_mov_b32 m0, s33
	s_nop 0
	global_load_lds_dwordx4 v162, s[28:29]
	s_waitcnt lgkmcnt(8)
	s_setprio 1
	s_barrier
	s_waitcnt lgkmcnt(0)
	v_mfma_f32_16x16x32_bf16 v[140:143], v[96:99], v[144:147], v[140:143]
	v_mfma_f32_16x16x32_bf16 v[136:139], v[112:115], v[144:147], v[136:139]
	v_mfma_f32_16x16x32_bf16 v[124:127], v[96:99], v[178:181], v[124:127]
	v_mfma_f32_16x16x32_bf16 v[120:123], v[112:115], v[178:181], v[120:123]
	v_mfma_f32_16x16x32_bf16 v[92:95], v[96:99], v[190:193], v[92:95]
	v_mfma_f32_16x16x32_bf16 v[88:91], v[112:115], v[190:193], v[88:91]
	v_mfma_f32_16x16x32_bf16 v[76:79], v[96:99], v[198:201], v[76:79]
	v_mfma_f32_16x16x32_bf16 v[72:75], v[112:115], v[198:201], v[72:75]
	v_mfma_f32_16x16x32_bf16 v[140:143], v[100:103], v[174:177], v[140:143]
	v_mfma_f32_16x16x32_bf16 v[136:139], v[116:119], v[174:177], v[136:139]
	v_mfma_f32_16x16x32_bf16 v[124:127], v[100:103], v[186:189], v[124:127]
	v_mfma_f32_16x16x32_bf16 v[120:123], v[116:119], v[186:189], v[120:123]
	v_mfma_f32_16x16x32_bf16 v[92:95], v[100:103], v[194:197], v[92:95]
	v_mfma_f32_16x16x32_bf16 v[88:91], v[116:119], v[194:197], v[88:91]
	v_mfma_f32_16x16x32_bf16 v[76:79], v[100:103], v[202:205], v[76:79]
	v_mfma_f32_16x16x32_bf16 v[72:75], v[116:119], v[202:205], v[72:75]
	s_barrier
	s_setprio 0
	s_add_i32 s28, 0, 0x1c000
	s_add_i32 s29, s55, s5
	v_add_u32_e32 v185, s28, v159
	s_mov_b32 m0, s29
	ds_read_b128 v[206:209], v185
	ds_read_b128 v[210:213], v185 offset:1024
	ds_read_b128 v[214:217], v185 offset:2048
	ds_read_b128 v[218:221], v185 offset:3072
	global_load_lds_dwordx4 v150, s[98:99]
	s_add_i32 m0, s29, 0x2000
	s_nop 0
	global_load_lds_dwordx4 v164, s[98:99]
	s_setprio 1
	s_barrier
; #define PG8_STAGE(bufoff, gbase, voff) do { _Pragma("unroll") for (int _i = 0; _i < 2; ++_i) \
;         __builtin_amdgcn_global_load_lds((const unsigned*)((const char*)(gbase) + (voff)[_i]), (LAS unsigned*)(lds + (bufoff) + ldsw + _i * 8192), 16, 0, 0); } while (0)
; #define PG8_LDA(dst, b, h) do { _Pragma("unroll") for (int m = 0; m < 4; ++m) _Pragma("unroll") for (int k = 0; k < 2; ++k) dst[m][k] = *(const LAS bf16x8*)(lds + PG8_SA(b, h) + aoff + m * 2048 + k * 1024); } while (0)
; #define PG8_MMA(ai, bj, At, Bt) do { __builtin_amdgcn_s_setprio(1); _Pragma("unroll") for (int m = 0; m < 4; ++m) _Pragma("unroll") for (int n = 0; n < 2; ++n) _Pragma("unroll") for (int k = 0; k < 2; ++k) \
;         acc[ai][bj][m][n] = __builtin_amdgcn_mfma_f32_16x16x32_bf16(Bt[n][k], At[m][k], acc[ai][bj][m][n], 0, 0, 0); __builtin_amdgcn_s_setprio(0); } while (0)
; #define PG8_WAIT_V(n) asm volatile("s_waitcnt vmcnt(" #n ")" ::: "memory")
; #define PG8_WAIT_L(n) asm volatile("s_waitcnt lgkmcnt(" #n ")" ::: "memory")
; #define PG8_BAR __builtin_amdgcn_s_barrier()
; #define PG8_SCHED __builtin_amdgcn_sched_barrier(0)
; template <class Epi, class Sched, bool ATILE = false>
; __device__ __forceinline__ void gemm_phase(LAS unsigned char* lds, const Gemm g, const Sched& S, const Epi& E) {
;     ...
;             PG8_BAR; PG8_WAIT_L(0); PG8_MMA(0, 1, At, B1); PG8_BAR;
;             PG8_LDA(At, 1, 1); PG8_STAGE(PG8_SA(1, 0), a3, voffA);
;             PG8_BAR; PG8_WAIT_L(0); PG8_MMA(1, 0, At, B0); PG8_BAR; PG8_SCHED;
;             PG8_STAGE(PG8_SB(1, 1), b3 + hstepB, voffB);
;             PG8_WAIT_V(6); PG8_BAR; PG8_MMA(1, 1, At, B1); PG8_BAR;
;         }
	s_waitcnt lgkmcnt(0)
	v_mfma_f32_16x16x32_bf16 v[132:135], v[206:209], v[144:147], v[132:135]
	v_mfma_f32_16x16x32_bf16 v[128:131], v[214:217], v[144:147], v[128:131]
	v_mfma_f32_16x16x32_bf16 v[108:111], v[206:209], v[178:181], v[108:111]
	v_mfma_f32_16x16x32_bf16 v[104:107], v[214:217], v[178:181], v[104:107]
	v_mfma_f32_16x16x32_bf16 v[84:87], v[206:209], v[190:193], v[84:87]
	v_mfma_f32_16x16x32_bf16 v[80:83], v[214:217], v[190:193], v[80:83]
	v_mfma_f32_16x16x32_bf16 v[68:71], v[206:209], v[198:201], v[68:71]
	v_mfma_f32_16x16x32_bf16 v[64:67], v[214:217], v[198:201], v[64:67]
	v_mfma_f32_16x16x32_bf16 v[132:135], v[210:213], v[174:177], v[132:135]
	v_mfma_f32_16x16x32_bf16 v[128:131], v[218:221], v[174:177], v[128:131]
	v_mfma_f32_16x16x32_bf16 v[108:111], v[210:213], v[186:189], v[108:111]
	v_mfma_f32_16x16x32_bf16 v[104:107], v[218:221], v[186:189], v[104:107]
	v_mfma_f32_16x16x32_bf16 v[84:87], v[210:213], v[194:197], v[84:87]
	v_mfma_f32_16x16x32_bf16 v[80:83], v[218:221], v[194:197], v[80:83]
	v_mfma_f32_16x16x32_bf16 v[68:71], v[210:213], v[202:205], v[68:71]
	v_mfma_f32_16x16x32_bf16 v[64:67], v[218:221], v[202:205], v[64:67]
	s_barrier
	s_setprio 0
	s_mov_b32 m0, s35
	ds_read_b128 v[144:147], v183 offset:49152
	ds_read_b128 v[174:177], v183 offset:50176
	ds_read_b128 v[178:181], v183 offset:51200
	ds_read_b128 v[186:189], v183 offset:52224
	ds_read_b128 v[190:193], v183 offset:53248
	ds_read_b128 v[194:197], v183 offset:54272
	ds_read_b128 v[198:201], v183 offset:55296
	ds_read_b128 v[202:205], v183 offset:56320
	global_load_lds_dwordx4 v148, s[100:101]
	s_mov_b32 m0, s36
	s_nop 0
	global_load_lds_dwordx4 v162, s[100:101]
	s_setprio 1
	s_barrier
	s_waitcnt lgkmcnt(0)
	v_mfma_f32_16x16x32_bf16 v[60:63], v[96:99], v[144:147], v[60:63]
	v_mfma_f32_16x16x32_bf16 v[56:59], v[112:115], v[144:147], v[56:59]
	v_mfma_f32_16x16x32_bf16 v[44:47], v[96:99], v[178:181], v[44:47]
	v_mfma_f32_16x16x32_bf16 v[40:43], v[112:115], v[178:181], v[40:43]
	v_mfma_f32_16x16x32_bf16 v[28:31], v[96:99], v[190:193], v[28:31]
	v_mfma_f32_16x16x32_bf16 v[24:27], v[112:115], v[190:193], v[24:27]
	v_mfma_f32_16x16x32_bf16 v[12:15], v[96:99], v[198:201], v[12:15]
	v_mfma_f32_16x16x32_bf16 v[8:11], v[112:115], v[198:201], v[8:11]
	v_mfma_f32_16x16x32_bf16 v[60:63], v[100:103], v[174:177], v[60:63]
	v_mfma_f32_16x16x32_bf16 v[56:59], v[116:119], v[174:177], v[56:59]
	v_mfma_f32_16x16x32_bf16 v[44:47], v[100:103], v[186:189], v[44:47]
	v_mfma_f32_16x16x32_bf16 v[40:43], v[116:119], v[186:189], v[40:43]
	v_mfma_f32_16x16x32_bf16 v[28:31], v[100:103], v[194:197], v[28:31]
	v_mfma_f32_16x16x32_bf16 v[24:27], v[116:119], v[194:197], v[24:27]
	v_mfma_f32_16x16x32_bf16 v[12:15], v[100:103], v[202:205], v[12:15]
	v_mfma_f32_16x16x32_bf16 v[8:11], v[116:119], v[202:205], v[8:11]
	s_barrier
	s_setprio 0
	s_add_u32 s26, s26, 0x40080
	s_addc_u32 s27, s27, 0
	s_add_i32 s28, s28, s5
	s_mov_b32 m0, s28
	s_nop 0
	global_load_lds_dwordx4 v150, s[26:27]
	s_add_i32 m0, s28, 0x2000
	s_nop 0
	global_load_lds_dwordx4 v164, s[26:27]
	s_waitcnt vmcnt(6)
	s_setprio 1
	s_barrier
	v_mfma_f32_16x16x32_bf16 v[52:55], v[206:209], v[144:147], v[52:55]
	v_mfma_f32_16x16x32_bf16 v[48:51], v[214:217], v[144:147], v[48:51]
	v_mfma_f32_16x16x32_bf16 v[36:39], v[206:209], v[178:181], v[36:39]
	v_mfma_f32_16x16x32_bf16 v[32:35], v[214:217], v[178:181], v[32:35]
	v_mfma_f32_16x16x32_bf16 v[20:23], v[206:209], v[190:193], v[20:23]
	v_mfma_f32_16x16x32_bf16 v[16:19], v[214:217], v[190:193], v[16:19]
	v_mfma_f32_16x16x32_bf16 v[4:7], v[206:209], v[198:201], v[4:7]
	v_mfma_f32_16x16x32_bf16 v[0:3], v[214:217], v[198:201], v[0:3]
	v_mfma_f32_16x16x32_bf16 v[52:55], v[210:213], v[174:177], v[52:55]
	v_mfma_f32_16x16x32_bf16 v[48:51], v[218:221], v[174:177], v[48:51]
	v_mfma_f32_16x16x32_bf16 v[36:39], v[210:213], v[186:189], v[36:39]
	v_mfma_f32_16x16x32_bf16 v[32:35], v[218:221], v[186:189], v[32:35]
	v_mfma_f32_16x16x32_bf16 v[20:23], v[210:213], v[194:197], v[20:23]
	v_mfma_f32_16x16x32_bf16 v[16:19], v[218:221], v[194:197], v[16:19]
	v_mfma_f32_16x16x32_bf16 v[4:7], v[210:213], v[202:205], v[4:7]
	v_mfma_f32_16x16x32_bf16 v[0:3], v[218:221], v[202:205], v[0:3]
	s_barrier
	s_setprio 0
	s_add_u32 s24, s24, 0x100
	s_addc_u32 s25, s25, 0
	s_add_u32 s52, s52, 0x100
	s_addc_u32 s53, s53, 0
	s_cmp_ge_i32 s54, s13
	s_mov_b32 s26, s54
	s_cbranch_scc0 .LBB0_1517
	s_branch .LBB0_1508

; #define PG8_STAGE(bufoff, gbase, voff) do { _Pragma("unroll") for (int _i = 0; _i < 2; ++_i) \
;         __builtin_amdgcn_global_load_lds((const unsigned*)((const char*)(gbase) + (voff)[_i]), (LAS unsigned*)(lds + (bufoff) + ldsw + _i * 8192), 16, 0, 0); } while (0)
; #define PG8_LDA(dst, b, h) do { _Pragma("unroll") for (int m = 0; m < 4; ++m) _Pragma("unroll") for (int k = 0; k < 2; ++k) dst[m][k] = *(const LAS bf16x8*)(lds + PG8_SA(b, h) + aoff + m * 2048 + k * 1024); } while (0)
; #define PG8_LDB(dst, b, h) do { _Pragma("unroll") for (int n = 0; n < 2; ++n) _Pragma("unroll") for (int k = 0; k < 2; ++k) dst[n][k] = *(const LAS bf16x8*)(lds + PG8_SB(b, h) + boff + n * 2048 + k * 1024); } while (0)
; #define PG8_MMA(ai, bj, At, Bt) do { __builtin_amdgcn_s_setprio(1); _Pragma("unroll") for (int m = 0; m < 4; ++m) _Pragma("unroll") for (int n = 0; n < 2; ++n) _Pragma("unroll") for (int k = 0; k < 2; ++k) \
;         acc[ai][bj][m][n] = __builtin_amdgcn_mfma_f32_16x16x32_bf16(Bt[n][k], At[m][k], acc[ai][bj][m][n], 0, 0, 0); __builtin_amdgcn_s_setprio(0); } while (0)
; #define PG8_WAIT_V(n) asm volatile("s_waitcnt vmcnt(" #n ")" ::: "memory")
; #define PG8_WAIT_L(n) asm volatile("s_waitcnt lgkmcnt(" #n ")" ::: "memory")
; template <class Epi, class Sched, bool ATILE = false>
; __device__ __forceinline__ void gemm_phase(LAS unsigned char* lds, const Gemm g, const Sched& S, const Epi& E) {
;     ...
;         for (int t = 0; t < nt; t += 2) {
;             const bool last = (t == nt - 2);
;             const char* a1 = cA + (size_t)(t + 1) * kstepA;
;             const char* a2 = last ? nA : cA + (size_t)(t + 2) * kstepA; const char* b2 = last ? nB : cB + (size_t)(t + 2) * kstep;
;             const char* a3 = a2 + kstepA; const char* b3 = b2 + kstep;
;             PG8_LDB(B0, 0, 0); PG8_SCHED; PG8_LDA(At, 0, 0); PG8_STAGE(PG8_SA(1, 1), a1 + hstepA, voffA);
;             PG8_WAIT_L(8); PG8_BAR; PG8_WAIT_L(0); PG8_MMA(0, 0, At, B0); PG8_BAR; PG8_SCHED;
;             PG8_LDB(B1, 0, 1); PG8_STAGE(PG8_SB(0, 0), b2, voffB);
;             PG8_BAR; PG8_WAIT_L(0); PG8_MMA(0, 1, At, B1); PG8_BAR;
;             PG8_LDA(At, 0, 1); PG8_STAGE(PG8_SA(0, 0), a2, voffA);
;             PG8_BAR; PG8_WAIT_L(0); PG8_MMA(1, 0, At, B0); PG8_BAR; PG8_SCHED;
;             PG8_STAGE(PG8_SB(0, 1), b2 + hstepB, voffB);
;             PG8_WAIT_V(6); PG8_BAR; PG8_MMA(1, 1, At, B1); PG8_BAR;
.LBB0_1658:
	s_waitcnt lgkmcnt(0)
	ds_read_b128 v[128:131], v169
	ds_read_b128 v[132:135], v169 offset:1024
	ds_read_b128 v[136:139], v169 offset:2048
	ds_read_b128 v[140:143], v169 offset:3072
	s_add_i32 s29, s27, 2
	s_add_u32 s34, s30, 0x4000
	s_addc_u32 s35, s31, 0
	s_cmp_eq_u32 s11, s27
	s_cselect_b32 s38, s22, s34
	s_cselect_b32 s39, s23, s35
	s_cselect_b32 s34, s24, s13
	s_cselect_b32 s35, s25, s17
	s_add_u32 s36, s38, 0x8000
	s_addc_u32 s37, s39, 0
	s_add_i32 m0, s5, 0xc000
	ds_read_b128 v[144:147], v210
	ds_read_b128 v[148:151], v210 offset:1024
	ds_read_b128 v[192:195], v210 offset:2048
	ds_read_b128 v[196:199], v210 offset:3072
	ds_read_b128 v[200:203], v210 offset:4096
	ds_read_b128 v[204:207], v210 offset:5120
	ds_read_b128 v[214:217], v210 offset:6144
	ds_read_b128 v[218:221], v210 offset:7168
	global_load_lds_dwordx4 v186, s[30:31]
	s_add_i32 m0, s5, 0xe000
	s_nop 0
	global_load_lds_dwordx4 v188, s[30:31]
	s_waitcnt lgkmcnt(8)
	s_setprio 1
	s_barrier
	s_waitcnt lgkmcnt(0)
	v_mfma_f32_16x16x32_bf16 v[120:123], v[128:131], v[144:147], v[120:123]
	v_mfma_f32_16x16x32_bf16 v[116:119], v[136:139], v[144:147], v[116:119]
	v_mfma_f32_16x16x32_bf16 v[108:111], v[128:131], v[192:195], v[108:111]
	v_mfma_f32_16x16x32_bf16 v[100:103], v[136:139], v[192:195], v[100:103]
	v_mfma_f32_16x16x32_bf16 v[92:95], v[128:131], v[200:203], v[92:95]
	v_mfma_f32_16x16x32_bf16 v[84:87], v[136:139], v[200:203], v[84:87]
	v_mfma_f32_16x16x32_bf16 v[76:79], v[128:131], v[214:217], v[76:79]
	v_mfma_f32_16x16x32_bf16 v[68:71], v[136:139], v[214:217], v[68:71]
	v_mfma_f32_16x16x32_bf16 v[120:123], v[132:135], v[148:151], v[120:123]
	v_mfma_f32_16x16x32_bf16 v[116:119], v[140:143], v[148:151], v[116:119]
	v_mfma_f32_16x16x32_bf16 v[108:111], v[132:135], v[196:199], v[108:111]
	v_mfma_f32_16x16x32_bf16 v[100:103], v[140:143], v[196:199], v[100:103]
	v_mfma_f32_16x16x32_bf16 v[92:95], v[132:135], v[204:207], v[92:95]
	v_mfma_f32_16x16x32_bf16 v[84:87], v[140:143], v[204:207], v[84:87]
	v_mfma_f32_16x16x32_bf16 v[76:79], v[132:135], v[218:221], v[76:79]
	v_mfma_f32_16x16x32_bf16 v[68:71], v[140:143], v[218:221], v[68:71]
	s_barrier
	s_setprio 0
	s_add_i32 s27, s52, s4
	s_add_u32 s98, s34, s8
	s_addc_u32 s99, s35, s9
	s_mov_b32 m0, s27
	ds_read_b128 v[222:225], v211
	ds_read_b128 v[226:229], v211 offset:1024
	ds_read_b128 v[230:233], v211 offset:2048
	ds_read_b128 v[234:237], v211 offset:3072
	global_load_lds_dwordx4 v162, s[34:35]
	s_add_i32 m0, s27, 0x2000
	s_nop 0
	global_load_lds_dwordx4 v166, s[34:35]
	s_setprio 1
	s_barrier
	s_waitcnt lgkmcnt(0)
	v_mfma_f32_16x16x32_bf16 v[124:127], v[222:225], v[144:147], v[124:127]
	v_mfma_f32_16x16x32_bf16 v[112:115], v[230:233], v[144:147], v[112:115]
	v_mfma_f32_16x16x32_bf16 v[104:107], v[222:225], v[192:195], v[104:107]
	v_mfma_f32_16x16x32_bf16 v[96:99], v[230:233], v[192:195], v[96:99]
	v_mfma_f32_16x16x32_bf16 v[88:91], v[222:225], v[200:203], v[88:91]
	v_mfma_f32_16x16x32_bf16 v[80:83], v[230:233], v[200:203], v[80:83]
	v_mfma_f32_16x16x32_bf16 v[72:75], v[222:225], v[214:217], v[72:75]
	v_mfma_f32_16x16x32_bf16 v[64:67], v[230:233], v[214:217], v[64:67]
	v_mfma_f32_16x16x32_bf16 v[124:127], v[226:229], v[148:151], v[124:127]
	v_mfma_f32_16x16x32_bf16 v[112:115], v[234:237], v[148:151], v[112:115]
	v_mfma_f32_16x16x32_bf16 v[104:107], v[226:229], v[196:199], v[104:107]
	v_mfma_f32_16x16x32_bf16 v[96:99], v[234:237], v[196:199], v[96:99]
	v_mfma_f32_16x16x32_bf16 v[88:91], v[226:229], v[204:207], v[88:91]
	v_mfma_f32_16x16x32_bf16 v[80:83], v[234:237], v[204:207], v[80:83]
	v_mfma_f32_16x16x32_bf16 v[72:75], v[226:229], v[218:221], v[72:75]
	v_mfma_f32_16x16x32_bf16 v[64:67], v[234:237], v[218:221], v[64:67]
	s_barrier
	s_setprio 0
	s_mov_b32 m0, s5
	ds_read_b128 v[144:147], v210 offset:16384
	ds_read_b128 v[148:151], v210 offset:17408
	ds_read_b128 v[192:195], v210 offset:18432
	ds_read_b128 v[196:199], v210 offset:19456
	ds_read_b128 v[200:203], v210 offset:20480
	ds_read_b128 v[204:207], v210 offset:21504
	ds_read_b128 v[214:217], v210 offset:22528
	ds_read_b128 v[218:221], v210 offset:23552
	global_load_lds_dwordx4 v160, s[38:39]
	s_mov_b32 m0, s33
	s_nop 0
	global_load_lds_dwordx4 v164, s[38:39]
	s_setprio 1
	s_barrier
	s_waitcnt lgkmcnt(0)
	v_mfma_f32_16x16x32_bf16 v[60:63], v[128:131], v[144:147], v[60:63]
	v_mfma_f32_16x16x32_bf16 v[56:59], v[136:139], v[144:147], v[56:59]
	v_mfma_f32_16x16x32_bf16 v[44:47], v[128:131], v[192:195], v[44:47]
	v_mfma_f32_16x16x32_bf16 v[40:43], v[136:139], v[192:195], v[40:43]
	v_mfma_f32_16x16x32_bf16 v[28:31], v[128:131], v[200:203], v[28:31]
	v_mfma_f32_16x16x32_bf16 v[24:27], v[136:139], v[200:203], v[24:27]
	v_mfma_f32_16x16x32_bf16 v[12:15], v[128:131], v[214:217], v[12:15]
	v_mfma_f32_16x16x32_bf16 v[8:11], v[136:139], v[214:217], v[8:11]
	v_mfma_f32_16x16x32_bf16 v[60:63], v[132:135], v[148:151], v[60:63]
	v_mfma_f32_16x16x32_bf16 v[56:59], v[140:143], v[148:151], v[56:59]
	v_mfma_f32_16x16x32_bf16 v[44:47], v[132:135], v[196:199], v[44:47]
	v_mfma_f32_16x16x32_bf16 v[40:43], v[140:143], v[196:199], v[40:43]
	v_mfma_f32_16x16x32_bf16 v[28:31], v[132:135], v[204:207], v[28:31]
	v_mfma_f32_16x16x32_bf16 v[24:27], v[140:143], v[204:207], v[24:27]
	v_mfma_f32_16x16x32_bf16 v[12:15], v[132:135], v[218:221], v[12:15]
	v_mfma_f32_16x16x32_bf16 v[8:11], v[140:143], v[218:221], v[8:11]
	s_barrier
	s_setprio 0
	s_add_u32 s56, s34, 0x80000
	s_addc_u32 s57, s35, 0
	s_add_i32 s27, s53, s4
	s_mov_b32 m0, s27
	s_nop 0
	global_load_lds_dwordx4 v162, s[56:57]
	s_add_i32 m0, s27, 0x2000
	s_nop 0
	global_load_lds_dwordx4 v166, s[56:57]
	s_waitcnt vmcnt(6)
	s_setprio 1
	s_barrier
; #define PG8_STAGE(bufoff, gbase, voff) do { _Pragma("unroll") for (int _i = 0; _i < 2; ++_i) \
;         __builtin_amdgcn_global_load_lds((const unsigned*)((const char*)(gbase) + (voff)[_i]), (LAS unsigned*)(lds + (bufoff) + ldsw + _i * 8192), 16, 0, 0); } while (0)
; #define PG8_LDA(dst, b, h) do { _Pragma("unroll") for (int m = 0; m < 4; ++m) _Pragma("unroll") for (int k = 0; k < 2; ++k) dst[m][k] = *(const LAS bf16x8*)(lds + PG8_SA(b, h) + aoff + m * 2048 + k * 1024); } while (0)
; #define PG8_LDB(dst, b, h) do { _Pragma("unroll") for (int n = 0; n < 2; ++n) _Pragma("unroll") for (int k = 0; k < 2; ++k) dst[n][k] = *(const LAS bf16x8*)(lds + PG8_SB(b, h) + boff + n * 2048 + k * 1024); } while (0)
; #define PG8_MMA(ai, bj, At, Bt) do { __builtin_amdgcn_s_setprio(1); _Pragma("unroll") for (int m = 0; m < 4; ++m) _Pragma("unroll") for (int n = 0; n < 2; ++n) _Pragma("unroll") for (int k = 0; k < 2; ++k) \
;         acc[ai][bj][m][n] = __builtin_amdgcn_mfma_f32_16x16x32_bf16(Bt[n][k], At[m][k], acc[ai][bj][m][n], 0, 0, 0); __builtin_amdgcn_s_setprio(0); } while (0)
; #define PG8_WAIT_V(n) asm volatile("s_waitcnt vmcnt(" #n ")" ::: "memory")
; #define PG8_WAIT_L(n) asm volatile("s_waitcnt lgkmcnt(" #n ")" ::: "memory")
; #define PG8_BAR __builtin_amdgcn_s_barrier()
; #define PG8_SCHED __builtin_amdgcn_sched_barrier(0)
; template <class Epi, class Sched, bool ATILE = false>
; __device__ __forceinline__ void gemm_phase(LAS unsigned char* lds, const Gemm g, const Sched& S, const Epi& E) {
;     ...
;             PG8_WAIT_V(6); PG8_BAR; PG8_MMA(1, 1, At, B1); PG8_BAR;
;             PG8_LDB(B0, 1, 0); PG8_SCHED; PG8_LDA(At, 1, 0); PG8_STAGE(PG8_SA(0, 1), a2 + hstepA, voffA);
;             PG8_WAIT_L(8); PG8_BAR; PG8_WAIT_L(0); PG8_MMA(0, 0, At, B0); PG8_BAR; PG8_SCHED;
;             PG8_LDB(B1, 1, 1); PG8_STAGE(PG8_SB(1, 0), b3, voffB);
;             PG8_BAR; PG8_WAIT_L(0); PG8_MMA(0, 1, At, B1); PG8_BAR;
	v_mfma_f32_16x16x32_bf16 v[52:55], v[222:225], v[144:147], v[52:55]
	v_mfma_f32_16x16x32_bf16 v[48:51], v[230:233], v[144:147], v[48:51]
	v_mfma_f32_16x16x32_bf16 v[36:39], v[222:225], v[192:195], v[36:39]
	v_mfma_f32_16x16x32_bf16 v[32:35], v[230:233], v[192:195], v[32:35]
	v_mfma_f32_16x16x32_bf16 v[20:23], v[222:225], v[200:203], v[20:23]
	v_mfma_f32_16x16x32_bf16 v[16:19], v[230:233], v[200:203], v[16:19]
	v_mfma_f32_16x16x32_bf16 v[4:7], v[222:225], v[214:217], v[4:7]
	v_mfma_f32_16x16x32_bf16 v[0:3], v[230:233], v[214:217], v[0:3]
	v_mfma_f32_16x16x32_bf16 v[52:55], v[226:229], v[148:151], v[52:55]
	v_mfma_f32_16x16x32_bf16 v[48:51], v[234:237], v[148:151], v[48:51]
	v_mfma_f32_16x16x32_bf16 v[36:39], v[226:229], v[196:199], v[36:39]
	v_mfma_f32_16x16x32_bf16 v[32:35], v[234:237], v[196:199], v[32:35]
	v_mfma_f32_16x16x32_bf16 v[20:23], v[226:229], v[204:207], v[20:23]
	v_mfma_f32_16x16x32_bf16 v[16:19], v[234:237], v[204:207], v[16:19]
	v_mfma_f32_16x16x32_bf16 v[4:7], v[226:229], v[218:221], v[4:7]
	v_mfma_f32_16x16x32_bf16 v[0:3], v[234:237], v[218:221], v[0:3]
	s_barrier
	s_setprio 0
	s_add_i32 s27, 0, 0x18000
	v_add_u32_e32 v140, s27, v157
	ds_read_b128 v[128:131], v140
	ds_read_b128 v[132:135], v140 offset:1024
	ds_read_b128 v[136:139], v140 offset:2048
	ds_read_b128 v[140:143], v140 offset:3072
	s_add_u32 s38, s38, 0x4000
	s_addc_u32 s39, s39, 0
	s_mov_b32 m0, s40
	ds_read_b128 v[144:147], v210 offset:32768
	ds_read_b128 v[148:151], v210 offset:33792
	ds_read_b128 v[192:195], v210 offset:34816
	ds_read_b128 v[196:199], v210 offset:35840
	ds_read_b128 v[200:203], v210 offset:36864
	ds_read_b128 v[204:207], v210 offset:37888
	ds_read_b128 v[214:217], v210 offset:38912
	ds_read_b128 v[218:221], v210 offset:39936
	global_load_lds_dwordx4 v160, s[38:39]
	s_mov_b32 m0, s41
	s_nop 0
	global_load_lds_dwordx4 v164, s[38:39]
	s_waitcnt lgkmcnt(8)
	s_setprio 1
	s_barrier
	s_waitcnt lgkmcnt(0)
	v_mfma_f32_16x16x32_bf16 v[120:123], v[128:131], v[144:147], v[120:123]
	v_mfma_f32_16x16x32_bf16 v[116:119], v[136:139], v[144:147], v[116:119]
	v_mfma_f32_16x16x32_bf16 v[108:111], v[128:131], v[192:195], v[108:111]
	v_mfma_f32_16x16x32_bf16 v[100:103], v[136:139], v[192:195], v[100:103]
	v_mfma_f32_16x16x32_bf16 v[92:95], v[128:131], v[200:203], v[92:95]
	v_mfma_f32_16x16x32_bf16 v[84:87], v[136:139], v[200:203], v[84:87]
	v_mfma_f32_16x16x32_bf16 v[76:79], v[128:131], v[214:217], v[76:79]
	v_mfma_f32_16x16x32_bf16 v[68:71], v[136:139], v[214:217], v[68:71]
	v_mfma_f32_16x16x32_bf16 v[120:123], v[132:135], v[148:151], v[120:123]
	v_mfma_f32_16x16x32_bf16 v[116:119], v[140:143], v[148:151], v[116:119]
	v_mfma_f32_16x16x32_bf16 v[108:111], v[132:135], v[196:199], v[108:111]
	v_mfma_f32_16x16x32_bf16 v[100:103], v[140:143], v[196:199], v[100:103]
	v_mfma_f32_16x16x32_bf16 v[92:95], v[132:135], v[204:207], v[92:95]
	v_mfma_f32_16x16x32_bf16 v[84:87], v[140:143], v[204:207], v[84:87]
	v_mfma_f32_16x16x32_bf16 v[76:79], v[132:135], v[218:221], v[76:79]
	v_mfma_f32_16x16x32_bf16 v[68:71], v[140:143], v[218:221], v[68:71]
	s_barrier
	s_setprio 0
	s_add_i32 s38, 0, 0x1c000
	s_add_i32 s27, s27, s4
	v_add_u32_e32 v213, s38, v157
	s_mov_b32 m0, s27
	ds_read_b128 v[222:225], v213
	ds_read_b128 v[226:229], v213 offset:1024
	ds_read_b128 v[230:233], v213 offset:2048
	ds_read_b128 v[234:237], v213 offset:3072
	global_load_lds_dwordx4 v162, s[98:99]
	s_add_i32 m0, s27, 0x2000
	s_nop 0
	global_load_lds_dwordx4 v166, s[98:99]
	s_setprio 1
	s_barrier
; #define PG8_STAGE(bufoff, gbase, voff) do { _Pragma("unroll") for (int _i = 0; _i < 2; ++_i) \
;         __builtin_amdgcn_global_load_lds((const unsigned*)((const char*)(gbase) + (voff)[_i]), (LAS unsigned*)(lds + (bufoff) + ldsw + _i * 8192), 16, 0, 0); } while (0)
; #define PG8_LDA(dst, b, h) do { _Pragma("unroll") for (int m = 0; m < 4; ++m) _Pragma("unroll") for (int k = 0; k < 2; ++k) dst[m][k] = *(const LAS bf16x8*)(lds + PG8_SA(b, h) + aoff + m * 2048 + k * 1024); } while (0)
; #define PG8_MMA(ai, bj, At, Bt) do { __builtin_amdgcn_s_setprio(1); _Pragma("unroll") for (int m = 0; m < 4; ++m) _Pragma("unroll") for (int n = 0; n < 2; ++n) _Pragma("unroll") for (int k = 0; k < 2; ++k) \
;         acc[ai][bj][m][n] = __builtin_amdgcn_mfma_f32_16x16x32_bf16(Bt[n][k], At[m][k], acc[ai][bj][m][n], 0, 0, 0); __builtin_amdgcn_s_setprio(0); } while (0)
; #define PG8_WAIT_V(n) asm volatile("s_waitcnt vmcnt(" #n ")" ::: "memory")
; #define PG8_WAIT_L(n) asm volatile("s_waitcnt lgkmcnt(" #n ")" ::: "memory")
; #define PG8_BAR __builtin_amdgcn_s_barrier()
; #define PG8_SCHED __builtin_amdgcn_sched_barrier(0)
; template <class Epi, class Sched, bool ATILE = false>
; __device__ __forceinline__ void gemm_phase(LAS unsigned char* lds, const Gemm g, const Sched& S, const Epi& E) {
;     ...
;             PG8_BAR; PG8_WAIT_L(0); PG8_MMA(0, 1, At, B1); PG8_BAR;
;             PG8_LDA(At, 1, 1); PG8_STAGE(PG8_SA(1, 0), a3, voffA);
;             PG8_BAR; PG8_WAIT_L(0); PG8_MMA(1, 0, At, B0); PG8_BAR; PG8_SCHED;
;             PG8_STAGE(PG8_SB(1, 1), b3 + hstepB, voffB);
;             PG8_WAIT_V(6); PG8_BAR; PG8_MMA(1, 1, At, B1); PG8_BAR;
;         }
	s_waitcnt lgkmcnt(0)
	v_mfma_f32_16x16x32_bf16 v[124:127], v[222:225], v[144:147], v[124:127]
	v_mfma_f32_16x16x32_bf16 v[112:115], v[230:233], v[144:147], v[112:115]
	v_mfma_f32_16x16x32_bf16 v[104:107], v[222:225], v[192:195], v[104:107]
	v_mfma_f32_16x16x32_bf16 v[96:99], v[230:233], v[192:195], v[96:99]
	v_mfma_f32_16x16x32_bf16 v[88:91], v[222:225], v[200:203], v[88:91]
	v_mfma_f32_16x16x32_bf16 v[80:83], v[230:233], v[200:203], v[80:83]
	v_mfma_f32_16x16x32_bf16 v[72:75], v[222:225], v[214:217], v[72:75]
	v_mfma_f32_16x16x32_bf16 v[64:67], v[230:233], v[214:217], v[64:67]
	v_mfma_f32_16x16x32_bf16 v[124:127], v[226:229], v[148:151], v[124:127]
	v_mfma_f32_16x16x32_bf16 v[112:115], v[234:237], v[148:151], v[112:115]
	v_mfma_f32_16x16x32_bf16 v[104:107], v[226:229], v[196:199], v[104:107]
	v_mfma_f32_16x16x32_bf16 v[96:99], v[234:237], v[196:199], v[96:99]
	v_mfma_f32_16x16x32_bf16 v[88:91], v[226:229], v[204:207], v[88:91]
	v_mfma_f32_16x16x32_bf16 v[80:83], v[234:237], v[204:207], v[80:83]
	v_mfma_f32_16x16x32_bf16 v[72:75], v[226:229], v[218:221], v[72:75]
	v_mfma_f32_16x16x32_bf16 v[64:67], v[234:237], v[218:221], v[64:67]
	s_barrier
	s_setprio 0
	s_mov_b32 m0, s43
	ds_read_b128 v[144:147], v210 offset:49152
	ds_read_b128 v[148:151], v210 offset:50176
	ds_read_b128 v[192:195], v210 offset:51200
	ds_read_b128 v[196:199], v210 offset:52224
	ds_read_b128 v[200:203], v210 offset:53248
	ds_read_b128 v[204:207], v210 offset:54272
	ds_read_b128 v[214:217], v210 offset:55296
	ds_read_b128 v[218:221], v210 offset:56320
	global_load_lds_dwordx4 v160, s[36:37]
	s_mov_b32 m0, s44
	s_nop 0
	global_load_lds_dwordx4 v164, s[36:37]
	s_setprio 1
	s_barrier
	s_waitcnt lgkmcnt(0)
	v_mfma_f32_16x16x32_bf16 v[60:63], v[128:131], v[144:147], v[60:63]
	v_mfma_f32_16x16x32_bf16 v[56:59], v[136:139], v[144:147], v[56:59]
	v_mfma_f32_16x16x32_bf16 v[44:47], v[128:131], v[192:195], v[44:47]
	v_mfma_f32_16x16x32_bf16 v[40:43], v[136:139], v[192:195], v[40:43]
	v_mfma_f32_16x16x32_bf16 v[28:31], v[128:131], v[200:203], v[28:31]
	v_mfma_f32_16x16x32_bf16 v[24:27], v[136:139], v[200:203], v[24:27]
	v_mfma_f32_16x16x32_bf16 v[12:15], v[128:131], v[214:217], v[12:15]
	v_mfma_f32_16x16x32_bf16 v[8:11], v[136:139], v[214:217], v[8:11]
	v_mfma_f32_16x16x32_bf16 v[60:63], v[132:135], v[148:151], v[60:63]
	v_mfma_f32_16x16x32_bf16 v[56:59], v[140:143], v[148:151], v[56:59]
	v_mfma_f32_16x16x32_bf16 v[44:47], v[132:135], v[196:199], v[44:47]
	v_mfma_f32_16x16x32_bf16 v[40:43], v[140:143], v[196:199], v[40:43]
	v_mfma_f32_16x16x32_bf16 v[28:31], v[132:135], v[204:207], v[28:31]
	v_mfma_f32_16x16x32_bf16 v[24:27], v[140:143], v[204:207], v[24:27]
	v_mfma_f32_16x16x32_bf16 v[12:15], v[132:135], v[218:221], v[12:15]
	v_mfma_f32_16x16x32_bf16 v[8:11], v[140:143], v[218:221], v[8:11]
	s_barrier
	s_setprio 0
	s_add_u32 s34, s34, 0x80080
	s_addc_u32 s35, s35, 0
	s_add_i32 s27, s38, s4
	s_mov_b32 m0, s27
	s_nop 0
	global_load_lds_dwordx4 v162, s[34:35]
	s_add_i32 m0, s27, 0x2000
	s_nop 0
	global_load_lds_dwordx4 v166, s[34:35]
	s_waitcnt vmcnt(6)
	s_setprio 1
	s_barrier
	v_mfma_f32_16x16x32_bf16 v[52:55], v[222:225], v[144:147], v[52:55]
	v_mfma_f32_16x16x32_bf16 v[48:51], v[230:233], v[144:147], v[48:51]
	v_mfma_f32_16x16x32_bf16 v[36:39], v[222:225], v[192:195], v[36:39]
	v_mfma_f32_16x16x32_bf16 v[32:35], v[230:233], v[192:195], v[32:35]
	v_mfma_f32_16x16x32_bf16 v[20:23], v[222:225], v[200:203], v[20:23]
	v_mfma_f32_16x16x32_bf16 v[16:19], v[230:233], v[200:203], v[16:19]
	v_mfma_f32_16x16x32_bf16 v[4:7], v[222:225], v[214:217], v[4:7]
	v_mfma_f32_16x16x32_bf16 v[0:3], v[230:233], v[214:217], v[0:3]
	v_mfma_f32_16x16x32_bf16 v[52:55], v[226:229], v[148:151], v[52:55]
	v_mfma_f32_16x16x32_bf16 v[48:51], v[234:237], v[148:151], v[48:51]
	v_mfma_f32_16x16x32_bf16 v[36:39], v[226:229], v[196:199], v[36:39]
	v_mfma_f32_16x16x32_bf16 v[32:35], v[234:237], v[196:199], v[32:35]
	v_mfma_f32_16x16x32_bf16 v[20:23], v[226:229], v[204:207], v[20:23]
	v_mfma_f32_16x16x32_bf16 v[16:19], v[234:237], v[204:207], v[16:19]
	v_mfma_f32_16x16x32_bf16 v[4:7], v[226:229], v[218:221], v[4:7]
	v_mfma_f32_16x16x32_bf16 v[0:3], v[234:237], v[218:221], v[0:3]
	s_barrier
	s_setprio 0
	s_add_u32 s13, s13, 0x100
	s_addc_u32 s17, s17, 0
	s_add_u32 s30, s30, 0x10000
	s_addc_u32 s31, s31, 0
	s_cmp_ge_i32 s29, s1
	s_mov_b32 s27, s29
	s_cbranch_scc0 .LBB0_1658
	s_branch .LBB0_1662

;     __device__ bool next(int i, Unit& u) const { const int L = i * G + c; if (L >= 64 * 9) return false; u.pm = L; u.pn = L / 9; u.kt0 = 0; u.nt = ntf; u.ks = 0; return true; }
; #define PG8_STAGE(bufoff, gbase, voff) do { _Pragma("unroll") for (int _i = 0; _i < 2; ++_i) \
;         __builtin_amdgcn_global_load_lds((const unsigned*)((const char*)(gbase) + (voff)[_i]), (LAS unsigned*)(lds + (bufoff) + ldsw + _i * 8192), 16, 0, 0); } while (0)
; #define PG8_LDA(dst, b, h) do { _Pragma("unroll") for (int m = 0; m < 4; ++m) _Pragma("unroll") for (int k = 0; k < 2; ++k) dst[m][k] = *(const LAS bf16x8*)(lds + PG8_SA(b, h) + aoff + m * 2048 + k * 1024); } while (0)
; #define PG8_LDB(dst, b, h) do { _Pragma("unroll") for (int n = 0; n < 2; ++n) _Pragma("unroll") for (int k = 0; k < 2; ++k) dst[n][k] = *(const LAS bf16x8*)(lds + PG8_SB(b, h) + boff + n * 2048 + k * 1024); } while (0)
; template <class Epi, class Sched, bool ATILE = false>
; __device__ __forceinline__ void gemm_phase(LAS unsigned char* lds, const Gemm g, const Sched& S, const Epi& E) {
;     ...
;         const bool has_next = S.next(ui + 1, nxt);
;         const char* nA = has_next ? (const char*)g.A + (size_t)nxt.pm * tstepA + (size_t)nxt.kt0 * kstepA : cA; const char* nB = has_next ? (const char*)g.Bt + (size_t)nxt.pn * tstepB + (size_t)nxt.kt0 * kstep : cB;
;         int nt = cur.nt; asm volatile("" : "+s"(nt));
;         for (int t = 0; t < nt; t += 2) {
;             const bool last = (t == nt - 2);
;             const char* a1 = cA + (size_t)(t + 1) * kstepA;
;             const char* a2 = last ? nA : cA + (size_t)(t + 2) * kstepA; const char* b2 = last ? nB : cB + (size_t)(t + 2) * kstep;
;             const char* a3 = a2 + kstepA; const char* b3 = b2 + kstep;
;             PG8_LDB(B0, 0, 0); PG8_SCHED; PG8_LDA(At, 0, 0); PG8_STAGE(PG8_SA(1, 1), a1 + hstepA, voffA);
;             PG8_WAIT_L(8); PG8_BAR; PG8_WAIT_L(0); PG8_MMA(0, 0, At, B0); PG8_BAR; PG8_SCHED;
;             PG8_LDB(B1, 0, 1); PG8_STAGE(PG8_SB(0, 0), b2, voffB);
;             PG8_BAR; PG8_WAIT_L(0); PG8_MMA(0, 1, At, B1); PG8_BAR;
;             PG8_LDA(At, 0, 1); PG8_STAGE(PG8_SA(0, 0), a2, voffA);
;             PG8_BAR; PG8_WAIT_L(0); PG8_MMA(1, 0, At, B0); PG8_BAR; PG8_SCHED;
;             PG8_STAGE(PG8_SB(0, 1), b2 + hstepB, voffB);
;             PG8_WAIT_V(6); PG8_BAR; PG8_MMA(1, 1, At, B1); PG8_BAR;
.LBB0_1812:
	ds_read_b128 v[176:179], v139
	ds_read_b128 v[180:183], v139 offset:1024
	ds_read_b128 v[184:187], v139 offset:2048
	ds_read_b128 v[188:191], v139 offset:3072
	s_add_i32 s34, s8, 2
	s_add_u32 s9, s6, 0xfff80080
	s_addc_u32 s10, s7, -1
	s_cmp_eq_u32 s19, s8
	s_cselect_b32 s8, s18, s25
	s_cselect_b32 s11, s13, s10
	s_cselect_b32 s10, s16, s9
	s_cselect_b32 s9, s17, s27
	s_add_i32 m0, s37, 0xc000
	ds_read_b128 v[192:195], v159
	ds_read_b128 v[196:199], v159 offset:1024
	ds_read_b128 v[200:203], v159 offset:2048
	ds_read_b128 v[204:207], v159 offset:3072
	ds_read_b128 v[208:211], v159 offset:4096
	ds_read_b128 v[212:215], v159 offset:5120
	ds_read_b128 v[216:219], v159 offset:6144
	ds_read_b128 v[220:223], v159 offset:7168
	global_load_lds_dwordx4 v164, s[6:7]
	s_add_i32 m0, s37, 0xe000
	s_nop 0
	global_load_lds_dwordx4 v166, s[6:7]
	s_waitcnt lgkmcnt(8)
	s_setprio 1
	s_barrier
	s_waitcnt lgkmcnt(0)
	v_mfma_f32_16x16x32_bf16 v[120:123], v[176:179], v[192:195], v[120:123]
	v_mfma_f32_16x16x32_bf16 v[112:115], v[184:187], v[192:195], v[112:115]
	v_mfma_f32_16x16x32_bf16 v[104:107], v[176:179], v[200:203], v[104:107]
	v_mfma_f32_16x16x32_bf16 v[96:99], v[184:187], v[200:203], v[96:99]
	v_mfma_f32_16x16x32_bf16 v[88:91], v[176:179], v[208:211], v[88:91]
	v_mfma_f32_16x16x32_bf16 v[80:83], v[184:187], v[208:211], v[80:83]
	v_mfma_f32_16x16x32_bf16 v[72:75], v[176:179], v[216:219], v[72:75]
	v_mfma_f32_16x16x32_bf16 v[64:67], v[184:187], v[216:219], v[64:67]
	v_mfma_f32_16x16x32_bf16 v[120:123], v[180:183], v[196:199], v[120:123]
	v_mfma_f32_16x16x32_bf16 v[112:115], v[188:191], v[196:199], v[112:115]
	v_mfma_f32_16x16x32_bf16 v[104:107], v[180:183], v[204:207], v[104:107]
	v_mfma_f32_16x16x32_bf16 v[96:99], v[188:191], v[204:207], v[96:99]
	v_mfma_f32_16x16x32_bf16 v[88:91], v[180:183], v[212:215], v[88:91]
	v_mfma_f32_16x16x32_bf16 v[80:83], v[188:191], v[212:215], v[80:83]
	v_mfma_f32_16x16x32_bf16 v[72:75], v[180:183], v[220:223], v[72:75]
	v_mfma_f32_16x16x32_bf16 v[64:67], v[188:191], v[220:223], v[64:67]
	s_barrier
	s_setprio 0
	s_add_i32 s35, s51, s36
	s_add_u32 s98, s8, s22
	s_addc_u32 s99, s9, s23
	s_mov_b32 m0, s35
	ds_read_b128 v[224:227], v173
	ds_read_b128 v[228:231], v173 offset:1024
	ds_read_b128 v[232:235], v173 offset:2048
	ds_read_b128 v[236:239], v173 offset:3072
	global_load_lds_dwordx4 v130, s[8:9]
	s_add_i32 m0, s35, 0x2000
	s_nop 0
	global_load_lds_dwordx4 v134, s[8:9]
	s_setprio 1
	s_barrier
	s_waitcnt lgkmcnt(0)
	v_mfma_f32_16x16x32_bf16 v[124:127], v[224:227], v[192:195], v[124:127]
	v_mfma_f32_16x16x32_bf16 v[116:119], v[232:235], v[192:195], v[116:119]
	v_mfma_f32_16x16x32_bf16 v[108:111], v[224:227], v[200:203], v[108:111]
	v_mfma_f32_16x16x32_bf16 v[100:103], v[232:235], v[200:203], v[100:103]
	v_mfma_f32_16x16x32_bf16 v[92:95], v[224:227], v[208:211], v[92:95]
	v_mfma_f32_16x16x32_bf16 v[84:87], v[232:235], v[208:211], v[84:87]
	v_mfma_f32_16x16x32_bf16 v[76:79], v[224:227], v[216:219], v[76:79]
	v_mfma_f32_16x16x32_bf16 v[68:71], v[232:235], v[216:219], v[68:71]
	v_mfma_f32_16x16x32_bf16 v[124:127], v[228:231], v[196:199], v[124:127]
	v_mfma_f32_16x16x32_bf16 v[116:119], v[236:239], v[196:199], v[116:119]
	v_mfma_f32_16x16x32_bf16 v[108:111], v[228:231], v[204:207], v[108:111]
	v_mfma_f32_16x16x32_bf16 v[100:103], v[236:239], v[204:207], v[100:103]
	v_mfma_f32_16x16x32_bf16 v[92:95], v[228:231], v[212:215], v[92:95]
	v_mfma_f32_16x16x32_bf16 v[84:87], v[236:239], v[212:215], v[84:87]
	v_mfma_f32_16x16x32_bf16 v[76:79], v[228:231], v[220:223], v[76:79]
	v_mfma_f32_16x16x32_bf16 v[68:71], v[236:239], v[220:223], v[68:71]
	s_barrier
	s_setprio 0
	s_mov_b32 m0, s37
	s_add_u32 s100, s10, s22
	s_addc_u32 s101, s11, s23
	ds_read_b128 v[192:195], v159 offset:16384
	ds_read_b128 v[196:199], v159 offset:17408
	ds_read_b128 v[200:203], v159 offset:18432
	ds_read_b128 v[204:207], v159 offset:19456
	ds_read_b128 v[208:211], v159 offset:20480
	ds_read_b128 v[212:215], v159 offset:21504
	ds_read_b128 v[216:219], v159 offset:22528
	ds_read_b128 v[220:223], v159 offset:23552
	global_load_lds_dwordx4 v128, s[10:11]
	s_mov_b32 m0, s38
	s_nop 0
	global_load_lds_dwordx4 v132, s[10:11]
	s_setprio 1
	s_barrier
	s_waitcnt lgkmcnt(0)
	v_mfma_f32_16x16x32_bf16 v[56:59], v[176:179], v[192:195], v[56:59]
	v_mfma_f32_16x16x32_bf16 v[48:51], v[184:187], v[192:195], v[48:51]
	v_mfma_f32_16x16x32_bf16 v[40:43], v[176:179], v[200:203], v[40:43]
	v_mfma_f32_16x16x32_bf16 v[32:35], v[184:187], v[200:203], v[32:35]
	v_mfma_f32_16x16x32_bf16 v[24:27], v[176:179], v[208:211], v[24:27]
	v_mfma_f32_16x16x32_bf16 v[16:19], v[184:187], v[208:211], v[16:19]
	v_mfma_f32_16x16x32_bf16 v[8:11], v[176:179], v[216:219], v[8:11]
	v_mfma_f32_16x16x32_bf16 v[4:7], v[184:187], v[216:219], v[4:7]
	v_mfma_f32_16x16x32_bf16 v[56:59], v[180:183], v[196:199], v[56:59]
	v_mfma_f32_16x16x32_bf16 v[48:51], v[188:191], v[196:199], v[48:51]
	v_mfma_f32_16x16x32_bf16 v[40:43], v[180:183], v[204:207], v[40:43]
	v_mfma_f32_16x16x32_bf16 v[32:35], v[188:191], v[204:207], v[32:35]
	v_mfma_f32_16x16x32_bf16 v[24:27], v[180:183], v[212:215], v[24:27]
	v_mfma_f32_16x16x32_bf16 v[16:19], v[188:191], v[212:215], v[16:19]
	v_mfma_f32_16x16x32_bf16 v[8:11], v[180:183], v[220:223], v[8:11]
	v_mfma_f32_16x16x32_bf16 v[4:7], v[188:191], v[220:223], v[4:7]
	s_barrier
	s_setprio 0
	s_add_u32 s54, s8, 0x80000
	s_addc_u32 s55, s9, 0
	s_add_i32 s35, s52, s36
	s_mov_b32 m0, s35
	s_nop 0
	global_load_lds_dwordx4 v130, s[54:55]
	s_add_i32 m0, s35, 0x2000
	s_nop 0
	global_load_lds_dwordx4 v134, s[54:55]
	s_waitcnt vmcnt(6)
	s_setprio 1
	s_barrier
; #define PG8_STAGE(bufoff, gbase, voff) do { _Pragma("unroll") for (int _i = 0; _i < 2; ++_i) \
;         __builtin_amdgcn_global_load_lds((const unsigned*)((const char*)(gbase) + (voff)[_i]), (LAS unsigned*)(lds + (bufoff) + ldsw + _i * 8192), 16, 0, 0); } while (0)
; #define PG8_LDA(dst, b, h) do { _Pragma("unroll") for (int m = 0; m < 4; ++m) _Pragma("unroll") for (int k = 0; k < 2; ++k) dst[m][k] = *(const LAS bf16x8*)(lds + PG8_SA(b, h) + aoff + m * 2048 + k * 1024); } while (0)
; #define PG8_LDB(dst, b, h) do { _Pragma("unroll") for (int n = 0; n < 2; ++n) _Pragma("unroll") for (int k = 0; k < 2; ++k) dst[n][k] = *(const LAS bf16x8*)(lds + PG8_SB(b, h) + boff + n * 2048 + k * 1024); } while (0)
; #define PG8_MMA(ai, bj, At, Bt) do { __builtin_amdgcn_s_setprio(1); _Pragma("unroll") for (int m = 0; m < 4; ++m) _Pragma("unroll") for (int n = 0; n < 2; ++n) _Pragma("unroll") for (int k = 0; k < 2; ++k) \
;         acc[ai][bj][m][n] = __builtin_amdgcn_mfma_f32_16x16x32_bf16(Bt[n][k], At[m][k], acc[ai][bj][m][n], 0, 0, 0); __builtin_amdgcn_s_setprio(0); } while (0)
; #define PG8_WAIT_V(n) asm volatile("s_waitcnt vmcnt(" #n ")" ::: "memory")
; #define PG8_WAIT_L(n) asm volatile("s_waitcnt lgkmcnt(" #n ")" ::: "memory")
; #define PG8_BAR __builtin_amdgcn_s_barrier()
; #define PG8_SCHED __builtin_amdgcn_sched_barrier(0)
; template <class Epi, class Sched, bool ATILE = false>
; __device__ __forceinline__ void gemm_phase(LAS unsigned char* lds, const Gemm g, const Sched& S, const Epi& E) {
;     ...
;             PG8_WAIT_V(6); PG8_BAR; PG8_MMA(1, 1, At, B1); PG8_BAR;
;             PG8_LDB(B0, 1, 0); PG8_SCHED; PG8_LDA(At, 1, 0); PG8_STAGE(PG8_SA(0, 1), a2 + hstepA, voffA);
;             PG8_WAIT_L(8); PG8_BAR; PG8_WAIT_L(0); PG8_MMA(0, 0, At, B0); PG8_BAR; PG8_SCHED;
;             PG8_LDB(B1, 1, 1); PG8_STAGE(PG8_SB(1, 0), b3, voffB);
;             PG8_BAR; PG8_WAIT_L(0); PG8_MMA(0, 1, At, B1); PG8_BAR;
	v_mfma_f32_16x16x32_bf16 v[60:63], v[224:227], v[192:195], v[60:63]
	v_mfma_f32_16x16x32_bf16 v[52:55], v[232:235], v[192:195], v[52:55]
	v_mfma_f32_16x16x32_bf16 v[44:47], v[224:227], v[200:203], v[44:47]
	v_mfma_f32_16x16x32_bf16 v[36:39], v[232:235], v[200:203], v[36:39]
	v_mfma_f32_16x16x32_bf16 v[28:31], v[224:227], v[208:211], v[28:31]
	v_mfma_f32_16x16x32_bf16 v[20:23], v[232:235], v[208:211], v[20:23]
	v_mfma_f32_16x16x32_bf16 v[12:15], v[224:227], v[216:219], v[12:15]
	v_mfma_f32_16x16x32_bf16 v[0:3], v[232:235], v[216:219], v[0:3]
	v_mfma_f32_16x16x32_bf16 v[60:63], v[228:231], v[196:199], v[60:63]
	v_mfma_f32_16x16x32_bf16 v[52:55], v[236:239], v[196:199], v[52:55]
	v_mfma_f32_16x16x32_bf16 v[44:47], v[228:231], v[204:207], v[44:47]
	v_mfma_f32_16x16x32_bf16 v[36:39], v[236:239], v[204:207], v[36:39]
	v_mfma_f32_16x16x32_bf16 v[28:31], v[228:231], v[212:215], v[28:31]
	v_mfma_f32_16x16x32_bf16 v[20:23], v[236:239], v[212:215], v[20:23]
	v_mfma_f32_16x16x32_bf16 v[12:15], v[228:231], v[220:223], v[12:15]
	v_mfma_f32_16x16x32_bf16 v[0:3], v[236:239], v[220:223], v[0:3]
	s_barrier
	s_setprio 0
	s_add_i32 s35, 0, 0x18000
	v_add_u32_e32 v172, s35, v157
	ds_read_b128 v[176:179], v172
	ds_read_b128 v[180:183], v172 offset:1024
	ds_read_b128 v[184:187], v172 offset:2048
	ds_read_b128 v[188:191], v172 offset:3072
	s_add_u32 s10, s10, 0x80000
	s_addc_u32 s11, s11, 0
	s_mov_b32 m0, s39
	ds_read_b128 v[192:195], v159 offset:32768
	ds_read_b128 v[196:199], v159 offset:33792
	ds_read_b128 v[200:203], v159 offset:34816
	ds_read_b128 v[204:207], v159 offset:35840
	ds_read_b128 v[208:211], v159 offset:36864
	ds_read_b128 v[212:215], v159 offset:37888
	ds_read_b128 v[216:219], v159 offset:38912
	ds_read_b128 v[220:223], v159 offset:39936
	global_load_lds_dwordx4 v128, s[10:11]
	s_mov_b32 m0, s40
	s_nop 0
	global_load_lds_dwordx4 v132, s[10:11]
	s_waitcnt lgkmcnt(8)
	s_setprio 1
	s_barrier
	s_waitcnt lgkmcnt(0)
	v_mfma_f32_16x16x32_bf16 v[120:123], v[176:179], v[192:195], v[120:123]
	v_mfma_f32_16x16x32_bf16 v[112:115], v[184:187], v[192:195], v[112:115]
	v_mfma_f32_16x16x32_bf16 v[104:107], v[176:179], v[200:203], v[104:107]
	v_mfma_f32_16x16x32_bf16 v[96:99], v[184:187], v[200:203], v[96:99]
	v_mfma_f32_16x16x32_bf16 v[88:91], v[176:179], v[208:211], v[88:91]
	v_mfma_f32_16x16x32_bf16 v[80:83], v[184:187], v[208:211], v[80:83]
	v_mfma_f32_16x16x32_bf16 v[72:75], v[176:179], v[216:219], v[72:75]
	v_mfma_f32_16x16x32_bf16 v[64:67], v[184:187], v[216:219], v[64:67]
	v_mfma_f32_16x16x32_bf16 v[120:123], v[180:183], v[196:199], v[120:123]
	v_mfma_f32_16x16x32_bf16 v[112:115], v[188:191], v[196:199], v[112:115]
	v_mfma_f32_16x16x32_bf16 v[104:107], v[180:183], v[204:207], v[104:107]
	v_mfma_f32_16x16x32_bf16 v[96:99], v[188:191], v[204:207], v[96:99]
	v_mfma_f32_16x16x32_bf16 v[88:91], v[180:183], v[212:215], v[88:91]
	v_mfma_f32_16x16x32_bf16 v[80:83], v[188:191], v[212:215], v[80:83]
	v_mfma_f32_16x16x32_bf16 v[72:75], v[180:183], v[220:223], v[72:75]
	v_mfma_f32_16x16x32_bf16 v[64:67], v[188:191], v[220:223], v[64:67]
	s_barrier
	s_setprio 0
	s_add_i32 s10, 0, 0x1c000
	s_add_i32 s11, s35, s36
	v_add_u32_e32 v172, s10, v157
	s_mov_b32 m0, s11
	ds_read_b128 v[224:227], v172
	ds_read_b128 v[228:231], v172 offset:1024
	ds_read_b128 v[232:235], v172 offset:2048
	ds_read_b128 v[236:239], v172 offset:3072
	global_load_lds_dwordx4 v130, s[98:99]
	s_add_i32 m0, s11, 0x2000
	s_nop 0
	global_load_lds_dwordx4 v134, s[98:99]
	s_setprio 1
	s_barrier
; #define PG8_STAGE(bufoff, gbase, voff) do { _Pragma("unroll") for (int _i = 0; _i < 2; ++_i) \
;         __builtin_amdgcn_global_load_lds((const unsigned*)((const char*)(gbase) + (voff)[_i]), (LAS unsigned*)(lds + (bufoff) + ldsw + _i * 8192), 16, 0, 0); } while (0)
; #define PG8_LDA(dst, b, h) do { _Pragma("unroll") for (int m = 0; m < 4; ++m) _Pragma("unroll") for (int k = 0; k < 2; ++k) dst[m][k] = *(const LAS bf16x8*)(lds + PG8_SA(b, h) + aoff + m * 2048 + k * 1024); } while (0)
; #define PG8_MMA(ai, bj, At, Bt) do { __builtin_amdgcn_s_setprio(1); _Pragma("unroll") for (int m = 0; m < 4; ++m) _Pragma("unroll") for (int n = 0; n < 2; ++n) _Pragma("unroll") for (int k = 0; k < 2; ++k) \
;         acc[ai][bj][m][n] = __builtin_amdgcn_mfma_f32_16x16x32_bf16(Bt[n][k], At[m][k], acc[ai][bj][m][n], 0, 0, 0); __builtin_amdgcn_s_setprio(0); } while (0)
; #define PG8_WAIT_V(n) asm volatile("s_waitcnt vmcnt(" #n ")" ::: "memory")
; #define PG8_WAIT_L(n) asm volatile("s_waitcnt lgkmcnt(" #n ")" ::: "memory")
; #define PG8_BAR __builtin_amdgcn_s_barrier()
; #define PG8_SCHED __builtin_amdgcn_sched_barrier(0)
; template <class Epi, class Sched, bool ATILE = false>
; __device__ __forceinline__ void gemm_phase(LAS unsigned char* lds, const Gemm g, const Sched& S, const Epi& E) {
;     ...
;             PG8_BAR; PG8_WAIT_L(0); PG8_MMA(0, 1, At, B1); PG8_BAR;
;             PG8_LDA(At, 1, 1); PG8_STAGE(PG8_SA(1, 0), a3, voffA);
;             PG8_BAR; PG8_WAIT_L(0); PG8_MMA(1, 0, At, B0); PG8_BAR; PG8_SCHED;
;             PG8_STAGE(PG8_SB(1, 1), b3 + hstepB, voffB);
;             PG8_WAIT_V(6); PG8_BAR; PG8_MMA(1, 1, At, B1); PG8_BAR;
;         }
	s_waitcnt lgkmcnt(0)
	v_mfma_f32_16x16x32_bf16 v[124:127], v[224:227], v[192:195], v[124:127]
	v_mfma_f32_16x16x32_bf16 v[116:119], v[232:235], v[192:195], v[116:119]
	v_mfma_f32_16x16x32_bf16 v[108:111], v[224:227], v[200:203], v[108:111]
	v_mfma_f32_16x16x32_bf16 v[100:103], v[232:235], v[200:203], v[100:103]
	v_mfma_f32_16x16x32_bf16 v[92:95], v[224:227], v[208:211], v[92:95]
	v_mfma_f32_16x16x32_bf16 v[84:87], v[232:235], v[208:211], v[84:87]
	v_mfma_f32_16x16x32_bf16 v[76:79], v[224:227], v[216:219], v[76:79]
	v_mfma_f32_16x16x32_bf16 v[68:71], v[232:235], v[216:219], v[68:71]
	v_mfma_f32_16x16x32_bf16 v[124:127], v[228:231], v[196:199], v[124:127]
	v_mfma_f32_16x16x32_bf16 v[116:119], v[236:239], v[196:199], v[116:119]
	v_mfma_f32_16x16x32_bf16 v[108:111], v[228:231], v[204:207], v[108:111]
	v_mfma_f32_16x16x32_bf16 v[100:103], v[236:239], v[204:207], v[100:103]
	v_mfma_f32_16x16x32_bf16 v[92:95], v[228:231], v[212:215], v[92:95]
	v_mfma_f32_16x16x32_bf16 v[84:87], v[236:239], v[212:215], v[84:87]
	v_mfma_f32_16x16x32_bf16 v[76:79], v[228:231], v[220:223], v[76:79]
	v_mfma_f32_16x16x32_bf16 v[68:71], v[236:239], v[220:223], v[68:71]
	s_barrier
	s_setprio 0
	s_mov_b32 m0, s43
	ds_read_b128 v[192:195], v159 offset:49152
	ds_read_b128 v[196:199], v159 offset:50176
	ds_read_b128 v[200:203], v159 offset:51200
	ds_read_b128 v[204:207], v159 offset:52224
	ds_read_b128 v[208:211], v159 offset:53248
	ds_read_b128 v[212:215], v159 offset:54272
	ds_read_b128 v[216:219], v159 offset:55296
	ds_read_b128 v[220:223], v159 offset:56320
	global_load_lds_dwordx4 v128, s[100:101]
	s_mov_b32 m0, s44
	s_nop 0
	global_load_lds_dwordx4 v132, s[100:101]
	s_setprio 1
	s_barrier
	s_waitcnt lgkmcnt(0)
	v_mfma_f32_16x16x32_bf16 v[56:59], v[176:179], v[192:195], v[56:59]
	v_mfma_f32_16x16x32_bf16 v[48:51], v[184:187], v[192:195], v[48:51]
	v_mfma_f32_16x16x32_bf16 v[40:43], v[176:179], v[200:203], v[40:43]
	v_mfma_f32_16x16x32_bf16 v[32:35], v[184:187], v[200:203], v[32:35]
	v_mfma_f32_16x16x32_bf16 v[24:27], v[176:179], v[208:211], v[24:27]
	v_mfma_f32_16x16x32_bf16 v[16:19], v[184:187], v[208:211], v[16:19]
	v_mfma_f32_16x16x32_bf16 v[8:11], v[176:179], v[216:219], v[8:11]
	v_mfma_f32_16x16x32_bf16 v[4:7], v[184:187], v[216:219], v[4:7]
	v_mfma_f32_16x16x32_bf16 v[56:59], v[180:183], v[196:199], v[56:59]
	v_mfma_f32_16x16x32_bf16 v[48:51], v[188:191], v[196:199], v[48:51]
	v_mfma_f32_16x16x32_bf16 v[40:43], v[180:183], v[204:207], v[40:43]
	v_mfma_f32_16x16x32_bf16 v[32:35], v[188:191], v[204:207], v[32:35]
	v_mfma_f32_16x16x32_bf16 v[24:27], v[180:183], v[212:215], v[24:27]
	v_mfma_f32_16x16x32_bf16 v[16:19], v[188:191], v[212:215], v[16:19]
	v_mfma_f32_16x16x32_bf16 v[8:11], v[180:183], v[220:223], v[8:11]
	v_mfma_f32_16x16x32_bf16 v[4:7], v[188:191], v[220:223], v[4:7]
	s_barrier
	s_setprio 0
	s_add_u32 s8, s8, 0x80080
	s_addc_u32 s9, s9, 0
	s_add_i32 s10, s10, s36
	s_mov_b32 m0, s10
	s_nop 0
	global_load_lds_dwordx4 v130, s[8:9]
	s_add_i32 m0, s10, 0x2000
	s_nop 0
	global_load_lds_dwordx4 v134, s[8:9]
	s_waitcnt vmcnt(6)
	s_setprio 1
	s_barrier
	v_mfma_f32_16x16x32_bf16 v[60:63], v[224:227], v[192:195], v[60:63]
	v_mfma_f32_16x16x32_bf16 v[52:55], v[232:235], v[192:195], v[52:55]
	v_mfma_f32_16x16x32_bf16 v[44:47], v[224:227], v[200:203], v[44:47]
	v_mfma_f32_16x16x32_bf16 v[36:39], v[232:235], v[200:203], v[36:39]
	v_mfma_f32_16x16x32_bf16 v[28:31], v[224:227], v[208:211], v[28:31]
	v_mfma_f32_16x16x32_bf16 v[20:23], v[232:235], v[208:211], v[20:23]
	v_mfma_f32_16x16x32_bf16 v[12:15], v[224:227], v[216:219], v[12:15]
	v_mfma_f32_16x16x32_bf16 v[0:3], v[232:235], v[216:219], v[0:3]
	v_mfma_f32_16x16x32_bf16 v[60:63], v[228:231], v[196:199], v[60:63]
	v_mfma_f32_16x16x32_bf16 v[52:55], v[236:239], v[196:199], v[52:55]
	v_mfma_f32_16x16x32_bf16 v[44:47], v[228:231], v[204:207], v[44:47]
	v_mfma_f32_16x16x32_bf16 v[36:39], v[236:239], v[204:207], v[36:39]
	v_mfma_f32_16x16x32_bf16 v[28:31], v[228:231], v[212:215], v[28:31]
	v_mfma_f32_16x16x32_bf16 v[20:23], v[236:239], v[212:215], v[20:23]
	v_mfma_f32_16x16x32_bf16 v[12:15], v[228:231], v[220:223], v[12:15]
	v_mfma_f32_16x16x32_bf16 v[0:3], v[236:239], v[220:223], v[0:3]
	s_barrier
	s_setprio 0
	s_add_u32 s6, s6, 0x100
	s_addc_u32 s7, s7, 0
	s_add_u32 s25, s25, 0x100
	s_addc_u32 s27, s27, 0
	s_cmp_ge_i32 s34, s12
	s_mov_b32 s8, s34
	s_cbranch_scc0 .LBB0_1812
	s_branch .LBB0_1803

;     __device__ bool next(int i, Unit& u) const { const int L = i * G + c; if (L >= 64 * 9) return false; u.pm = L; u.pn = L / 9; u.kt0 = 0; u.nt = ntf; u.ks = 0; return true; }
; #define PG8_STAGE(bufoff, gbase, voff) do { _Pragma("unroll") for (int _i = 0; _i < 2; ++_i) \
;         __builtin_amdgcn_global_load_lds((const unsigned*)((const char*)(gbase) + (voff)[_i]), (LAS unsigned*)(lds + (bufoff) + ldsw + _i * 8192), 16, 0, 0); } while (0)
; #define PG8_LDA(dst, b, h) do { _Pragma("unroll") for (int m = 0; m < 4; ++m) _Pragma("unroll") for (int k = 0; k < 2; ++k) dst[m][k] = *(const LAS bf16x8*)(lds + PG8_SA(b, h) + aoff + m * 2048 + k * 1024); } while (0)
; #define PG8_LDB(dst, b, h) do { _Pragma("unroll") for (int n = 0; n < 2; ++n) _Pragma("unroll") for (int k = 0; k < 2; ++k) dst[n][k] = *(const LAS bf16x8*)(lds + PG8_SB(b, h) + boff + n * 2048 + k * 1024); } while (0)
; template <class Epi, class Sched, bool ATILE = false>
; __device__ __forceinline__ void gemm_phase(LAS unsigned char* lds, const Gemm g, const Sched& S, const Epi& E) {
;     ...
;         const bool has_next = S.next(ui + 1, nxt);
;         const char* nA = has_next ? (const char*)g.A + (size_t)nxt.pm * tstepA + (size_t)nxt.kt0 * kstepA : cA; const char* nB = has_next ? (const char*)g.Bt + (size_t)nxt.pn * tstepB + (size_t)nxt.kt0 * kstep : cB;
;         int nt = cur.nt; asm volatile("" : "+s"(nt));
;         for (int t = 0; t < nt; t += 2) {
;             const bool last = (t == nt - 2);
;             const char* a1 = cA + (size_t)(t + 1) * kstepA;
;             const char* a2 = last ? nA : cA + (size_t)(t + 2) * kstepA; const char* b2 = last ? nB : cB + (size_t)(t + 2) * kstep;
;             const char* a3 = a2 + kstepA; const char* b3 = b2 + kstep;
;             PG8_LDB(B0, 0, 0); PG8_SCHED; PG8_LDA(At, 0, 0); PG8_STAGE(PG8_SA(1, 1), a1 + hstepA, voffA);
;             PG8_WAIT_L(8); PG8_BAR; PG8_WAIT_L(0); PG8_MMA(0, 0, At, B0); PG8_BAR; PG8_SCHED;
;             PG8_LDB(B1, 0, 1); PG8_STAGE(PG8_SB(0, 0), b2, voffB);
;             PG8_BAR; PG8_WAIT_L(0); PG8_MMA(0, 1, At, B1); PG8_BAR;
;             PG8_LDA(At, 0, 1); PG8_STAGE(PG8_SA(0, 0), a2, voffA);
;             PG8_BAR; PG8_WAIT_L(0); PG8_MMA(1, 0, At, B0); PG8_BAR; PG8_SCHED;
;             PG8_STAGE(PG8_SB(0, 1), b2 + hstepB, voffB);
;             PG8_WAIT_V(6); PG8_BAR; PG8_MMA(1, 1, At, B1); PG8_BAR;
.LBB0_1898:
	ds_read_b128 v[20:23], v180
	ds_read_b128 v[28:31], v180 offset:1024
	ds_read_b128 v[174:177], v180 offset:2048
	ds_read_b128 v[184:187], v180 offset:3072
	s_add_i32 s58, s26, 2
	s_add_u32 s27, s24, 0x4000
	s_addc_u32 s28, s25, 0
	s_cmp_eq_u32 s17, s26
	s_cselect_b32 s30, s20, s27
	s_cselect_b32 s31, s21, s28
	s_cselect_b32 s26, s22, s56
	s_cselect_b32 s27, s23, s57
	s_add_u32 s28, s30, 0x8000
	s_addc_u32 s29, s31, 0
	s_add_i32 m0, s34, 0xc000
	ds_read_b128 v[188:191], v181
	ds_read_b128 v[192:195], v181 offset:1024
	ds_read_b128 v[196:199], v181 offset:2048
	ds_read_b128 v[200:203], v181 offset:3072
	ds_read_b128 v[204:207], v181 offset:4096
	ds_read_b128 v[208:211], v181 offset:5120
	ds_read_b128 v[212:215], v181 offset:6144
	ds_read_b128 v[216:219], v181 offset:7168
	global_load_lds_dwordx4 v168, s[24:25]
	s_add_i32 m0, s34, 0xe000
	s_nop 0
	global_load_lds_dwordx4 v170, s[24:25]
	s_waitcnt lgkmcnt(8)
	s_setprio 1
	s_barrier
	s_waitcnt lgkmcnt(0)
	v_mfma_f32_16x16x32_bf16 v[0:3], v[20:23], v[188:191], v[0:3]
	v_mfma_f32_16x16x32_bf16 v[4:7], v[174:177], v[188:191], v[4:7]
	v_mfma_f32_16x16x32_bf16 v[44:47], v[20:23], v[196:199], v[44:47]
	v_mfma_f32_16x16x32_bf16 v[36:39], v[174:177], v[196:199], v[36:39]
	v_mfma_f32_16x16x32_bf16 v[52:55], v[20:23], v[204:207], v[52:55]
	v_mfma_f32_16x16x32_bf16 v[48:51], v[174:177], v[204:207], v[48:51]
	v_mfma_f32_16x16x32_bf16 v[92:95], v[20:23], v[212:215], v[92:95]
	v_mfma_f32_16x16x32_bf16 v[84:87], v[174:177], v[212:215], v[84:87]
	v_mfma_f32_16x16x32_bf16 v[0:3], v[28:31], v[192:195], v[0:3]
	v_mfma_f32_16x16x32_bf16 v[4:7], v[184:187], v[192:195], v[4:7]
	v_mfma_f32_16x16x32_bf16 v[44:47], v[28:31], v[200:203], v[44:47]
	v_mfma_f32_16x16x32_bf16 v[36:39], v[184:187], v[200:203], v[36:39]
	v_mfma_f32_16x16x32_bf16 v[52:55], v[28:31], v[208:211], v[52:55]
	v_mfma_f32_16x16x32_bf16 v[48:51], v[184:187], v[208:211], v[48:51]
	v_mfma_f32_16x16x32_bf16 v[92:95], v[28:31], v[216:219], v[92:95]
	v_mfma_f32_16x16x32_bf16 v[84:87], v[184:187], v[216:219], v[84:87]
	s_barrier
	s_setprio 0
	s_add_i32 s59, s44, s33
	s_add_u32 s98, s26, s4
	s_addc_u32 s99, s27, s5
	s_mov_b32 m0, s59
	ds_read_b128 v[220:223], v182
	ds_read_b128 v[224:227], v182 offset:1024
	ds_read_b128 v[228:231], v182 offset:2048
	ds_read_b128 v[232:235], v182 offset:3072
	global_load_lds_dwordx4 v138, s[26:27]
	s_add_i32 m0, s59, 0x2000
	s_nop 0
	global_load_lds_dwordx4 v142, s[26:27]
	s_setprio 1
	s_barrier
	s_waitcnt lgkmcnt(0)
	v_mfma_f32_16x16x32_bf16 v[12:15], v[220:223], v[188:191], v[12:15]
	v_mfma_f32_16x16x32_bf16 v[8:11], v[228:231], v[188:191], v[8:11]
	v_mfma_f32_16x16x32_bf16 v[24:27], v[220:223], v[196:199], v[24:27]
	v_mfma_f32_16x16x32_bf16 v[16:19], v[228:231], v[196:199], v[16:19]
	v_mfma_f32_16x16x32_bf16 v[40:43], v[220:223], v[204:207], v[40:43]
	v_mfma_f32_16x16x32_bf16 v[32:35], v[228:231], v[204:207], v[32:35]
	v_mfma_f32_16x16x32_bf16 v[56:59], v[220:223], v[212:215], v[56:59]
	v_mfma_f32_16x16x32_bf16 v[60:63], v[228:231], v[212:215], v[60:63]
	v_mfma_f32_16x16x32_bf16 v[12:15], v[224:227], v[192:195], v[12:15]
	v_mfma_f32_16x16x32_bf16 v[8:11], v[232:235], v[192:195], v[8:11]
	v_mfma_f32_16x16x32_bf16 v[24:27], v[224:227], v[200:203], v[24:27]
	v_mfma_f32_16x16x32_bf16 v[16:19], v[232:235], v[200:203], v[16:19]
	v_mfma_f32_16x16x32_bf16 v[40:43], v[224:227], v[208:211], v[40:43]
	v_mfma_f32_16x16x32_bf16 v[32:35], v[232:235], v[208:211], v[32:35]
	v_mfma_f32_16x16x32_bf16 v[56:59], v[224:227], v[216:219], v[56:59]
	v_mfma_f32_16x16x32_bf16 v[60:63], v[232:235], v[216:219], v[60:63]
	s_barrier
	s_setprio 0
	s_mov_b32 m0, s34
	ds_read_b128 v[188:191], v181 offset:16384
	ds_read_b128 v[192:195], v181 offset:17408
	ds_read_b128 v[196:199], v181 offset:18432
	ds_read_b128 v[200:203], v181 offset:19456
	ds_read_b128 v[204:207], v181 offset:20480
	ds_read_b128 v[208:211], v181 offset:21504
	ds_read_b128 v[212:215], v181 offset:22528
	ds_read_b128 v[216:219], v181 offset:23552
	global_load_lds_dwordx4 v136, s[30:31]
	s_mov_b32 m0, s35
	s_nop 0
	global_load_lds_dwordx4 v140, s[30:31]
	s_setprio 1
	s_barrier
	s_waitcnt lgkmcnt(0)
	v_mfma_f32_16x16x32_bf16 v[64:67], v[20:23], v[188:191], v[64:67]
	v_mfma_f32_16x16x32_bf16 v[68:71], v[174:177], v[188:191], v[68:71]
	v_mfma_f32_16x16x32_bf16 v[108:111], v[20:23], v[196:199], v[108:111]
	v_mfma_f32_16x16x32_bf16 v[100:103], v[174:177], v[196:199], v[100:103]
	v_mfma_f32_16x16x32_bf16 v[116:119], v[20:23], v[204:207], v[116:119]
	v_mfma_f32_16x16x32_bf16 v[112:115], v[174:177], v[204:207], v[112:115]
	v_mfma_f32_16x16x32_bf16 v[20:23], v[20:23], v[212:215], v[132:135]
	v_mfma_f32_16x16x32_bf16 v[64:67], v[28:31], v[192:195], v[64:67]
	v_mfma_f32_16x16x32_bf16 v[68:71], v[184:187], v[192:195], v[68:71]
	v_mfma_f32_16x16x32_bf16 v[108:111], v[28:31], v[200:203], v[108:111]
	v_mfma_f32_16x16x32_bf16 v[100:103], v[184:187], v[200:203], v[100:103]
	v_mfma_f32_16x16x32_bf16 v[116:119], v[28:31], v[208:211], v[116:119]
	v_mfma_f32_16x16x32_bf16 v[112:115], v[184:187], v[208:211], v[112:115]
	v_mfma_f32_16x16x32_bf16 v[20:23], v[28:31], v[216:219], v[20:23]
	v_mfma_f32_16x16x32_bf16 v[28:31], v[174:177], v[212:215], v[128:131]
	v_mfma_f32_16x16x32_bf16 v[28:31], v[184:187], v[216:219], v[28:31]
	s_barrier
	s_setprio 0
	s_add_u32 s60, s26, 0x158000
	s_addc_u32 s61, s27, 0
	s_add_i32 s59, s45, s33
	s_mov_b32 m0, s59
	s_nop 0
	global_load_lds_dwordx4 v138, s[60:61]
	s_add_i32 m0, s59, 0x2000
	s_nop 0
	global_load_lds_dwordx4 v142, s[60:61]
	s_waitcnt vmcnt(6)
	s_setprio 1
	s_barrier
; #define PG8_STAGE(bufoff, gbase, voff) do { _Pragma("unroll") for (int _i = 0; _i < 2; ++_i) \
;         __builtin_amdgcn_global_load_lds((const unsigned*)((const char*)(gbase) + (voff)[_i]), (LAS unsigned*)(lds + (bufoff) + ldsw + _i * 8192), 16, 0, 0); } while (0)
; #define PG8_LDA(dst, b, h) do { _Pragma("unroll") for (int m = 0; m < 4; ++m) _Pragma("unroll") for (int k = 0; k < 2; ++k) dst[m][k] = *(const LAS bf16x8*)(lds + PG8_SA(b, h) + aoff + m * 2048 + k * 1024); } while (0)
; #define PG8_LDB(dst, b, h) do { _Pragma("unroll") for (int n = 0; n < 2; ++n) _Pragma("unroll") for (int k = 0; k < 2; ++k) dst[n][k] = *(const LAS bf16x8*)(lds + PG8_SB(b, h) + boff + n * 2048 + k * 1024); } while (0)
; #define PG8_MMA(ai, bj, At, Bt) do { __builtin_amdgcn_s_setprio(1); _Pragma("unroll") for (int m = 0; m < 4; ++m) _Pragma("unroll") for (int n = 0; n < 2; ++n) _Pragma("unroll") for (int k = 0; k < 2; ++k) \
;         acc[ai][bj][m][n] = __builtin_amdgcn_mfma_f32_16x16x32_bf16(Bt[n][k], At[m][k], acc[ai][bj][m][n], 0, 0, 0); __builtin_amdgcn_s_setprio(0); } while (0)
; #define PG8_WAIT_V(n) asm volatile("s_waitcnt vmcnt(" #n ")" ::: "memory")
; #define PG8_WAIT_L(n) asm volatile("s_waitcnt lgkmcnt(" #n ")" ::: "memory")
; #define PG8_BAR __builtin_amdgcn_s_barrier()
; #define PG8_SCHED __builtin_amdgcn_sched_barrier(0)
; template <class Epi, class Sched, bool ATILE = false>
; __device__ __forceinline__ void gemm_phase(LAS unsigned char* lds, const Gemm g, const Sched& S, const Epi& E) {
;     ...
;             PG8_WAIT_V(6); PG8_BAR; PG8_MMA(1, 1, At, B1); PG8_BAR;
;             PG8_LDB(B0, 1, 0); PG8_SCHED; PG8_LDA(At, 1, 0); PG8_STAGE(PG8_SA(0, 1), a2 + hstepA, voffA);
;             PG8_WAIT_L(8); PG8_BAR; PG8_WAIT_L(0); PG8_MMA(0, 0, At, B0); PG8_BAR; PG8_SCHED;
;             PG8_LDB(B1, 1, 1); PG8_STAGE(PG8_SB(1, 0), b3, voffB);
;             PG8_BAR; PG8_WAIT_L(0); PG8_MMA(0, 1, At, B1); PG8_BAR;
;             PG8_LDA(At, 1, 1); PG8_STAGE(PG8_SA(1, 0), a3, voffA);
;             PG8_BAR; PG8_WAIT_L(0); PG8_MMA(1, 0, At, B0); PG8_BAR; PG8_SCHED;
	v_mfma_f32_16x16x32_bf16 v[76:79], v[220:223], v[188:191], v[76:79]
	v_mfma_f32_16x16x32_bf16 v[72:75], v[228:231], v[188:191], v[72:75]
	v_mfma_f32_16x16x32_bf16 v[88:91], v[220:223], v[196:199], v[88:91]
	v_mfma_f32_16x16x32_bf16 v[80:83], v[228:231], v[196:199], v[80:83]
	v_mfma_f32_16x16x32_bf16 v[104:107], v[220:223], v[204:207], v[104:107]
	v_mfma_f32_16x16x32_bf16 v[96:99], v[228:231], v[204:207], v[96:99]
	v_mfma_f32_16x16x32_bf16 v[120:123], v[220:223], v[212:215], v[120:123]
	v_mfma_f32_16x16x32_bf16 v[124:127], v[228:231], v[212:215], v[124:127]
	v_mfma_f32_16x16x32_bf16 v[76:79], v[224:227], v[192:195], v[76:79]
	v_mfma_f32_16x16x32_bf16 v[72:75], v[232:235], v[192:195], v[72:75]
	v_mfma_f32_16x16x32_bf16 v[88:91], v[224:227], v[200:203], v[88:91]
	v_mfma_f32_16x16x32_bf16 v[80:83], v[232:235], v[200:203], v[80:83]
	v_mfma_f32_16x16x32_bf16 v[104:107], v[224:227], v[208:211], v[104:107]
	v_mfma_f32_16x16x32_bf16 v[96:99], v[232:235], v[208:211], v[96:99]
	v_mfma_f32_16x16x32_bf16 v[120:123], v[224:227], v[216:219], v[120:123]
	v_mfma_f32_16x16x32_bf16 v[124:127], v[232:235], v[216:219], v[124:127]
	s_barrier
	s_setprio 0
	s_add_i32 s59, 0, 0x18000
	v_add_u32_e32 v183, s59, v157
	ds_read_b128 v[128:131], v183
	ds_read_b128 v[132:135], v183 offset:1024
	ds_read_b128 v[174:177], v183 offset:2048
	ds_read_b128 v[184:187], v183 offset:3072
	s_add_u32 s30, s30, 0x4000
	s_addc_u32 s31, s31, 0
	s_mov_b32 m0, s36
	ds_read_b128 v[188:191], v181 offset:32768
	ds_read_b128 v[192:195], v181 offset:33792
	ds_read_b128 v[196:199], v181 offset:34816
	ds_read_b128 v[200:203], v181 offset:35840
	ds_read_b128 v[204:207], v181 offset:36864
	ds_read_b128 v[208:211], v181 offset:37888
	ds_read_b128 v[212:215], v181 offset:38912
	ds_read_b128 v[216:219], v181 offset:39936
	global_load_lds_dwordx4 v136, s[30:31]
	s_mov_b32 m0, s37
	s_nop 0
	global_load_lds_dwordx4 v140, s[30:31]
	s_waitcnt lgkmcnt(8)
	s_setprio 1
	s_barrier
	s_waitcnt lgkmcnt(0)
	v_mfma_f32_16x16x32_bf16 v[0:3], v[128:131], v[188:191], v[0:3]
	v_mfma_f32_16x16x32_bf16 v[4:7], v[174:177], v[188:191], v[4:7]
	v_mfma_f32_16x16x32_bf16 v[44:47], v[128:131], v[196:199], v[44:47]
	v_mfma_f32_16x16x32_bf16 v[36:39], v[174:177], v[196:199], v[36:39]
	v_mfma_f32_16x16x32_bf16 v[52:55], v[128:131], v[204:207], v[52:55]
	v_mfma_f32_16x16x32_bf16 v[48:51], v[174:177], v[204:207], v[48:51]
	v_mfma_f32_16x16x32_bf16 v[92:95], v[128:131], v[212:215], v[92:95]
	v_mfma_f32_16x16x32_bf16 v[84:87], v[174:177], v[212:215], v[84:87]
	v_mfma_f32_16x16x32_bf16 v[0:3], v[132:135], v[192:195], v[0:3]
	v_mfma_f32_16x16x32_bf16 v[4:7], v[184:187], v[192:195], v[4:7]
	v_mfma_f32_16x16x32_bf16 v[44:47], v[132:135], v[200:203], v[44:47]
	v_mfma_f32_16x16x32_bf16 v[36:39], v[184:187], v[200:203], v[36:39]
	v_mfma_f32_16x16x32_bf16 v[52:55], v[132:135], v[208:211], v[52:55]
	v_mfma_f32_16x16x32_bf16 v[48:51], v[184:187], v[208:211], v[48:51]
	v_mfma_f32_16x16x32_bf16 v[92:95], v[132:135], v[216:219], v[92:95]
	v_mfma_f32_16x16x32_bf16 v[84:87], v[184:187], v[216:219], v[84:87]
	s_barrier
	s_setprio 0
	s_add_i32 s30, 0, 0x1c000
	s_add_i32 s31, s59, s33
	v_add_u32_e32 v183, s30, v157
	s_mov_b32 m0, s31
	ds_read_b128 v[220:223], v183
	ds_read_b128 v[224:227], v183 offset:1024
	ds_read_b128 v[228:231], v183 offset:2048
	ds_read_b128 v[232:235], v183 offset:3072
	global_load_lds_dwordx4 v138, s[98:99]
	s_add_i32 m0, s31, 0x2000
	s_nop 0
	global_load_lds_dwordx4 v142, s[98:99]
	s_setprio 1
	s_barrier
	s_waitcnt lgkmcnt(0)
	v_mfma_f32_16x16x32_bf16 v[12:15], v[220:223], v[188:191], v[12:15]
	v_mfma_f32_16x16x32_bf16 v[8:11], v[228:231], v[188:191], v[8:11]
	v_mfma_f32_16x16x32_bf16 v[24:27], v[220:223], v[196:199], v[24:27]
	v_mfma_f32_16x16x32_bf16 v[16:19], v[228:231], v[196:199], v[16:19]
	v_mfma_f32_16x16x32_bf16 v[40:43], v[220:223], v[204:207], v[40:43]
	v_mfma_f32_16x16x32_bf16 v[32:35], v[228:231], v[204:207], v[32:35]
	v_mfma_f32_16x16x32_bf16 v[56:59], v[220:223], v[212:215], v[56:59]
	v_mfma_f32_16x16x32_bf16 v[60:63], v[228:231], v[212:215], v[60:63]
	v_mfma_f32_16x16x32_bf16 v[12:15], v[224:227], v[192:195], v[12:15]
	v_mfma_f32_16x16x32_bf16 v[8:11], v[232:235], v[192:195], v[8:11]
	v_mfma_f32_16x16x32_bf16 v[24:27], v[224:227], v[200:203], v[24:27]
	v_mfma_f32_16x16x32_bf16 v[16:19], v[232:235], v[200:203], v[16:19]
	v_mfma_f32_16x16x32_bf16 v[40:43], v[224:227], v[208:211], v[40:43]
	v_mfma_f32_16x16x32_bf16 v[32:35], v[232:235], v[208:211], v[32:35]
	v_mfma_f32_16x16x32_bf16 v[56:59], v[224:227], v[216:219], v[56:59]
	v_mfma_f32_16x16x32_bf16 v[60:63], v[232:235], v[216:219], v[60:63]
	s_barrier
	s_setprio 0
	s_mov_b32 m0, s39
	ds_read_b128 v[188:191], v181 offset:49152
	ds_read_b128 v[192:195], v181 offset:50176
	ds_read_b128 v[196:199], v181 offset:51200
	ds_read_b128 v[200:203], v181 offset:52224
	ds_read_b128 v[204:207], v181 offset:53248
	ds_read_b128 v[208:211], v181 offset:54272
	ds_read_b128 v[212:215], v181 offset:55296
	ds_read_b128 v[216:219], v181 offset:56320
	global_load_lds_dwordx4 v136, s[28:29]
	s_mov_b32 m0, s40
	s_nop 0
	global_load_lds_dwordx4 v140, s[28:29]
	s_setprio 1
	s_barrier
; __device__ __forceinline__ float bflo(unsigned w) { return __uint_as_float(w << 16); }
; __device__ __forceinline__ float bfhi(unsigned w) { return __uint_as_float(w & 0xffff0000u); }
; #define PG8_STAGE(bufoff, gbase, voff) do { _Pragma("unroll") for (int _i = 0; _i < 2; ++_i) \
;         __builtin_amdgcn_global_load_lds((const unsigned*)((const char*)(gbase) + (voff)[_i]), (LAS unsigned*)(lds + (bufoff) + ldsw + _i * 8192), 16, 0, 0); } while (0)
; #define PG8_MMA(ai, bj, At, Bt) do { __builtin_amdgcn_s_setprio(1); _Pragma("unroll") for (int m = 0; m < 4; ++m) _Pragma("unroll") for (int n = 0; n < 2; ++n) _Pragma("unroll") for (int k = 0; k < 2; ++k) \
;         acc[ai][bj][m][n] = __builtin_amdgcn_mfma_f32_16x16x32_bf16(Bt[n][k], At[m][k], acc[ai][bj][m][n], 0, 0, 0); __builtin_amdgcn_s_setprio(0); } while (0)
; #define PG8_WAIT_V(n) asm volatile("s_waitcnt vmcnt(" #n ")" ::: "memory")
; #define PG8_WAIT_L(n) asm volatile("s_waitcnt lgkmcnt(" #n ")" ::: "memory")
; #define PG8_BAR __builtin_amdgcn_s_barrier()
; #define PG8_SCHED __builtin_amdgcn_sched_barrier(0)
; template <class Epi, class Sched, bool ATILE = false>
; __device__ __forceinline__ void gemm_phase(LAS unsigned char* lds, const Gemm g, const Sched& S, const Epi& E) {
;     ...
;             PG8_BAR; PG8_WAIT_L(0); PG8_MMA(1, 0, At, B0); PG8_BAR; PG8_SCHED;
;             PG8_STAGE(PG8_SB(1, 1), b3 + hstepB, voffB);
;             PG8_WAIT_V(6); PG8_BAR; PG8_MMA(1, 1, At, B1); PG8_BAR;
;         }
;     __device__ __forceinline__ void operator()(const f32x4 (&acc)[2][2][4][2], const Unit& u, int wr, int wc, int fr, int fq) const {
;     ...
;                     const f32x4 v0 = (f32x4){bflo(x.x), bfhi(x.x), bflo(x.y), bfhi(x.y)} + alpha * acc[ai][bj][m][0];
;                     const f32x4 v1 = (f32x4){bflo(x.z), bfhi(x.z), bflo(x.w), bfhi(x.w)} + alpha * acc[ai][bj][m][1];
	s_waitcnt lgkmcnt(0)
	v_mfma_f32_16x16x32_bf16 v[64:67], v[128:131], v[188:191], v[64:67]
	v_mfma_f32_16x16x32_bf16 v[108:111], v[128:131], v[196:199], v[108:111]
	v_mfma_f32_16x16x32_bf16 v[116:119], v[128:131], v[204:207], v[116:119]
	v_mfma_f32_16x16x32_bf16 v[20:23], v[128:131], v[212:215], v[20:23]
	v_mfma_f32_16x16x32_bf16 v[64:67], v[132:135], v[192:195], v[64:67]
	v_mfma_f32_16x16x32_bf16 v[68:71], v[174:177], v[188:191], v[68:71]
	v_mfma_f32_16x16x32_bf16 v[108:111], v[132:135], v[200:203], v[108:111]
	v_mfma_f32_16x16x32_bf16 v[100:103], v[174:177], v[196:199], v[100:103]
	v_mfma_f32_16x16x32_bf16 v[116:119], v[132:135], v[208:211], v[116:119]
	v_mfma_f32_16x16x32_bf16 v[112:115], v[174:177], v[204:207], v[112:115]
	v_mfma_f32_16x16x32_bf16 v[132:135], v[132:135], v[216:219], v[20:23]
	v_mfma_f32_16x16x32_bf16 v[20:23], v[174:177], v[212:215], v[28:31]
	v_mfma_f32_16x16x32_bf16 v[68:71], v[184:187], v[192:195], v[68:71]
	v_mfma_f32_16x16x32_bf16 v[100:103], v[184:187], v[200:203], v[100:103]
	v_mfma_f32_16x16x32_bf16 v[112:115], v[184:187], v[208:211], v[112:115]
	v_mfma_f32_16x16x32_bf16 v[128:131], v[184:187], v[216:219], v[20:23]
	s_barrier
	s_setprio 0
	s_add_u32 s26, s26, 0x158080
	s_addc_u32 s27, s27, 0
	s_add_i32 s28, s30, s33
	s_mov_b32 m0, s28
	s_nop 0
	global_load_lds_dwordx4 v138, s[26:27]
	s_add_i32 m0, s28, 0x2000
	s_nop 0
	global_load_lds_dwordx4 v142, s[26:27]
	s_waitcnt vmcnt(6)
	s_setprio 1
	s_barrier
	v_mfma_f32_16x16x32_bf16 v[20:23], v[220:223], v[188:191], v[76:79]
	v_mfma_f32_16x16x32_bf16 v[76:79], v[224:227], v[192:195], v[20:23]
	v_mfma_f32_16x16x32_bf16 v[20:23], v[228:231], v[188:191], v[72:75]
	v_mfma_f32_16x16x32_bf16 v[72:75], v[232:235], v[192:195], v[20:23]
	v_mfma_f32_16x16x32_bf16 v[20:23], v[220:223], v[196:199], v[88:91]
	v_mfma_f32_16x16x32_bf16 v[88:91], v[224:227], v[200:203], v[20:23]
	v_mfma_f32_16x16x32_bf16 v[20:23], v[228:231], v[196:199], v[80:83]
	v_mfma_f32_16x16x32_bf16 v[80:83], v[232:235], v[200:203], v[20:23]
	v_mfma_f32_16x16x32_bf16 v[20:23], v[220:223], v[204:207], v[104:107]
	v_mfma_f32_16x16x32_bf16 v[104:107], v[224:227], v[208:211], v[20:23]
	v_mfma_f32_16x16x32_bf16 v[20:23], v[228:231], v[204:207], v[96:99]
	v_mfma_f32_16x16x32_bf16 v[96:99], v[232:235], v[208:211], v[20:23]
	v_mfma_f32_16x16x32_bf16 v[20:23], v[220:223], v[212:215], v[120:123]
	v_mfma_f32_16x16x32_bf16 v[120:123], v[224:227], v[216:219], v[20:23]
	v_mfma_f32_16x16x32_bf16 v[20:23], v[228:231], v[212:215], v[124:127]
	v_mfma_f32_16x16x32_bf16 v[124:127], v[232:235], v[216:219], v[20:23]
	s_barrier
	s_setprio 0
	s_add_u32 s56, s56, 0x100
	s_addc_u32 s57, s57, 0
	s_add_u32 s24, s24, 0x10000
	s_addc_u32 s25, s25, 0
	s_cmp_ge_i32 s58, s55
	s_mov_b32 s26, s58
	s_cbranch_scc0 .LBB0_1898
	v_pk_mul_f32 v[2:3], v[2:3], 0.5 op_sel_hi:[1,0]
	v_pk_mul_f32 v[0:1], v[0:1], 0.5 op_sel_hi:[1,0]
	v_pk_mul_f32 v[6:7], v[6:7], 0.5 op_sel_hi:[1,0]
	v_pk_mul_f32 v[4:5], v[4:5], 0.5 op_sel_hi:[1,0]
	v_pk_mul_f32 v[22:23], v[14:15], 0.5 op_sel_hi:[1,0]
	v_pk_mul_f32 v[20:21], v[12:13], 0.5 op_sel_hi:[1,0]
	v_pk_mul_f32 v[30:31], v[10:11], 0.5 op_sel_hi:[1,0]
	v_pk_mul_f32 v[28:29], v[8:9], 0.5 op_sel_hi:[1,0]
	v_pk_mul_f32 v[10:11], v[46:47], 0.5 op_sel_hi:[1,0]
	v_pk_mul_f32 v[8:9], v[44:45], 0.5 op_sel_hi:[1,0]
	v_pk_mul_f32 v[14:15], v[38:39], 0.5 op_sel_hi:[1,0]
	v_pk_mul_f32 v[12:13], v[36:37], 0.5 op_sel_hi:[1,0]
	v_pk_mul_f32 v[38:39], v[26:27], 0.5 op_sel_hi:[1,0]
	v_pk_mul_f32 v[36:37], v[24:25], 0.5 op_sel_hi:[1,0]
	v_pk_mul_f32 v[46:47], v[18:19], 0.5 op_sel_hi:[1,0]
	v_pk_mul_f32 v[44:45], v[16:17], 0.5 op_sel_hi:[1,0]
	v_pk_mul_f32 v[18:19], v[54:55], 0.5 op_sel_hi:[1,0]
	v_pk_mul_f32 v[16:17], v[52:53], 0.5 op_sel_hi:[1,0]
	v_pk_mul_f32 v[26:27], v[50:51], 0.5 op_sel_hi:[1,0]
	v_pk_mul_f32 v[24:25], v[48:49], 0.5 op_sel_hi:[1,0]
	v_pk_mul_f32 v[50:51], v[42:43], 0.5 op_sel_hi:[1,0]
	v_pk_mul_f32 v[48:49], v[40:41], 0.5 op_sel_hi:[1,0]
	v_pk_mul_f32 v[54:55], v[34:35], 0.5 op_sel_hi:[1,0]
	v_pk_mul_f32 v[52:53], v[32:33], 0.5 op_sel_hi:[1,0]
	v_pk_mul_f32 v[34:35], v[94:95], 0.5 op_sel_hi:[1,0]
	v_pk_mul_f32 v[32:33], v[92:93], 0.5 op_sel_hi:[1,0]
	v_pk_mul_f32 v[42:43], v[86:87], 0.5 op_sel_hi:[1,0]
	v_pk_mul_f32 v[40:41], v[84:85], 0.5 op_sel_hi:[1,0]
	v_pk_mul_f32 v[58:59], v[58:59], 0.5 op_sel_hi:[1,0]
	v_pk_mul_f32 v[56:57], v[56:57], 0.5 op_sel_hi:[1,0]
	v_pk_mul_f32 v[62:63], v[62:63], 0.5 op_sel_hi:[1,0]
	v_pk_mul_f32 v[60:61], v[60:61], 0.5 op_sel_hi:[1,0]
	v_pk_mul_f32 v[66:67], v[66:67], 0.5 op_sel_hi:[1,0]
	v_pk_mul_f32 v[64:65], v[64:65], 0.5 op_sel_hi:[1,0]
	v_pk_mul_f32 v[70:71], v[70:71], 0.5 op_sel_hi:[1,0]
	v_pk_mul_f32 v[68:69], v[68:69], 0.5 op_sel_hi:[1,0]
	v_pk_mul_f32 v[86:87], v[78:79], 0.5 op_sel_hi:[1,0]
	v_pk_mul_f32 v[84:85], v[76:77], 0.5 op_sel_hi:[1,0]
	v_pk_mul_f32 v[94:95], v[74:75], 0.5 op_sel_hi:[1,0]
	v_pk_mul_f32 v[92:93], v[72:73], 0.5 op_sel_hi:[1,0]
	v_pk_mul_f32 v[74:75], v[110:111], 0.5 op_sel_hi:[1,0]
	v_pk_mul_f32 v[72:73], v[108:109], 0.5 op_sel_hi:[1,0]
	v_pk_mul_f32 v[78:79], v[102:103], 0.5 op_sel_hi:[1,0]
	v_pk_mul_f32 v[76:77], v[100:101], 0.5 op_sel_hi:[1,0]
	v_pk_mul_f32 v[102:103], v[90:91], 0.5 op_sel_hi:[1,0]
	v_pk_mul_f32 v[100:101], v[88:89], 0.5 op_sel_hi:[1,0]
	v_pk_mul_f32 v[110:111], v[82:83], 0.5 op_sel_hi:[1,0]
	v_pk_mul_f32 v[108:109], v[80:81], 0.5 op_sel_hi:[1,0]
	v_pk_mul_f32 v[82:83], v[118:119], 0.5 op_sel_hi:[1,0]
	v_pk_mul_f32 v[80:81], v[116:117], 0.5 op_sel_hi:[1,0]
	v_pk_mul_f32 v[90:91], v[114:115], 0.5 op_sel_hi:[1,0]
	v_pk_mul_f32 v[88:89], v[112:113], 0.5 op_sel_hi:[1,0]
	v_pk_mul_f32 v[114:115], v[106:107], 0.5 op_sel_hi:[1,0]
	v_pk_mul_f32 v[112:113], v[104:105], 0.5 op_sel_hi:[1,0]
	v_pk_mul_f32 v[118:119], v[98:99], 0.5 op_sel_hi:[1,0]
	v_pk_mul_f32 v[116:117], v[96:97], 0.5 op_sel_hi:[1,0]
	v_pk_mul_f32 v[98:99], v[134:135], 0.5 op_sel_hi:[1,0]
	v_pk_mul_f32 v[96:97], v[132:133], 0.5 op_sel_hi:[1,0]
	v_pk_mul_f32 v[106:107], v[130:131], 0.5 op_sel_hi:[1,0]
	v_pk_mul_f32 v[104:105], v[128:129], 0.5 op_sel_hi:[1,0]
	v_pk_mul_f32 v[122:123], v[122:123], 0.5 op_sel_hi:[1,0]
	v_pk_mul_f32 v[120:121], v[120:121], 0.5 op_sel_hi:[1,0]
	v_pk_mul_f32 v[126:127], v[126:127], 0.5 op_sel_hi:[1,0]
	v_pk_mul_f32 v[124:125], v[124:125], 0.5 op_sel_hi:[1,0]
	s_branch .LBB0_1903
